# combined: v40 stack + fp8 mid-burst flip + burst-edge trim + scheduler shift/mask + peeled first iteration with inline-zero SrcC
# speedup vs baseline: 1.0105x; 1.0105x over previous
; #define PG8_LDA(dst, b, h) do { if constexpr (FP8) { _Pragma("unroll") for (int m = 0; m < 4; ++m) dst##8[m] = PG8_LD8(PG8_SA(b, h), aoff, aoff1, m); } \
;         else { _Pragma("unroll") for (int m = 0; m < 4; ++m) _Pragma("unroll") for (int k = 0; k < 2; ++k) dst[m][k] = *(const LAS bf16x8*)(lds + PG8_SA(b, h) + (k ? aoff1 : aoff) + m * 2048); } } while (0)
; #define PG8_LDB(dst, b, h) do { if constexpr (FP8) { dst##8[0] = PG8_LD8(PG8_SB(b, h), boff, boff1, 0); dst##8[1] = PG8_LD8(PG8_SB(b, h), boff, boff1, 1); } \
;         else { _Pragma("unroll") for (int n = 0; n < 2; ++n) _Pragma("unroll") for (int k = 0; k < 2; ++k) dst[n][k] = *(const LAS bf16x8*)(lds + PG8_SB(b, h) + (k ? boff1 : boff) + n * 2048); } } while (0)
; #define PG8_WAIT_V(n) asm volatile("s_waitcnt vmcnt(" #n ")" ::: "memory")
; #define PG8_BAR __builtin_amdgcn_s_barrier()
; template <class Epi, class SchedT, bool ALIGN_EPI, bool SP2, bool FP8 = false>
; __device__ __forceinline__ void gemm_phase(LAS unsigned char* lds, const Gemm g, const SchedT& S, const Epi& E, const int wid) {
;     ...
;     f32x4 acc[2][2][4][2];
; #pragma unroll
;     for (int a = 0; a < 2; ++a)
; #pragma unroll
;         for (int b = 0; b < 2; ++b)
; #pragma unroll
;             for (int m = 0; m < 4; ++m)
; #pragma unroll
;                 for (int n = 0; n < 2; ++n) acc[a][b][m][n] = (f32x4){0.f, 0.f, 0.f, 0.f};
;     ...
;         const bool has_next = S.next(ui + 1, nxt);
;         const char* nA = has_next ? (const char*)g.A + (size_t)nxt.pm * tstepA + (size_t)nxt.aoff * 2 : cA; const char* nB = has_next ? (const char*)g.Bt + (size_t)nxt.pn * tstepB + (size_t)nxt.boff * 2 : cB;
;         const int nt = cur.nt;
;         for (int t = 0; t < nt; t += 2) {
;             const bool last = (t == nt - 2);
;             const char* a1 = cA + (size_t)(t + 1) * kstep;
;             const char* a2 = last ? nA : cA + (size_t)(t + 2) * kstep; const char* b2 = last ? nB : cB + (size_t)(t + 2) * kstep;
;             const char* a3 = a2 + kstep; const char* b3 = b2 + kstep;
;             if constexpr (SP2) {
;     ...
;             PG8_LDB(B0, 0, 0); PG8_LDB(B1, 0, 1); PG8_SCHED; PG8_LDA(At, 0, 0); PG8_S1;
;             PG8_WAIT_V(8); PG8_WAIT_L(0); PG8_BAR; PG8_MMAP(0, 0, 0); PG8_BAR; PG8_SCHED;
;             PG8_LDA(At, 0, 1); PG8_S2;
;             PG8_WAIT_V(8); PG8_WAIT_L(0); PG8_BAR; PG8_MMAP(1, 0, 1); PG8_BAR; PG8_SCHED;
.LBB0_237:
	s_ashr_i32 s47, s46, 31
	s_lshl_b64 s[8:9], s[46:47], 18
	s_add_u32 s50, s4, s8
	s_addc_u32 s51, s5, s9
	s_cmp_lt_i32 s22, 1
	s_cbranch_scc1 .LBB0_245
	s_and_b64 s[8:9], s[68:69], exec
	s_cselect_b32 s8, s51, s67
	s_cselect_b32 s9, s50, s66
	s_add_i32 s20, s22, -2
	s_add_u32 s52, s52, 0x90080
	s_addc_u32 s53, s53, 0
	s_add_u32 s21, s66, 0x100
	s_addc_u32 s24, s67, 0
	s_mov_b32 s31, 0
	ds_read_b128 v[130:133], v143
	ds_read_b128 v[134:137], v143 offset:16
	ds_read_b128 v[148:151], v143 offset:2048
	ds_read_b128 v[152:155], v143 offset:2064
	ds_read_b128 v[156:159], v144
	ds_read_b128 v[160:163], v144 offset:16
	ds_read_b128 v[164:167], v144 offset:2048
	ds_read_b128 v[168:171], v144 offset:2064
	s_add_i32 s30, s31, 2
	s_add_u32 s6, s52, 0xfff70080
	s_addc_u32 s7, s53, -1
	s_cmp_eq_u32 s20, s31
	s_cselect_b32 s67, s49, s7
	s_cselect_b32 s66, s48, s6
	v_mov_b32_e32 v128, v138
	ds_read_b128 v[172:175], v145
	ds_read_b128 v[176:179], v145 offset:16
	ds_read_b128 v[180:183], v145 offset:2048
	ds_read_b128 v[184:187], v145 offset:2064
	ds_read_b128 v[188:191], v145 offset:4096
	ds_read_b128 v[192:195], v145 offset:4112
	ds_read_b128 v[196:199], v145 offset:6144
	ds_read_b128 v[200:203], v145 offset:6160
	s_cselect_b32 s69, s8, s24
	s_cselect_b32 s68, s9, s21
	s_add_i32 m0, s87, 0xc000
	s_nop 0
	global_load_lds_dwordx4 v128, s[52:53]
	v_mov_b32_e32 v128, v140
	s_add_i32 m0, s87, 0xe000
	s_nop 0
	global_load_lds_dwordx4 v128, s[52:53]
	s_waitcnt vmcnt(8)
	s_waitcnt lgkmcnt(0)
	s_setprio 1
	s_barrier
	v_mfma_scale_f32_16x16x128_f8f6f4 v[124:127], v[130:137], v[172:179], 0, v146, v146 op_sel_hi:[0,0,0]
	v_mfma_scale_f32_16x16x128_f8f6f4 v[108:111], v[156:163], v[172:179], 0, v146, v146 op_sel_hi:[0,0,0]
	v_mfma_scale_f32_16x16x128_f8f6f4 v[120:123], v[148:155], v[172:179], 0, v146, v146 op_sel_hi:[0,0,0]
	v_mfma_scale_f32_16x16x128_f8f6f4 v[100:103], v[164:171], v[172:179], 0, v146, v146 op_sel_hi:[0,0,0]
	v_mfma_scale_f32_16x16x128_f8f6f4 v[116:119], v[130:137], v[180:187], 0, v146, v146 op_sel_hi:[0,0,0]
	v_mfma_scale_f32_16x16x128_f8f6f4 v[112:115], v[148:155], v[180:187], 0, v146, v146 op_sel_hi:[0,0,0]
	v_mfma_scale_f32_16x16x128_f8f6f4 v[104:107], v[130:137], v[188:195], 0, v146, v146 op_sel_hi:[0,0,0]
	v_mfma_scale_f32_16x16x128_f8f6f4 v[60:63], v[164:171], v[196:203], 0, v146, v146 op_sel_hi:[0,0,0]
	s_setprio 0
	s_setprio 1
	v_mfma_scale_f32_16x16x128_f8f6f4 v[172:175], v[156:163], v[180:187], 0, v146, v146 op_sel_hi:[0,0,0]
	v_mfma_scale_f32_16x16x128_f8f6f4 v[176:179], v[164:171], v[180:187], 0, v146, v146 op_sel_hi:[0,0,0]
	v_mfma_scale_f32_16x16x128_f8f6f4 v[180:183], v[156:163], v[188:195], 0, v146, v146 op_sel_hi:[0,0,0]
	v_mfma_scale_f32_16x16x128_f8f6f4 v[184:187], v[148:155], v[188:195], 0, v146, v146 op_sel_hi:[0,0,0]
	v_mfma_scale_f32_16x16x128_f8f6f4 v[188:191], v[164:171], v[188:195], 0, v146, v146 op_sel_hi:[0,0,0]
	v_mfma_scale_f32_16x16x128_f8f6f4 v[192:195], v[130:137], v[196:203], 0, v146, v146 op_sel_hi:[0,0,0]
	v_mfma_scale_f32_16x16x128_f8f6f4 v[204:207], v[156:163], v[196:203], 0, v146, v146 op_sel_hi:[0,0,0]
	v_mfma_scale_f32_16x16x128_f8f6f4 v[208:211], v[148:155], v[196:203], 0, v146, v146 op_sel_hi:[0,0,0]
	s_barrier
	s_setprio 0
	v_mov_b32_e32 v128, v139
	s_add_i32 s6, s94, s86
	s_nop 1
	ds_read_b128 v[68:71], v145 offset:16384
	ds_read_b128 v[72:75], v145 offset:16400
	ds_read_b128 v[76:79], v145 offset:18432
	ds_read_b128 v[80:83], v145 offset:18448
	ds_read_b128 v[84:87], v145 offset:20480
	ds_read_b128 v[88:91], v145 offset:20496
	ds_read_b128 v[92:95], v145 offset:22528
	ds_read_b128 v[96:99], v145 offset:22544
	s_mov_b32 m0, s6
	s_nop 0
	global_load_lds_dwordx4 v128, s[68:69]
	v_mov_b32_e32 v128, v141
	s_add_i32 m0, s6, 0x2000
	s_add_u32 s38, s68, 0x20000
	global_load_lds_dwordx4 v128, s[68:69]
	s_addc_u32 s39, s69, 0
	v_mov_b32_e32 v128, v139
	s_add_i32 s6, s95, s86
	s_mov_b32 m0, s6
	s_nop 0
	global_load_lds_dwordx4 v128, s[38:39]
	v_mov_b32_e32 v128, v141
	s_add_i32 m0, s6, 0x2000
	s_nop 0
	global_load_lds_dwordx4 v128, s[38:39]
	v_mov_b32_e32 v128, v138
	s_mov_b32 m0, s87
	s_nop 0
	global_load_lds_dwordx4 v128, s[66:67]
	v_mov_b32_e32 v128, v140
	s_mov_b32 m0, s88
	s_nop 0
	global_load_lds_dwordx4 v128, s[66:67]
	s_waitcnt vmcnt(8)
	s_waitcnt lgkmcnt(0)
	s_setprio 1
	s_barrier
	v_mfma_scale_f32_16x16x128_f8f6f4 v[64:67], v[130:137], v[68:75], 0, v146, v146 op_sel_hi:[0,0,0]
	v_mfma_scale_f32_16x16x128_f8f6f4 v[44:47], v[156:163], v[68:75], 0, v146, v146 op_sel_hi:[0,0,0]
	v_mfma_scale_f32_16x16x128_f8f6f4 v[56:59], v[148:155], v[68:75], 0, v146, v146 op_sel_hi:[0,0,0]
	v_mfma_scale_f32_16x16x128_f8f6f4 v[52:55], v[130:137], v[76:83], 0, v146, v146 op_sel_hi:[0,0,0]
	v_mfma_scale_f32_16x16x128_f8f6f4 v[48:51], v[148:155], v[76:83], 0, v146, v146 op_sel_hi:[0,0,0]
	v_mfma_scale_f32_16x16x128_f8f6f4 v[40:43], v[130:137], v[84:91], 0, v146, v146 op_sel_hi:[0,0,0]
	v_mfma_scale_f32_16x16x128_f8f6f4 v[196:199], v[164:171], v[68:75], 0, v146, v146 op_sel_hi:[0,0,0]
	v_mfma_scale_f32_16x16x128_f8f6f4 v[200:203], v[156:163], v[76:83], 0, v146, v146 op_sel_hi:[0,0,0]
	s_setprio 0
	s_setprio 1
	v_mfma_scale_f32_16x16x128_f8f6f4 v[212:215], v[164:171], v[76:83], 0, v146, v146 op_sel_hi:[0,0,0]
	v_mfma_scale_f32_16x16x128_f8f6f4 v[216:219], v[156:163], v[84:91], 0, v146, v146 op_sel_hi:[0,0,0]
	v_mfma_scale_f32_16x16x128_f8f6f4 v[220:223], v[148:155], v[84:91], 0, v146, v146 op_sel_hi:[0,0,0]
	v_mfma_scale_f32_16x16x128_f8f6f4 v[224:227], v[164:171], v[84:91], 0, v146, v146 op_sel_hi:[0,0,0]
	v_mfma_scale_f32_16x16x128_f8f6f4 v[228:231], v[130:137], v[92:99], 0, v146, v146 op_sel_hi:[0,0,0]
	v_mfma_scale_f32_16x16x128_f8f6f4 v[232:235], v[156:163], v[92:99], 0, v146, v146 op_sel_hi:[0,0,0]
	v_mfma_scale_f32_16x16x128_f8f6f4 v[236:239], v[148:155], v[92:99], 0, v146, v146 op_sel_hi:[0,0,0]
	v_mfma_scale_f32_16x16x128_f8f6f4 v[240:243], v[164:171], v[92:99], 0, v146, v146 op_sel_hi:[0,0,0]
	s_barrier
; #define PG8_LDA(dst, b, h) do { if constexpr (FP8) { _Pragma("unroll") for (int m = 0; m < 4; ++m) dst##8[m] = PG8_LD8(PG8_SA(b, h), aoff, aoff1, m); } \
;         else { _Pragma("unroll") for (int m = 0; m < 4; ++m) _Pragma("unroll") for (int k = 0; k < 2; ++k) dst[m][k] = *(const LAS bf16x8*)(lds + PG8_SA(b, h) + (k ? aoff1 : aoff) + m * 2048); } } while (0)
; #define PG8_LDB(dst, b, h) do { if constexpr (FP8) { dst##8[0] = PG8_LD8(PG8_SB(b, h), boff, boff1, 0); dst##8[1] = PG8_LD8(PG8_SB(b, h), boff, boff1, 1); } \
;         else { _Pragma("unroll") for (int n = 0; n < 2; ++n) _Pragma("unroll") for (int k = 0; k < 2; ++k) dst[n][k] = *(const LAS bf16x8*)(lds + PG8_SB(b, h) + (k ? boff1 : boff) + n * 2048); } } while (0)
; #define PG8_WAIT_V(n) asm volatile("s_waitcnt vmcnt(" #n ")" ::: "memory")
; #define PG8_WAIT_L(n) asm volatile("s_waitcnt lgkmcnt(" #n ")" ::: "memory")
; #define PG8_BAR __builtin_amdgcn_s_barrier()
; #define PG8_SCHED __builtin_amdgcn_sched_barrier(0)
; #define PG8_S3 PG8_STAGE(PG8_SA(0, 1), a2 + hstepA, voffA)
; #define PG8_S4 do { PG8_STAGE(PG8_SB(1, 0), b3, voffB); PG8_STAGE(PG8_SB(1, 1), b3 + hstepB, voffB); PG8_STAGE(PG8_SA(1, 0), a3, voffA); } while (0)
; template <class Epi, class SchedT, bool ALIGN_EPI, bool SP2, bool FP8 = false>
; __device__ __forceinline__ void gemm_phase(LAS unsigned char* lds, const Gemm g, const SchedT& S, const Epi& E, const int wid) {
;     ...
;             PG8_LDB(B0, 1, 0); PG8_LDB(B1, 1, 1); PG8_SCHED; PG8_LDA(At, 1, 0); PG8_S3;
;             PG8_WAIT_V(8); PG8_WAIT_L(0); PG8_BAR; PG8_MMAP(0, 1, 0); PG8_BAR; PG8_SCHED;
;             PG8_LDA(At, 1, 1); PG8_S4;
;             PG8_WAIT_V(8); PG8_WAIT_L(0); PG8_BAR; PG8_MMAP(1, 1, 1); PG8_BAR; PG8_SCHED;
	s_setprio 0
	s_add_i32 s6, 0, 0x18000
	v_add_u32_e32 v8, s6, v142
	s_add_i32 s7, 0, 0x1c000
	s_nop 1
	ds_read_b128 v[0:3], v8
	ds_read_b128 v[4:7], v8 offset:16
	ds_read_b128 v[130:133], v8 offset:2048
	ds_read_b128 v[134:137], v8 offset:2064
	v_add_u32_e32 v8, s7, v142
	ds_read_b128 v[148:151], v8
	ds_read_b128 v[152:155], v8 offset:16
	ds_read_b128 v[156:159], v8 offset:2048
	ds_read_b128 v[160:163], v8 offset:2064
	s_add_u32 s38, s66, 0x90000
	v_mov_b32_e32 v68, v138
	s_mov_b32 m0, s89
	ds_read_b128 v[8:11], v145 offset:32768
	ds_read_b128 v[12:15], v145 offset:32784
	ds_read_b128 v[16:19], v145 offset:34816
	ds_read_b128 v[20:23], v145 offset:34832
	ds_read_b128 v[24:27], v145 offset:36864
	ds_read_b128 v[28:31], v145 offset:36880
	ds_read_b128 v[32:35], v145 offset:38912
	ds_read_b128 v[36:39], v145 offset:38928
	s_addc_u32 s39, s67, 0
	s_nop 0
	global_load_lds_dwordx4 v68, s[38:39]
	v_mov_b32_e32 v68, v140
	s_mov_b32 m0, s90
	s_nop 0
	global_load_lds_dwordx4 v68, s[38:39]
	s_waitcnt vmcnt(8)
	s_waitcnt lgkmcnt(0)
	s_setprio 1
	s_barrier
	v_mfma_scale_f32_16x16x128_f8f6f4 v[124:127], v[0:7], v[8:15], v[124:127], v146, v146 op_sel_hi:[0,0,0]
	v_mfma_scale_f32_16x16x128_f8f6f4 v[108:111], v[148:155], v[8:15], v[108:111], v146, v146 op_sel_hi:[0,0,0]
	v_mfma_scale_f32_16x16x128_f8f6f4 v[120:123], v[130:137], v[8:15], v[120:123], v146, v146 op_sel_hi:[0,0,0]
	v_mfma_scale_f32_16x16x128_f8f6f4 v[100:103], v[156:163], v[8:15], v[100:103], v146, v146 op_sel_hi:[0,0,0]
	v_mfma_scale_f32_16x16x128_f8f6f4 v[116:119], v[0:7], v[16:23], v[116:119], v146, v146 op_sel_hi:[0,0,0]
	v_mfma_scale_f32_16x16x128_f8f6f4 v[92:95], v[148:155], v[16:23], v[172:175], v146, v146 op_sel_hi:[0,0,0]
	v_mfma_scale_f32_16x16x128_f8f6f4 v[112:115], v[130:137], v[16:23], v[112:115], v146, v146 op_sel_hi:[0,0,0]
	v_mfma_scale_f32_16x16x128_f8f6f4 v[84:87], v[156:163], v[16:23], v[176:179], v146, v146 op_sel_hi:[0,0,0]
	s_setprio 0
	s_setprio 1
	v_mfma_scale_f32_16x16x128_f8f6f4 v[104:107], v[0:7], v[24:31], v[104:107], v146, v146 op_sel_hi:[0,0,0]
	v_mfma_scale_f32_16x16x128_f8f6f4 v[76:79], v[148:155], v[24:31], v[180:183], v146, v146 op_sel_hi:[0,0,0]
	v_mfma_scale_f32_16x16x128_f8f6f4 v[96:99], v[130:137], v[24:31], v[184:187], v146, v146 op_sel_hi:[0,0,0]
	v_mfma_scale_f32_16x16x128_f8f6f4 v[72:75], v[156:163], v[24:31], v[188:191], v146, v146 op_sel_hi:[0,0,0]
	v_mfma_scale_f32_16x16x128_f8f6f4 v[88:91], v[0:7], v[32:39], v[192:195], v146, v146 op_sel_hi:[0,0,0]
	v_mfma_scale_f32_16x16x128_f8f6f4 v[68:71], v[148:155], v[32:39], v[204:207], v146, v146 op_sel_hi:[0,0,0]
	v_mfma_scale_f32_16x16x128_f8f6f4 v[80:83], v[130:137], v[32:39], v[208:211], v146, v146 op_sel_hi:[0,0,0]
	v_mfma_scale_f32_16x16x128_f8f6f4 v[60:63], v[156:163], v[32:39], v[60:63], v146, v146 op_sel_hi:[0,0,0]
	s_barrier
	s_setprio 0
	v_mov_b32_e32 v128, v139
	ds_read_b128 v[8:11], v145 offset:49152
	ds_read_b128 v[12:15], v145 offset:49168
	ds_read_b128 v[16:19], v145 offset:51200
	ds_read_b128 v[20:23], v145 offset:51216
	ds_read_b128 v[164:167], v145 offset:53248
	ds_read_b128 v[168:171], v145 offset:53264
	ds_read_b128 v[172:175], v145 offset:55296
	ds_read_b128 v[176:179], v145 offset:55312
	s_add_i32 s6, s6, s86
	v_lshl_add_u64 v[24:25], s[68:69], 0, v[128:129]
	v_lshl_add_u64 v[24:25], v[24:25], 0, s[40:41]
	s_mov_b32 m0, s6
	v_mov_b32_e32 v128, v141
	global_load_lds_dwordx4 v[24:25], off
	s_add_i32 m0, s6, 0x2000
	v_lshl_add_u64 v[24:25], s[68:69], 0, v[128:129]
	v_lshl_add_u64 v[24:25], v[24:25], 0, s[40:41]
	s_add_u32 s38, s68, 0x20080
	global_load_lds_dwordx4 v[24:25], off
	s_addc_u32 s39, s69, 0
	v_mov_b32_e32 v24, v139
	s_add_i32 s6, s7, s86
	s_mov_b32 m0, s6
	v_mov_b32_e32 v128, v138
	global_load_lds_dwordx4 v24, s[38:39]
	v_mov_b32_e32 v24, v141
	s_add_i32 m0, s6, 0x2000
	s_nop 0
	global_load_lds_dwordx4 v24, s[38:39]
	s_mov_b32 m0, s92
	v_lshl_add_u64 v[24:25], s[66:67], 0, v[128:129]
	v_lshl_add_u64 v[24:25], v[24:25], 0, s[40:41]
	v_mov_b32_e32 v128, v140
	global_load_lds_dwordx4 v[24:25], off
	s_mov_b32 m0, s93
	v_lshl_add_u64 v[24:25], s[66:67], 0, v[128:129]
	v_lshl_add_u64 v[24:25], v[24:25], 0, s[40:41]
	global_load_lds_dwordx4 v[24:25], off
	s_waitcnt vmcnt(8)
	s_waitcnt lgkmcnt(0)
	s_setprio 1
	s_barrier
	v_mfma_scale_f32_16x16x128_f8f6f4 v[64:67], v[0:7], v[8:15], v[64:67], v146, v146 op_sel_hi:[0,0,0]
	v_mfma_scale_f32_16x16x128_f8f6f4 v[44:47], v[148:155], v[8:15], v[44:47], v146, v146 op_sel_hi:[0,0,0]
	v_mfma_scale_f32_16x16x128_f8f6f4 v[56:59], v[130:137], v[8:15], v[56:59], v146, v146 op_sel_hi:[0,0,0]
	v_mfma_scale_f32_16x16x128_f8f6f4 v[36:39], v[156:163], v[8:15], v[196:199], v146, v146 op_sel_hi:[0,0,0]
	v_mfma_scale_f32_16x16x128_f8f6f4 v[52:55], v[0:7], v[16:23], v[52:55], v146, v146 op_sel_hi:[0,0,0]
	v_mfma_scale_f32_16x16x128_f8f6f4 v[28:31], v[148:155], v[16:23], v[200:203], v146, v146 op_sel_hi:[0,0,0]
	v_mfma_scale_f32_16x16x128_f8f6f4 v[48:51], v[130:137], v[16:23], v[48:51], v146, v146 op_sel_hi:[0,0,0]
	v_mfma_scale_f32_16x16x128_f8f6f4 v[20:23], v[156:163], v[16:23], v[212:215], v146, v146 op_sel_hi:[0,0,0]
	s_setprio 0
	s_setprio 1
	v_mfma_scale_f32_16x16x128_f8f6f4 v[40:43], v[0:7], v[164:171], v[40:43], v146, v146 op_sel_hi:[0,0,0]
	v_mfma_scale_f32_16x16x128_f8f6f4 v[12:15], v[148:155], v[164:171], v[216:219], v146, v146 op_sel_hi:[0,0,0]
	v_mfma_scale_f32_16x16x128_f8f6f4 v[32:35], v[130:137], v[164:171], v[220:223], v146, v146 op_sel_hi:[0,0,0]
	v_mfma_scale_f32_16x16x128_f8f6f4 v[8:11], v[156:163], v[164:171], v[224:227], v146, v146 op_sel_hi:[0,0,0]
	v_mfma_scale_f32_16x16x128_f8f6f4 v[24:27], v[0:7], v[172:179], v[228:231], v146, v146 op_sel_hi:[0,0,0]
	v_mfma_scale_f32_16x16x128_f8f6f4 v[4:7], v[148:155], v[172:179], v[232:235], v146, v146 op_sel_hi:[0,0,0]
	v_mfma_scale_f32_16x16x128_f8f6f4 v[16:19], v[130:137], v[172:179], v[236:239], v146, v146 op_sel_hi:[0,0,0]
	v_mfma_scale_f32_16x16x128_f8f6f4 v[0:3], v[156:163], v[172:179], v[240:243], v146, v146 op_sel_hi:[0,0,0]
	s_barrier
	s_setprio 0
	s_add_u32 s52, s52, 0x100
	s_addc_u32 s53, s53, 0
	s_add_u32 s21, s21, 0x100
	s_addc_u32 s24, s24, 0
	s_cmp_ge_i32 s30, s22
	s_mov_b32 s31, s30
	s_cbranch_scc1 .Lpeel_exit_lbb0_239
; #define PG8_LDA(dst, b, h) do { if constexpr (FP8) { _Pragma("unroll") for (int m = 0; m < 4; ++m) dst##8[m] = PG8_LD8(PG8_SA(b, h), aoff, aoff1, m); } \
;         else { _Pragma("unroll") for (int m = 0; m < 4; ++m) _Pragma("unroll") for (int k = 0; k < 2; ++k) dst[m][k] = *(const LAS bf16x8*)(lds + PG8_SA(b, h) + (k ? aoff1 : aoff) + m * 2048); } } while (0)
; #define PG8_LDB(dst, b, h) do { if constexpr (FP8) { dst##8[0] = PG8_LD8(PG8_SB(b, h), boff, boff1, 0); dst##8[1] = PG8_LD8(PG8_SB(b, h), boff, boff1, 1); } \
;         else { _Pragma("unroll") for (int n = 0; n < 2; ++n) _Pragma("unroll") for (int k = 0; k < 2; ++k) dst[n][k] = *(const LAS bf16x8*)(lds + PG8_SB(b, h) + (k ? boff1 : boff) + n * 2048); } } while (0)
; #define PG8_WAIT_V(n) asm volatile("s_waitcnt vmcnt(" #n ")" ::: "memory")
; #define PG8_WAIT_L(n) asm volatile("s_waitcnt lgkmcnt(" #n ")" ::: "memory")
; #define PG8_BAR __builtin_amdgcn_s_barrier()
; #define PG8_SCHED __builtin_amdgcn_sched_barrier(0)
; #define PG8_S1 PG8_STAGE(PG8_SA(1, 1), a1 + hstepA, voffA)
; #define PG8_S2 do { PG8_STAGE(PG8_SB(0, 0), b2, voffB); PG8_STAGE(PG8_SB(0, 1), b2 + hstepB, voffB); PG8_STAGE(PG8_SA(0, 0), a2, voffA); } while (0)
; template <class Epi, class SchedT, bool ALIGN_EPI, bool SP2, bool FP8 = false>
; __device__ __forceinline__ void gemm_phase(LAS unsigned char* lds, const Gemm g, const SchedT& S, const Epi& E, const int wid) {
;     ...
;         for (int t = 0; t < nt; t += 2) {
;             const bool last = (t == nt - 2);
;             const char* a1 = cA + (size_t)(t + 1) * kstep;
;             const char* a2 = last ? nA : cA + (size_t)(t + 2) * kstep; const char* b2 = last ? nB : cB + (size_t)(t + 2) * kstep;
;             const char* a3 = a2 + kstep; const char* b3 = b2 + kstep;
;             if constexpr (SP2) {
;     ...
;             PG8_LDB(B0, 0, 0); PG8_LDB(B1, 0, 1); PG8_SCHED; PG8_LDA(At, 0, 0); PG8_S1;
;             PG8_WAIT_V(8); PG8_WAIT_L(0); PG8_BAR; PG8_MMAP(0, 0, 0); PG8_BAR; PG8_SCHED;
;             PG8_LDA(At, 0, 1); PG8_S2;
;             PG8_WAIT_V(8); PG8_WAIT_L(0); PG8_BAR; PG8_MMAP(1, 0, 1); PG8_BAR; PG8_SCHED;
.LBB0_239:
	ds_read_b128 v[130:133], v143
	ds_read_b128 v[134:137], v143 offset:16
	ds_read_b128 v[148:151], v143 offset:2048
	ds_read_b128 v[152:155], v143 offset:2064
	ds_read_b128 v[156:159], v144
	ds_read_b128 v[160:163], v144 offset:16
	ds_read_b128 v[164:167], v144 offset:2048
	ds_read_b128 v[168:171], v144 offset:2064
	s_add_i32 s30, s31, 2
	s_add_u32 s6, s52, 0xfff70080
	s_addc_u32 s7, s53, -1
	s_cmp_eq_u32 s20, s31
	s_cselect_b32 s67, s49, s7
	s_cselect_b32 s66, s48, s6
	v_mov_b32_e32 v128, v138
	ds_read_b128 v[172:175], v145
	ds_read_b128 v[176:179], v145 offset:16
	ds_read_b128 v[180:183], v145 offset:2048
	ds_read_b128 v[184:187], v145 offset:2064
	ds_read_b128 v[188:191], v145 offset:4096
	ds_read_b128 v[192:195], v145 offset:4112
	ds_read_b128 v[196:199], v145 offset:6144
	ds_read_b128 v[200:203], v145 offset:6160
	s_cselect_b32 s69, s8, s24
	s_cselect_b32 s68, s9, s21
	s_add_i32 m0, s87, 0xc000
	s_nop 0
	global_load_lds_dwordx4 v128, s[52:53]
	v_mov_b32_e32 v128, v140
	s_add_i32 m0, s87, 0xe000
	s_nop 0
	global_load_lds_dwordx4 v128, s[52:53]
	s_waitcnt vmcnt(8)
	s_waitcnt lgkmcnt(0)
	s_setprio 1
	s_barrier
	v_mfma_scale_f32_16x16x128_f8f6f4 v[124:127], v[130:137], v[172:179], v[124:127], v146, v146 op_sel_hi:[0,0,0]
	v_mfma_scale_f32_16x16x128_f8f6f4 v[108:111], v[156:163], v[172:179], v[108:111], v146, v146 op_sel_hi:[0,0,0]
	v_mfma_scale_f32_16x16x128_f8f6f4 v[120:123], v[148:155], v[172:179], v[120:123], v146, v146 op_sel_hi:[0,0,0]
	v_mfma_scale_f32_16x16x128_f8f6f4 v[100:103], v[164:171], v[172:179], v[100:103], v146, v146 op_sel_hi:[0,0,0]
	v_mfma_scale_f32_16x16x128_f8f6f4 v[116:119], v[130:137], v[180:187], v[116:119], v146, v146 op_sel_hi:[0,0,0]
	v_mfma_scale_f32_16x16x128_f8f6f4 v[112:115], v[148:155], v[180:187], v[112:115], v146, v146 op_sel_hi:[0,0,0]
	v_mfma_scale_f32_16x16x128_f8f6f4 v[104:107], v[130:137], v[188:195], v[104:107], v146, v146 op_sel_hi:[0,0,0]
	v_mfma_scale_f32_16x16x128_f8f6f4 v[60:63], v[164:171], v[196:203], v[60:63], v146, v146 op_sel_hi:[0,0,0]
	s_setprio 0
	s_setprio 1
	v_mfma_scale_f32_16x16x128_f8f6f4 v[172:175], v[156:163], v[180:187], v[92:95], v146, v146 op_sel_hi:[0,0,0]
	v_mfma_scale_f32_16x16x128_f8f6f4 v[176:179], v[164:171], v[180:187], v[84:87], v146, v146 op_sel_hi:[0,0,0]
	v_mfma_scale_f32_16x16x128_f8f6f4 v[180:183], v[156:163], v[188:195], v[76:79], v146, v146 op_sel_hi:[0,0,0]
	v_mfma_scale_f32_16x16x128_f8f6f4 v[184:187], v[148:155], v[188:195], v[96:99], v146, v146 op_sel_hi:[0,0,0]
	v_mfma_scale_f32_16x16x128_f8f6f4 v[188:191], v[164:171], v[188:195], v[72:75], v146, v146 op_sel_hi:[0,0,0]
	v_mfma_scale_f32_16x16x128_f8f6f4 v[192:195], v[130:137], v[196:203], v[88:91], v146, v146 op_sel_hi:[0,0,0]
	v_mfma_scale_f32_16x16x128_f8f6f4 v[204:207], v[156:163], v[196:203], v[68:71], v146, v146 op_sel_hi:[0,0,0]
	v_mfma_scale_f32_16x16x128_f8f6f4 v[208:211], v[148:155], v[196:203], v[80:83], v146, v146 op_sel_hi:[0,0,0]
	s_barrier
	s_setprio 0
	v_mov_b32_e32 v128, v139
	s_add_i32 s6, s94, s86
	s_nop 1
	ds_read_b128 v[68:71], v145 offset:16384
	ds_read_b128 v[72:75], v145 offset:16400
	ds_read_b128 v[76:79], v145 offset:18432
	ds_read_b128 v[80:83], v145 offset:18448
	ds_read_b128 v[84:87], v145 offset:20480
	ds_read_b128 v[88:91], v145 offset:20496
	ds_read_b128 v[92:95], v145 offset:22528
	ds_read_b128 v[96:99], v145 offset:22544
	s_mov_b32 m0, s6
	s_nop 0
	global_load_lds_dwordx4 v128, s[68:69]
	v_mov_b32_e32 v128, v141
	s_add_i32 m0, s6, 0x2000
	s_add_u32 s38, s68, 0x20000
	global_load_lds_dwordx4 v128, s[68:69]
	s_addc_u32 s39, s69, 0
	v_mov_b32_e32 v128, v139
	s_add_i32 s6, s95, s86
	s_mov_b32 m0, s6
	s_nop 0
	global_load_lds_dwordx4 v128, s[38:39]
	v_mov_b32_e32 v128, v141
	s_add_i32 m0, s6, 0x2000
	s_nop 0
	global_load_lds_dwordx4 v128, s[38:39]
	v_mov_b32_e32 v128, v138
	s_mov_b32 m0, s87
	s_nop 0
	global_load_lds_dwordx4 v128, s[66:67]
	v_mov_b32_e32 v128, v140
	s_mov_b32 m0, s88
	s_nop 0
	global_load_lds_dwordx4 v128, s[66:67]
	s_waitcnt vmcnt(8)
	s_waitcnt lgkmcnt(0)
	s_setprio 1
	s_barrier
	v_mfma_scale_f32_16x16x128_f8f6f4 v[64:67], v[130:137], v[68:75], v[64:67], v146, v146 op_sel_hi:[0,0,0]
	v_mfma_scale_f32_16x16x128_f8f6f4 v[44:47], v[156:163], v[68:75], v[44:47], v146, v146 op_sel_hi:[0,0,0]
	v_mfma_scale_f32_16x16x128_f8f6f4 v[56:59], v[148:155], v[68:75], v[56:59], v146, v146 op_sel_hi:[0,0,0]
	v_mfma_scale_f32_16x16x128_f8f6f4 v[52:55], v[130:137], v[76:83], v[52:55], v146, v146 op_sel_hi:[0,0,0]
	v_mfma_scale_f32_16x16x128_f8f6f4 v[48:51], v[148:155], v[76:83], v[48:51], v146, v146 op_sel_hi:[0,0,0]
	v_mfma_scale_f32_16x16x128_f8f6f4 v[40:43], v[130:137], v[84:91], v[40:43], v146, v146 op_sel_hi:[0,0,0]
	v_mfma_scale_f32_16x16x128_f8f6f4 v[196:199], v[164:171], v[68:75], v[36:39], v146, v146 op_sel_hi:[0,0,0]
	v_mfma_scale_f32_16x16x128_f8f6f4 v[200:203], v[156:163], v[76:83], v[28:31], v146, v146 op_sel_hi:[0,0,0]
	s_setprio 0
	s_setprio 1
	v_mfma_scale_f32_16x16x128_f8f6f4 v[212:215], v[164:171], v[76:83], v[20:23], v146, v146 op_sel_hi:[0,0,0]
	v_mfma_scale_f32_16x16x128_f8f6f4 v[216:219], v[156:163], v[84:91], v[12:15], v146, v146 op_sel_hi:[0,0,0]
	v_mfma_scale_f32_16x16x128_f8f6f4 v[220:223], v[148:155], v[84:91], v[32:35], v146, v146 op_sel_hi:[0,0,0]
	v_mfma_scale_f32_16x16x128_f8f6f4 v[224:227], v[164:171], v[84:91], v[8:11], v146, v146 op_sel_hi:[0,0,0]
	v_mfma_scale_f32_16x16x128_f8f6f4 v[228:231], v[130:137], v[92:99], v[24:27], v146, v146 op_sel_hi:[0,0,0]
	v_mfma_scale_f32_16x16x128_f8f6f4 v[232:235], v[156:163], v[92:99], v[4:7], v146, v146 op_sel_hi:[0,0,0]
	v_mfma_scale_f32_16x16x128_f8f6f4 v[236:239], v[148:155], v[92:99], v[16:19], v146, v146 op_sel_hi:[0,0,0]
	v_mfma_scale_f32_16x16x128_f8f6f4 v[240:243], v[164:171], v[92:99], v[0:3], v146, v146 op_sel_hi:[0,0,0]
	s_barrier
; #define PG8_LDA(dst, b, h) do { if constexpr (FP8) { _Pragma("unroll") for (int m = 0; m < 4; ++m) dst##8[m] = PG8_LD8(PG8_SA(b, h), aoff, aoff1, m); } \
;         else { _Pragma("unroll") for (int m = 0; m < 4; ++m) _Pragma("unroll") for (int k = 0; k < 2; ++k) dst[m][k] = *(const LAS bf16x8*)(lds + PG8_SA(b, h) + (k ? aoff1 : aoff) + m * 2048); } } while (0)
; #define PG8_LDB(dst, b, h) do { if constexpr (FP8) { dst##8[0] = PG8_LD8(PG8_SB(b, h), boff, boff1, 0); dst##8[1] = PG8_LD8(PG8_SB(b, h), boff, boff1, 1); } \
;         else { _Pragma("unroll") for (int n = 0; n < 2; ++n) _Pragma("unroll") for (int k = 0; k < 2; ++k) dst[n][k] = *(const LAS bf16x8*)(lds + PG8_SB(b, h) + (k ? boff1 : boff) + n * 2048); } } while (0)
; #define PG8_WAIT_V(n) asm volatile("s_waitcnt vmcnt(" #n ")" ::: "memory")
; #define PG8_WAIT_L(n) asm volatile("s_waitcnt lgkmcnt(" #n ")" ::: "memory")
; #define PG8_BAR __builtin_amdgcn_s_barrier()
; #define PG8_SCHED __builtin_amdgcn_sched_barrier(0)
; #define PG8_S3 PG8_STAGE(PG8_SA(0, 1), a2 + hstepA, voffA)
; #define PG8_S4 do { PG8_STAGE(PG8_SB(1, 0), b3, voffB); PG8_STAGE(PG8_SB(1, 1), b3 + hstepB, voffB); PG8_STAGE(PG8_SA(1, 0), a3, voffA); } while (0)
; template <class Epi, class SchedT, bool ALIGN_EPI, bool SP2, bool FP8 = false>
; __device__ __forceinline__ void gemm_phase(LAS unsigned char* lds, const Gemm g, const SchedT& S, const Epi& E, const int wid) {
;     ...
;             PG8_LDB(B0, 1, 0); PG8_LDB(B1, 1, 1); PG8_SCHED; PG8_LDA(At, 1, 0); PG8_S3;
;             PG8_WAIT_V(8); PG8_WAIT_L(0); PG8_BAR; PG8_MMAP(0, 1, 0); PG8_BAR; PG8_SCHED;
;             PG8_LDA(At, 1, 1); PG8_S4;
;             PG8_WAIT_V(8); PG8_WAIT_L(0); PG8_BAR; PG8_MMAP(1, 1, 1); PG8_BAR; PG8_SCHED;
	s_setprio 0
	s_add_i32 s6, 0, 0x18000
	v_add_u32_e32 v8, s6, v142
	s_add_i32 s7, 0, 0x1c000
	s_nop 1
	ds_read_b128 v[0:3], v8
	ds_read_b128 v[4:7], v8 offset:16
	ds_read_b128 v[130:133], v8 offset:2048
	ds_read_b128 v[134:137], v8 offset:2064
	v_add_u32_e32 v8, s7, v142
	ds_read_b128 v[148:151], v8
	ds_read_b128 v[152:155], v8 offset:16
	ds_read_b128 v[156:159], v8 offset:2048
	ds_read_b128 v[160:163], v8 offset:2064
	s_add_u32 s38, s66, 0x90000
	v_mov_b32_e32 v68, v138
	s_mov_b32 m0, s89
	ds_read_b128 v[8:11], v145 offset:32768
	ds_read_b128 v[12:15], v145 offset:32784
	ds_read_b128 v[16:19], v145 offset:34816
	ds_read_b128 v[20:23], v145 offset:34832
	ds_read_b128 v[24:27], v145 offset:36864
	ds_read_b128 v[28:31], v145 offset:36880
	ds_read_b128 v[32:35], v145 offset:38912
	ds_read_b128 v[36:39], v145 offset:38928
	s_addc_u32 s39, s67, 0
	s_nop 0
	global_load_lds_dwordx4 v68, s[38:39]
	v_mov_b32_e32 v68, v140
	s_mov_b32 m0, s90
	s_nop 0
	global_load_lds_dwordx4 v68, s[38:39]
	s_waitcnt vmcnt(8)
	s_waitcnt lgkmcnt(0)
	s_setprio 1
	s_barrier
	v_mfma_scale_f32_16x16x128_f8f6f4 v[124:127], v[0:7], v[8:15], v[124:127], v146, v146 op_sel_hi:[0,0,0]
	v_mfma_scale_f32_16x16x128_f8f6f4 v[108:111], v[148:155], v[8:15], v[108:111], v146, v146 op_sel_hi:[0,0,0]
	v_mfma_scale_f32_16x16x128_f8f6f4 v[120:123], v[130:137], v[8:15], v[120:123], v146, v146 op_sel_hi:[0,0,0]
	v_mfma_scale_f32_16x16x128_f8f6f4 v[100:103], v[156:163], v[8:15], v[100:103], v146, v146 op_sel_hi:[0,0,0]
	v_mfma_scale_f32_16x16x128_f8f6f4 v[116:119], v[0:7], v[16:23], v[116:119], v146, v146 op_sel_hi:[0,0,0]
	v_mfma_scale_f32_16x16x128_f8f6f4 v[92:95], v[148:155], v[16:23], v[172:175], v146, v146 op_sel_hi:[0,0,0]
	v_mfma_scale_f32_16x16x128_f8f6f4 v[112:115], v[130:137], v[16:23], v[112:115], v146, v146 op_sel_hi:[0,0,0]
	v_mfma_scale_f32_16x16x128_f8f6f4 v[84:87], v[156:163], v[16:23], v[176:179], v146, v146 op_sel_hi:[0,0,0]
	s_setprio 0
	s_setprio 1
	v_mfma_scale_f32_16x16x128_f8f6f4 v[104:107], v[0:7], v[24:31], v[104:107], v146, v146 op_sel_hi:[0,0,0]
	v_mfma_scale_f32_16x16x128_f8f6f4 v[76:79], v[148:155], v[24:31], v[180:183], v146, v146 op_sel_hi:[0,0,0]
	v_mfma_scale_f32_16x16x128_f8f6f4 v[96:99], v[130:137], v[24:31], v[184:187], v146, v146 op_sel_hi:[0,0,0]
	v_mfma_scale_f32_16x16x128_f8f6f4 v[72:75], v[156:163], v[24:31], v[188:191], v146, v146 op_sel_hi:[0,0,0]
	v_mfma_scale_f32_16x16x128_f8f6f4 v[88:91], v[0:7], v[32:39], v[192:195], v146, v146 op_sel_hi:[0,0,0]
	v_mfma_scale_f32_16x16x128_f8f6f4 v[68:71], v[148:155], v[32:39], v[204:207], v146, v146 op_sel_hi:[0,0,0]
	v_mfma_scale_f32_16x16x128_f8f6f4 v[80:83], v[130:137], v[32:39], v[208:211], v146, v146 op_sel_hi:[0,0,0]
	v_mfma_scale_f32_16x16x128_f8f6f4 v[60:63], v[156:163], v[32:39], v[60:63], v146, v146 op_sel_hi:[0,0,0]
	s_barrier
	s_setprio 0
	v_mov_b32_e32 v128, v139
	ds_read_b128 v[8:11], v145 offset:49152
	ds_read_b128 v[12:15], v145 offset:49168
	ds_read_b128 v[16:19], v145 offset:51200
	ds_read_b128 v[20:23], v145 offset:51216
	ds_read_b128 v[164:167], v145 offset:53248
	ds_read_b128 v[168:171], v145 offset:53264
	ds_read_b128 v[172:175], v145 offset:55296
	ds_read_b128 v[176:179], v145 offset:55312
	s_add_i32 s6, s6, s86
	v_lshl_add_u64 v[24:25], s[68:69], 0, v[128:129]
	v_lshl_add_u64 v[24:25], v[24:25], 0, s[40:41]
	s_mov_b32 m0, s6
	v_mov_b32_e32 v128, v141
	global_load_lds_dwordx4 v[24:25], off
	s_add_i32 m0, s6, 0x2000
	v_lshl_add_u64 v[24:25], s[68:69], 0, v[128:129]
	v_lshl_add_u64 v[24:25], v[24:25], 0, s[40:41]
	s_add_u32 s38, s68, 0x20080
	global_load_lds_dwordx4 v[24:25], off
	s_addc_u32 s39, s69, 0
	v_mov_b32_e32 v24, v139
	s_add_i32 s6, s7, s86
	s_mov_b32 m0, s6
	v_mov_b32_e32 v128, v138
	global_load_lds_dwordx4 v24, s[38:39]
	v_mov_b32_e32 v24, v141
	s_add_i32 m0, s6, 0x2000
	s_nop 0
	global_load_lds_dwordx4 v24, s[38:39]
	s_mov_b32 m0, s92
	v_lshl_add_u64 v[24:25], s[66:67], 0, v[128:129]
	v_lshl_add_u64 v[24:25], v[24:25], 0, s[40:41]
	v_mov_b32_e32 v128, v140
	global_load_lds_dwordx4 v[24:25], off
	s_mov_b32 m0, s93
	v_lshl_add_u64 v[24:25], s[66:67], 0, v[128:129]
	v_lshl_add_u64 v[24:25], v[24:25], 0, s[40:41]
	global_load_lds_dwordx4 v[24:25], off
	s_waitcnt vmcnt(8)
	s_waitcnt lgkmcnt(0)
	s_setprio 1
	s_barrier
	v_mfma_scale_f32_16x16x128_f8f6f4 v[64:67], v[0:7], v[8:15], v[64:67], v146, v146 op_sel_hi:[0,0,0]
	v_mfma_scale_f32_16x16x128_f8f6f4 v[44:47], v[148:155], v[8:15], v[44:47], v146, v146 op_sel_hi:[0,0,0]
	v_mfma_scale_f32_16x16x128_f8f6f4 v[56:59], v[130:137], v[8:15], v[56:59], v146, v146 op_sel_hi:[0,0,0]
	v_mfma_scale_f32_16x16x128_f8f6f4 v[36:39], v[156:163], v[8:15], v[196:199], v146, v146 op_sel_hi:[0,0,0]
	v_mfma_scale_f32_16x16x128_f8f6f4 v[52:55], v[0:7], v[16:23], v[52:55], v146, v146 op_sel_hi:[0,0,0]
	v_mfma_scale_f32_16x16x128_f8f6f4 v[28:31], v[148:155], v[16:23], v[200:203], v146, v146 op_sel_hi:[0,0,0]
	v_mfma_scale_f32_16x16x128_f8f6f4 v[48:51], v[130:137], v[16:23], v[48:51], v146, v146 op_sel_hi:[0,0,0]
	v_mfma_scale_f32_16x16x128_f8f6f4 v[20:23], v[156:163], v[16:23], v[212:215], v146, v146 op_sel_hi:[0,0,0]
	s_setprio 0
	s_setprio 1
	v_mfma_scale_f32_16x16x128_f8f6f4 v[40:43], v[0:7], v[164:171], v[40:43], v146, v146 op_sel_hi:[0,0,0]
	v_mfma_scale_f32_16x16x128_f8f6f4 v[12:15], v[148:155], v[164:171], v[216:219], v146, v146 op_sel_hi:[0,0,0]
	v_mfma_scale_f32_16x16x128_f8f6f4 v[32:35], v[130:137], v[164:171], v[220:223], v146, v146 op_sel_hi:[0,0,0]
	v_mfma_scale_f32_16x16x128_f8f6f4 v[8:11], v[156:163], v[164:171], v[224:227], v146, v146 op_sel_hi:[0,0,0]
	v_mfma_scale_f32_16x16x128_f8f6f4 v[24:27], v[0:7], v[172:179], v[228:231], v146, v146 op_sel_hi:[0,0,0]
	v_mfma_scale_f32_16x16x128_f8f6f4 v[4:7], v[148:155], v[172:179], v[232:235], v146, v146 op_sel_hi:[0,0,0]
	v_mfma_scale_f32_16x16x128_f8f6f4 v[16:19], v[130:137], v[172:179], v[236:239], v146, v146 op_sel_hi:[0,0,0]
	v_mfma_scale_f32_16x16x128_f8f6f4 v[0:3], v[156:163], v[172:179], v[240:243], v146, v146 op_sel_hi:[0,0,0]
	s_barrier
	s_setprio 0
	s_add_u32 s52, s52, 0x100
	s_addc_u32 s53, s53, 0
	s_add_u32 s21, s21, 0x100
	s_addc_u32 s24, s24, 0
	s_cmp_ge_i32 s30, s22
	s_mov_b32 s31, s30
	s_cbranch_scc0 .LBB0_239

; #define PG8_LDA(dst, b, h) do { if constexpr (FP8) { _Pragma("unroll") for (int m = 0; m < 4; ++m) dst##8[m] = PG8_LD8(PG8_SA(b, h), aoff, aoff1, m); } \
;         else { _Pragma("unroll") for (int m = 0; m < 4; ++m) _Pragma("unroll") for (int k = 0; k < 2; ++k) dst[m][k] = *(const LAS bf16x8*)(lds + PG8_SA(b, h) + (k ? aoff1 : aoff) + m * 2048); } } while (0)
; #define PG8_LDB(dst, b, h) do { if constexpr (FP8) { dst##8[0] = PG8_LD8(PG8_SB(b, h), boff, boff1, 0); dst##8[1] = PG8_LD8(PG8_SB(b, h), boff, boff1, 1); } \
;         else { _Pragma("unroll") for (int n = 0; n < 2; ++n) _Pragma("unroll") for (int k = 0; k < 2; ++k) dst[n][k] = *(const LAS bf16x8*)(lds + PG8_SB(b, h) + (k ? boff1 : boff) + n * 2048); } } while (0)
; #define PG8_WAIT_V(n) asm volatile("s_waitcnt vmcnt(" #n ")" ::: "memory")
; #define PG8_BAR __builtin_amdgcn_s_barrier()
; template <class Epi, class SchedT, bool ALIGN_EPI, bool SP2, bool FP8 = false>
; __device__ __forceinline__ void gemm_phase(LAS unsigned char* lds, const Gemm g, const SchedT& S, const Epi& E, const int wid) {
;     ...
;     f32x4 acc[2][2][4][2];
; #pragma unroll
;     for (int a = 0; a < 2; ++a)
; #pragma unroll
;         for (int b = 0; b < 2; ++b)
; #pragma unroll
;             for (int m = 0; m < 4; ++m)
; #pragma unroll
;                 for (int n = 0; n < 2; ++n) acc[a][b][m][n] = (f32x4){0.f, 0.f, 0.f, 0.f};
;     ...
;         const bool has_next = S.next(ui + 1, nxt);
;         const char* nA = has_next ? (const char*)g.A + (size_t)nxt.pm * tstepA + (size_t)nxt.aoff * 2 : cA; const char* nB = has_next ? (const char*)g.Bt + (size_t)nxt.pn * tstepB + (size_t)nxt.boff * 2 : cB;
;         const int nt = cur.nt;
;         for (int t = 0; t < nt; t += 2) {
;             const bool last = (t == nt - 2);
;             const char* a1 = cA + (size_t)(t + 1) * kstep;
;             const char* a2 = last ? nA : cA + (size_t)(t + 2) * kstep; const char* b2 = last ? nB : cB + (size_t)(t + 2) * kstep;
;             const char* a3 = a2 + kstep; const char* b3 = b2 + kstep;
;             if constexpr (SP2) {
;     ...
;             PG8_LDB(B0, 0, 0); PG8_LDB(B1, 0, 1); PG8_SCHED; PG8_LDA(At, 0, 0); PG8_S1;
;             PG8_WAIT_V(8); PG8_WAIT_L(0); PG8_BAR; PG8_MMAP(0, 0, 0); PG8_BAR; PG8_SCHED;
;             PG8_LDA(At, 0, 1); PG8_S2;
;             PG8_WAIT_V(8); PG8_WAIT_L(0); PG8_BAR; PG8_MMAP(1, 0, 1); PG8_BAR; PG8_SCHED;
.LBB0_254:
	s_ashr_i32 s45, s44, 31
	s_lshl_b64 s[20:21], s[44:45], 19
	s_add_u32 s46, s23, s20
	s_addc_u32 s47, s34, s21
	s_ashr_i32 s43, s42, 31
	s_lshl_b64 s[20:21], s[42:43], 19
	s_add_u32 s48, s64, s20
	s_addc_u32 s49, s65, s21
	s_cmp_lt_i32 s8, 1
	s_cbranch_scc1 .LBB0_262
	s_and_b64 s[20:21], s[4:5], exec
	s_cselect_b32 s9, s47, s51
	s_cselect_b32 s20, s46, s50
	s_cselect_b32 s21, s49, s53
	s_cselect_b32 s24, s48, s52
	s_add_i32 s30, s8, -2
	s_add_u32 s50, s50, 0x40080
	s_addc_u32 s51, s51, 0
	s_add_u32 s31, s52, 0x100
	s_addc_u32 s38, s53, 0
	s_mov_b32 s39, 0
	ds_read_b128 v[146:149], v139
	ds_read_b128 v[150:153], v139 offset:1024
	ds_read_b128 v[154:157], v140
	ds_read_b128 v[158:161], v140 offset:1024
	ds_read_b128 v[162:165], v141
	ds_read_b128 v[166:169], v141 offset:1024
	ds_read_b128 v[170:173], v142
	ds_read_b128 v[174:177], v142 offset:1024
	s_add_i32 s43, s39, 2
	s_add_u32 s6, s50, 0xfffc0080
	s_addc_u32 s7, s51, -1
	s_cmp_eq_u32 s30, s39
	s_cselect_b32 s53, s9, s7
	s_cselect_b32 s52, s20, s6
	s_cselect_b32 s67, s21, s38
	s_cselect_b32 s66, s24, s31
	v_mov_b32_e32 v128, v134
	ds_read_b128 v[178:181], v143
	ds_read_b128 v[182:185], v143 offset:1024
	ds_read_b128 v[186:189], v143 offset:2048
	ds_read_b128 v[190:193], v143 offset:3072
	ds_read_b128 v[194:197], v143 offset:4096
	ds_read_b128 v[198:201], v143 offset:5120
	ds_read_b128 v[202:205], v143 offset:6144
	ds_read_b128 v[206:209], v143 offset:7168
	s_add_i32 m0, s87, 0xc000
	s_nop 0
	global_load_lds_dwordx4 v128, s[50:51]
	v_mov_b32_e32 v128, v136
	s_add_i32 m0, s87, 0xe000
	s_nop 0
	global_load_lds_dwordx4 v128, s[50:51]
	s_waitcnt vmcnt(8)
	s_waitcnt lgkmcnt(0)
	s_setprio 1
	s_barrier
	v_mfma_f32_16x16x32_bf16 v[124:127], v[146:149], v[178:181], 0
	v_mfma_f32_16x16x32_bf16 v[120:123], v[154:157], v[178:181], 0
	v_mfma_f32_16x16x32_bf16 v[104:107], v[154:157], v[186:189], 0
	v_mfma_f32_16x16x32_bf16 v[108:111], v[146:149], v[186:189], 0
	v_mfma_f32_16x16x32_bf16 v[92:95], v[146:149], v[194:197], 0
	v_mfma_f32_16x16x32_bf16 v[88:91], v[154:157], v[194:197], 0
	v_mfma_f32_16x16x32_bf16 v[72:75], v[154:157], v[202:205], 0
	v_mfma_f32_16x16x32_bf16 v[76:79], v[146:149], v[202:205], 0
	v_mfma_f32_16x16x32_bf16 v[124:127], v[150:153], v[182:185], v[124:127]
	v_mfma_f32_16x16x32_bf16 v[120:123], v[158:161], v[182:185], v[120:123]
	v_mfma_f32_16x16x32_bf16 v[104:107], v[158:161], v[190:193], v[104:107]
	v_mfma_f32_16x16x32_bf16 v[108:111], v[150:153], v[190:193], v[108:111]
	v_mfma_f32_16x16x32_bf16 v[92:95], v[150:153], v[198:201], v[92:95]
	v_mfma_f32_16x16x32_bf16 v[88:91], v[158:161], v[198:201], v[88:91]
	v_mfma_f32_16x16x32_bf16 v[72:75], v[158:161], v[206:209], v[72:75]
	v_mfma_f32_16x16x32_bf16 v[76:79], v[150:153], v[206:209], v[76:79]
	s_setprio 0
	s_setprio 1
	v_mfma_f32_16x16x32_bf16 v[116:119], v[162:165], v[178:181], 0
	v_mfma_f32_16x16x32_bf16 v[112:115], v[170:173], v[178:181], 0
	v_mfma_f32_16x16x32_bf16 v[96:99], v[170:173], v[186:189], 0
	v_mfma_f32_16x16x32_bf16 v[100:103], v[162:165], v[186:189], 0
	v_mfma_f32_16x16x32_bf16 v[84:87], v[162:165], v[194:197], 0
	v_mfma_f32_16x16x32_bf16 v[80:83], v[170:173], v[194:197], 0
	v_mfma_f32_16x16x32_bf16 v[56:59], v[170:173], v[202:205], 0
	v_mfma_f32_16x16x32_bf16 v[60:63], v[162:165], v[202:205], 0
	v_mfma_f32_16x16x32_bf16 v[116:119], v[166:169], v[182:185], v[116:119]
	v_mfma_f32_16x16x32_bf16 v[112:115], v[174:177], v[182:185], v[112:115]
	v_mfma_f32_16x16x32_bf16 v[96:99], v[174:177], v[190:193], v[96:99]
	v_mfma_f32_16x16x32_bf16 v[100:103], v[166:169], v[190:193], v[100:103]
	v_mfma_f32_16x16x32_bf16 v[84:87], v[166:169], v[198:201], v[84:87]
	v_mfma_f32_16x16x32_bf16 v[80:83], v[174:177], v[198:201], v[80:83]
	v_mfma_f32_16x16x32_bf16 v[56:59], v[174:177], v[206:209], v[56:59]
	v_mfma_f32_16x16x32_bf16 v[60:63], v[166:169], v[206:209], v[60:63]
	s_barrier
	s_setprio 0
	v_mov_b32_e32 v128, v135
	s_add_i32 s6, s94, s86
	ds_read_b128 v[178:181], v143 offset:16384
	ds_read_b128 v[182:185], v143 offset:17408
	ds_read_b128 v[186:189], v143 offset:18432
	ds_read_b128 v[190:193], v143 offset:19456
	ds_read_b128 v[194:197], v143 offset:20480
	ds_read_b128 v[198:201], v143 offset:21504
	ds_read_b128 v[202:205], v143 offset:22528
	ds_read_b128 v[206:209], v143 offset:23552
	s_mov_b32 m0, s6
	s_nop 0
	global_load_lds_dwordx4 v128, s[66:67]
	v_mov_b32_e32 v128, v137
	s_add_i32 m0, s6, 0x2000
	s_add_u32 s60, s66, 0x40000
	global_load_lds_dwordx4 v128, s[66:67]
	s_addc_u32 s61, s67, 0
	v_mov_b32_e32 v128, v135
	s_add_i32 s6, s95, s86
	s_mov_b32 m0, s6
	s_nop 0
	global_load_lds_dwordx4 v128, s[60:61]
	v_mov_b32_e32 v128, v137
	s_add_i32 m0, s6, 0x2000
	s_nop 0
	global_load_lds_dwordx4 v128, s[60:61]
	v_mov_b32_e32 v128, v134
	s_mov_b32 m0, s87
	s_nop 0
	global_load_lds_dwordx4 v128, s[52:53]
	v_mov_b32_e32 v128, v136
	s_mov_b32 m0, s88
	s_nop 0
	global_load_lds_dwordx4 v128, s[52:53]
	s_waitcnt vmcnt(8)
	s_waitcnt lgkmcnt(0)
	s_setprio 1
	s_barrier
; #define PG8_LDA(dst, b, h) do { if constexpr (FP8) { _Pragma("unroll") for (int m = 0; m < 4; ++m) dst##8[m] = PG8_LD8(PG8_SA(b, h), aoff, aoff1, m); } \
;         else { _Pragma("unroll") for (int m = 0; m < 4; ++m) _Pragma("unroll") for (int k = 0; k < 2; ++k) dst[m][k] = *(const LAS bf16x8*)(lds + PG8_SA(b, h) + (k ? aoff1 : aoff) + m * 2048); } } while (0)
; #define PG8_LDB(dst, b, h) do { if constexpr (FP8) { dst##8[0] = PG8_LD8(PG8_SB(b, h), boff, boff1, 0); dst##8[1] = PG8_LD8(PG8_SB(b, h), boff, boff1, 1); } \
;         else { _Pragma("unroll") for (int n = 0; n < 2; ++n) _Pragma("unroll") for (int k = 0; k < 2; ++k) dst[n][k] = *(const LAS bf16x8*)(lds + PG8_SB(b, h) + (k ? boff1 : boff) + n * 2048); } } while (0)
; #define PG8_WAIT_V(n) asm volatile("s_waitcnt vmcnt(" #n ")" ::: "memory")
; #define PG8_WAIT_L(n) asm volatile("s_waitcnt lgkmcnt(" #n ")" ::: "memory")
; #define PG8_BAR __builtin_amdgcn_s_barrier()
; #define PG8_SCHED __builtin_amdgcn_sched_barrier(0)
; #define PG8_S3 PG8_STAGE(PG8_SA(0, 1), a2 + hstepA, voffA)
; #define PG8_S4 do { PG8_STAGE(PG8_SB(1, 0), b3, voffB); PG8_STAGE(PG8_SB(1, 1), b3 + hstepB, voffB); PG8_STAGE(PG8_SA(1, 0), a3, voffA); } while (0)
; template <class Epi, class SchedT, bool ALIGN_EPI, bool SP2, bool FP8 = false>
; __device__ __forceinline__ void gemm_phase(LAS unsigned char* lds, const Gemm g, const SchedT& S, const Epi& E, const int wid) {
;     ...
;             PG8_WAIT_V(8); PG8_WAIT_L(0); PG8_BAR; PG8_MMAP(1, 0, 1); PG8_BAR; PG8_SCHED;
;             PG8_LDB(B0, 1, 0); PG8_LDB(B1, 1, 1); PG8_SCHED; PG8_LDA(At, 1, 0); PG8_S3;
;             PG8_WAIT_V(8); PG8_WAIT_L(0); PG8_BAR; PG8_MMAP(0, 1, 0); PG8_BAR; PG8_SCHED;
;             PG8_LDA(At, 1, 1); PG8_S4;
	v_mfma_f32_16x16x32_bf16 v[68:71], v[146:149], v[178:181], 0
	v_mfma_f32_16x16x32_bf16 v[64:67], v[154:157], v[178:181], 0
	v_mfma_f32_16x16x32_bf16 v[40:43], v[154:157], v[186:189], 0
	v_mfma_f32_16x16x32_bf16 v[44:47], v[146:149], v[186:189], 0
	v_mfma_f32_16x16x32_bf16 v[28:31], v[146:149], v[194:197], 0
	v_mfma_f32_16x16x32_bf16 v[24:27], v[154:157], v[194:197], 0
	v_mfma_f32_16x16x32_bf16 v[8:11], v[154:157], v[202:205], 0
	v_mfma_f32_16x16x32_bf16 v[12:15], v[146:149], v[202:205], 0
	v_mfma_f32_16x16x32_bf16 v[68:71], v[150:153], v[182:185], v[68:71]
	v_mfma_f32_16x16x32_bf16 v[64:67], v[158:161], v[182:185], v[64:67]
	v_mfma_f32_16x16x32_bf16 v[40:43], v[158:161], v[190:193], v[40:43]
	v_mfma_f32_16x16x32_bf16 v[44:47], v[150:153], v[190:193], v[44:47]
	v_mfma_f32_16x16x32_bf16 v[28:31], v[150:153], v[198:201], v[28:31]
	v_mfma_f32_16x16x32_bf16 v[24:27], v[158:161], v[198:201], v[24:27]
	v_mfma_f32_16x16x32_bf16 v[8:11], v[158:161], v[206:209], v[8:11]
	v_mfma_f32_16x16x32_bf16 v[12:15], v[150:153], v[206:209], v[12:15]
	s_setprio 0
	s_setprio 1
	v_mfma_f32_16x16x32_bf16 v[52:55], v[162:165], v[178:181], 0
	v_mfma_f32_16x16x32_bf16 v[48:51], v[170:173], v[178:181], 0
	v_mfma_f32_16x16x32_bf16 v[32:35], v[170:173], v[186:189], 0
	v_mfma_f32_16x16x32_bf16 v[36:39], v[162:165], v[186:189], 0
	v_mfma_f32_16x16x32_bf16 v[20:23], v[162:165], v[194:197], 0
	v_mfma_f32_16x16x32_bf16 v[16:19], v[170:173], v[194:197], 0
	v_mfma_f32_16x16x32_bf16 v[0:3], v[170:173], v[202:205], 0
	v_mfma_f32_16x16x32_bf16 v[4:7], v[162:165], v[202:205], 0
	v_mfma_f32_16x16x32_bf16 v[52:55], v[166:169], v[182:185], v[52:55]
	v_mfma_f32_16x16x32_bf16 v[48:51], v[174:177], v[182:185], v[48:51]
	v_mfma_f32_16x16x32_bf16 v[32:35], v[174:177], v[190:193], v[32:35]
	v_mfma_f32_16x16x32_bf16 v[36:39], v[166:169], v[190:193], v[36:39]
	v_mfma_f32_16x16x32_bf16 v[20:23], v[166:169], v[198:201], v[20:23]
	v_mfma_f32_16x16x32_bf16 v[16:19], v[174:177], v[198:201], v[16:19]
	v_mfma_f32_16x16x32_bf16 v[0:3], v[174:177], v[206:209], v[0:3]
	v_mfma_f32_16x16x32_bf16 v[4:7], v[166:169], v[206:209], v[4:7]
	s_barrier
	s_setprio 0
	s_add_i32 s6, 0, 0x18000
	v_add_u32_e32 v128, s6, v138
	s_add_i32 s7, 0, 0x1c000
	ds_read_b128 v[146:149], v128
	ds_read_b128 v[150:153], v128 offset:1024
	ds_read_b128 v[154:157], v144
	ds_read_b128 v[158:161], v144 offset:1024
	v_add_u32_e32 v128, s7, v138
	ds_read_b128 v[162:165], v128
	ds_read_b128 v[166:169], v128 offset:1024
	ds_read_b128 v[170:173], v145
	ds_read_b128 v[174:177], v145 offset:1024
	s_add_u32 s60, s52, 0x40000
	v_mov_b32_e32 v128, v134
	s_mov_b32 m0, s89
	ds_read_b128 v[178:181], v143 offset:32768
	ds_read_b128 v[182:185], v143 offset:33792
	ds_read_b128 v[186:189], v143 offset:34816
	ds_read_b128 v[190:193], v143 offset:35840
	ds_read_b128 v[194:197], v143 offset:36864
	ds_read_b128 v[198:201], v143 offset:37888
	ds_read_b128 v[202:205], v143 offset:38912
	ds_read_b128 v[206:209], v143 offset:39936
	s_addc_u32 s61, s53, 0
	s_nop 0
	global_load_lds_dwordx4 v128, s[60:61]
	v_mov_b32_e32 v128, v136
	s_mov_b32 m0, s90
	s_nop 0
	global_load_lds_dwordx4 v128, s[60:61]
	s_waitcnt vmcnt(8)
	s_waitcnt lgkmcnt(0)
	s_setprio 1
	s_barrier
	v_mfma_f32_16x16x32_bf16 v[124:127], v[146:149], v[178:181], v[124:127]
	v_mfma_f32_16x16x32_bf16 v[120:123], v[154:157], v[178:181], v[120:123]
	v_mfma_f32_16x16x32_bf16 v[104:107], v[154:157], v[186:189], v[104:107]
	v_mfma_f32_16x16x32_bf16 v[108:111], v[146:149], v[186:189], v[108:111]
	v_mfma_f32_16x16x32_bf16 v[92:95], v[146:149], v[194:197], v[92:95]
	v_mfma_f32_16x16x32_bf16 v[88:91], v[154:157], v[194:197], v[88:91]
	v_mfma_f32_16x16x32_bf16 v[72:75], v[154:157], v[202:205], v[72:75]
	v_mfma_f32_16x16x32_bf16 v[76:79], v[146:149], v[202:205], v[76:79]
	v_mfma_f32_16x16x32_bf16 v[124:127], v[150:153], v[182:185], v[124:127]
	v_mfma_f32_16x16x32_bf16 v[120:123], v[158:161], v[182:185], v[120:123]
	v_mfma_f32_16x16x32_bf16 v[104:107], v[158:161], v[190:193], v[104:107]
	v_mfma_f32_16x16x32_bf16 v[108:111], v[150:153], v[190:193], v[108:111]
	v_mfma_f32_16x16x32_bf16 v[92:95], v[150:153], v[198:201], v[92:95]
	v_mfma_f32_16x16x32_bf16 v[88:91], v[158:161], v[198:201], v[88:91]
	v_mfma_f32_16x16x32_bf16 v[72:75], v[158:161], v[206:209], v[72:75]
	v_mfma_f32_16x16x32_bf16 v[76:79], v[150:153], v[206:209], v[76:79]
	s_setprio 0
	s_setprio 1
	v_mfma_f32_16x16x32_bf16 v[116:119], v[162:165], v[178:181], v[116:119]
	v_mfma_f32_16x16x32_bf16 v[112:115], v[170:173], v[178:181], v[112:115]
	v_mfma_f32_16x16x32_bf16 v[96:99], v[170:173], v[186:189], v[96:99]
	v_mfma_f32_16x16x32_bf16 v[100:103], v[162:165], v[186:189], v[100:103]
	v_mfma_f32_16x16x32_bf16 v[84:87], v[162:165], v[194:197], v[84:87]
	v_mfma_f32_16x16x32_bf16 v[80:83], v[170:173], v[194:197], v[80:83]
	v_mfma_f32_16x16x32_bf16 v[56:59], v[170:173], v[202:205], v[56:59]
	v_mfma_f32_16x16x32_bf16 v[60:63], v[162:165], v[202:205], v[60:63]
	v_mfma_f32_16x16x32_bf16 v[116:119], v[166:169], v[182:185], v[116:119]
	v_mfma_f32_16x16x32_bf16 v[112:115], v[174:177], v[182:185], v[112:115]
	v_mfma_f32_16x16x32_bf16 v[96:99], v[174:177], v[190:193], v[96:99]
	v_mfma_f32_16x16x32_bf16 v[100:103], v[166:169], v[190:193], v[100:103]
	v_mfma_f32_16x16x32_bf16 v[84:87], v[166:169], v[198:201], v[84:87]
	v_mfma_f32_16x16x32_bf16 v[80:83], v[174:177], v[198:201], v[80:83]
	v_mfma_f32_16x16x32_bf16 v[56:59], v[174:177], v[206:209], v[56:59]
	v_mfma_f32_16x16x32_bf16 v[60:63], v[166:169], v[206:209], v[60:63]
	s_barrier
; #define PG8_LDA(dst, b, h) do { if constexpr (FP8) { _Pragma("unroll") for (int m = 0; m < 4; ++m) dst##8[m] = PG8_LD8(PG8_SA(b, h), aoff, aoff1, m); } \
;         else { _Pragma("unroll") for (int m = 0; m < 4; ++m) _Pragma("unroll") for (int k = 0; k < 2; ++k) dst[m][k] = *(const LAS bf16x8*)(lds + PG8_SA(b, h) + (k ? aoff1 : aoff) + m * 2048); } } while (0)
; #define PG8_LDB(dst, b, h) do { if constexpr (FP8) { dst##8[0] = PG8_LD8(PG8_SB(b, h), boff, boff1, 0); dst##8[1] = PG8_LD8(PG8_SB(b, h), boff, boff1, 1); } \
;         else { _Pragma("unroll") for (int n = 0; n < 2; ++n) _Pragma("unroll") for (int k = 0; k < 2; ++k) dst[n][k] = *(const LAS bf16x8*)(lds + PG8_SB(b, h) + (k ? boff1 : boff) + n * 2048); } } while (0)
; #define PG8_WAIT_V(n) asm volatile("s_waitcnt vmcnt(" #n ")" ::: "memory")
; #define PG8_WAIT_L(n) asm volatile("s_waitcnt lgkmcnt(" #n ")" ::: "memory")
; #define PG8_BAR __builtin_amdgcn_s_barrier()
; #define PG8_SCHED __builtin_amdgcn_sched_barrier(0)
; #define PG8_S1 PG8_STAGE(PG8_SA(1, 1), a1 + hstepA, voffA)
; #define PG8_S4 do { PG8_STAGE(PG8_SB(1, 0), b3, voffB); PG8_STAGE(PG8_SB(1, 1), b3 + hstepB, voffB); PG8_STAGE(PG8_SA(1, 0), a3, voffA); } while (0)
; template <class Epi, class SchedT, bool ALIGN_EPI, bool SP2, bool FP8 = false>
; __device__ __forceinline__ void gemm_phase(LAS unsigned char* lds, const Gemm g, const SchedT& S, const Epi& E, const int wid) {
;     ...
;         for (int t = 0; t < nt; t += 2) {
;             const bool last = (t == nt - 2);
;             const char* a1 = cA + (size_t)(t + 1) * kstep;
;             const char* a2 = last ? nA : cA + (size_t)(t + 2) * kstep; const char* b2 = last ? nB : cB + (size_t)(t + 2) * kstep;
;             const char* a3 = a2 + kstep; const char* b3 = b2 + kstep;
;             if constexpr (SP2) {
;     ...
;             PG8_LDB(B0, 0, 0); PG8_LDB(B1, 0, 1); PG8_SCHED; PG8_LDA(At, 0, 0); PG8_S1;
;             PG8_WAIT_V(8); PG8_WAIT_L(0); PG8_BAR; PG8_MMAP(0, 0, 0); PG8_BAR; PG8_SCHED;
;     ...
;             PG8_WAIT_V(8); PG8_WAIT_L(0); PG8_BAR; PG8_MMAP(0, 1, 0); PG8_BAR; PG8_SCHED;
;             PG8_LDA(At, 1, 1); PG8_S4;
;             PG8_WAIT_V(8); PG8_WAIT_L(0); PG8_BAR; PG8_MMAP(1, 1, 1); PG8_BAR; PG8_SCHED;
	s_setprio 0
	v_mov_b32_e32 v128, v135
	ds_read_b128 v[178:181], v143 offset:49152
	ds_read_b128 v[182:185], v143 offset:50176
	ds_read_b128 v[186:189], v143 offset:51200
	ds_read_b128 v[190:193], v143 offset:52224
	ds_read_b128 v[194:197], v143 offset:53248
	ds_read_b128 v[198:201], v143 offset:54272
	ds_read_b128 v[202:205], v143 offset:55296
	ds_read_b128 v[206:209], v143 offset:56320
	s_add_i32 s6, s6, s86
	v_lshl_add_u64 v[210:211], s[66:67], 0, v[128:129]
	v_lshl_add_u64 v[210:211], v[210:211], 0, s[36:37]
	s_mov_b32 m0, s6
	v_mov_b32_e32 v128, v137
	global_load_lds_dwordx4 v[210:211], off
	s_add_i32 m0, s6, 0x2000
	s_add_u32 s60, s66, 0x40080
	v_lshl_add_u64 v[210:211], s[66:67], 0, v[128:129]
	v_lshl_add_u64 v[210:211], v[210:211], 0, s[36:37]
	s_addc_u32 s61, s67, 0
	v_mov_b32_e32 v128, v135
	s_add_i32 s6, s7, s86
	global_load_lds_dwordx4 v[210:211], off
	s_mov_b32 m0, s6
	s_nop 0
	global_load_lds_dwordx4 v128, s[60:61]
	v_mov_b32_e32 v128, v137
	s_add_i32 m0, s6, 0x2000
	s_nop 0
	global_load_lds_dwordx4 v128, s[60:61]
	v_mov_b32_e32 v128, v134
	s_mov_b32 m0, s92
	v_lshl_add_u64 v[210:211], s[52:53], 0, v[128:129]
	v_lshl_add_u64 v[210:211], v[210:211], 0, s[36:37]
	v_mov_b32_e32 v128, v136
	global_load_lds_dwordx4 v[210:211], off
	s_mov_b32 m0, s93
	v_lshl_add_u64 v[210:211], s[52:53], 0, v[128:129]
	v_lshl_add_u64 v[210:211], v[210:211], 0, s[36:37]
	global_load_lds_dwordx4 v[210:211], off
	s_waitcnt vmcnt(8)
	s_waitcnt lgkmcnt(0)
	s_setprio 1
	s_barrier
	v_mfma_f32_16x16x32_bf16 v[68:71], v[146:149], v[178:181], v[68:71]
	v_mfma_f32_16x16x32_bf16 v[64:67], v[154:157], v[178:181], v[64:67]
	v_mfma_f32_16x16x32_bf16 v[40:43], v[154:157], v[186:189], v[40:43]
	v_mfma_f32_16x16x32_bf16 v[44:47], v[146:149], v[186:189], v[44:47]
	v_mfma_f32_16x16x32_bf16 v[28:31], v[146:149], v[194:197], v[28:31]
	v_mfma_f32_16x16x32_bf16 v[24:27], v[154:157], v[194:197], v[24:27]
	v_mfma_f32_16x16x32_bf16 v[8:11], v[154:157], v[202:205], v[8:11]
	v_mfma_f32_16x16x32_bf16 v[12:15], v[146:149], v[202:205], v[12:15]
	v_mfma_f32_16x16x32_bf16 v[68:71], v[150:153], v[182:185], v[68:71]
	v_mfma_f32_16x16x32_bf16 v[64:67], v[158:161], v[182:185], v[64:67]
	v_mfma_f32_16x16x32_bf16 v[40:43], v[158:161], v[190:193], v[40:43]
	v_mfma_f32_16x16x32_bf16 v[44:47], v[150:153], v[190:193], v[44:47]
	v_mfma_f32_16x16x32_bf16 v[28:31], v[150:153], v[198:201], v[28:31]
	v_mfma_f32_16x16x32_bf16 v[24:27], v[158:161], v[198:201], v[24:27]
	v_mfma_f32_16x16x32_bf16 v[8:11], v[158:161], v[206:209], v[8:11]
	v_mfma_f32_16x16x32_bf16 v[12:15], v[150:153], v[206:209], v[12:15]
	s_setprio 0
	s_setprio 1
	v_mfma_f32_16x16x32_bf16 v[52:55], v[162:165], v[178:181], v[52:55]
	v_mfma_f32_16x16x32_bf16 v[48:51], v[170:173], v[178:181], v[48:51]
	v_mfma_f32_16x16x32_bf16 v[32:35], v[170:173], v[186:189], v[32:35]
	v_mfma_f32_16x16x32_bf16 v[36:39], v[162:165], v[186:189], v[36:39]
	v_mfma_f32_16x16x32_bf16 v[20:23], v[162:165], v[194:197], v[20:23]
	v_mfma_f32_16x16x32_bf16 v[16:19], v[170:173], v[194:197], v[16:19]
	v_mfma_f32_16x16x32_bf16 v[0:3], v[170:173], v[202:205], v[0:3]
	v_mfma_f32_16x16x32_bf16 v[4:7], v[162:165], v[202:205], v[4:7]
	v_mfma_f32_16x16x32_bf16 v[52:55], v[166:169], v[182:185], v[52:55]
	v_mfma_f32_16x16x32_bf16 v[48:51], v[174:177], v[182:185], v[48:51]
	v_mfma_f32_16x16x32_bf16 v[32:35], v[174:177], v[190:193], v[32:35]
	v_mfma_f32_16x16x32_bf16 v[36:39], v[166:169], v[190:193], v[36:39]
	v_mfma_f32_16x16x32_bf16 v[20:23], v[166:169], v[198:201], v[20:23]
	v_mfma_f32_16x16x32_bf16 v[16:19], v[174:177], v[198:201], v[16:19]
	v_mfma_f32_16x16x32_bf16 v[0:3], v[174:177], v[206:209], v[0:3]
	v_mfma_f32_16x16x32_bf16 v[4:7], v[166:169], v[206:209], v[4:7]
	s_barrier
	s_setprio 0
	s_add_u32 s50, s50, 0x100
	s_addc_u32 s51, s51, 0
	s_add_u32 s31, s31, 0x100
	s_addc_u32 s38, s38, 0
	s_cmp_ge_i32 s43, s8
	s_mov_b32 s39, s43
	s_cbranch_scc1 .Lpeel_exit_lbb0_256
.LBB0_256:
	ds_read_b128 v[146:149], v139
	ds_read_b128 v[150:153], v139 offset:1024
	ds_read_b128 v[154:157], v140
	ds_read_b128 v[158:161], v140 offset:1024
	ds_read_b128 v[162:165], v141
	ds_read_b128 v[166:169], v141 offset:1024
	ds_read_b128 v[170:173], v142
	ds_read_b128 v[174:177], v142 offset:1024
	s_add_i32 s43, s39, 2
	s_add_u32 s6, s50, 0xfffc0080
	s_addc_u32 s7, s51, -1
	s_cmp_eq_u32 s30, s39
	s_cselect_b32 s53, s9, s7
	s_cselect_b32 s52, s20, s6
	s_cselect_b32 s67, s21, s38
	s_cselect_b32 s66, s24, s31
	v_mov_b32_e32 v128, v134
	ds_read_b128 v[178:181], v143
	ds_read_b128 v[182:185], v143 offset:1024
	ds_read_b128 v[186:189], v143 offset:2048
	ds_read_b128 v[190:193], v143 offset:3072
	ds_read_b128 v[194:197], v143 offset:4096
	ds_read_b128 v[198:201], v143 offset:5120
	ds_read_b128 v[202:205], v143 offset:6144
	ds_read_b128 v[206:209], v143 offset:7168
	s_add_i32 m0, s87, 0xc000
	s_nop 0
	global_load_lds_dwordx4 v128, s[50:51]
	v_mov_b32_e32 v128, v136
	s_add_i32 m0, s87, 0xe000
	s_nop 0
	global_load_lds_dwordx4 v128, s[50:51]
	s_waitcnt vmcnt(8)
	s_waitcnt lgkmcnt(0)
	s_setprio 1
	s_barrier
; #define PG8_LDA(dst, b, h) do { if constexpr (FP8) { _Pragma("unroll") for (int m = 0; m < 4; ++m) dst##8[m] = PG8_LD8(PG8_SA(b, h), aoff, aoff1, m); } \
;         else { _Pragma("unroll") for (int m = 0; m < 4; ++m) _Pragma("unroll") for (int k = 0; k < 2; ++k) dst[m][k] = *(const LAS bf16x8*)(lds + PG8_SA(b, h) + (k ? aoff1 : aoff) + m * 2048); } } while (0)
; #define PG8_LDB(dst, b, h) do { if constexpr (FP8) { dst##8[0] = PG8_LD8(PG8_SB(b, h), boff, boff1, 0); dst##8[1] = PG8_LD8(PG8_SB(b, h), boff, boff1, 1); } \
;         else { _Pragma("unroll") for (int n = 0; n < 2; ++n) _Pragma("unroll") for (int k = 0; k < 2; ++k) dst[n][k] = *(const LAS bf16x8*)(lds + PG8_SB(b, h) + (k ? boff1 : boff) + n * 2048); } } while (0)
; #define PG8_WAIT_V(n) asm volatile("s_waitcnt vmcnt(" #n ")" ::: "memory")
; #define PG8_WAIT_L(n) asm volatile("s_waitcnt lgkmcnt(" #n ")" ::: "memory")
; #define PG8_BAR __builtin_amdgcn_s_barrier()
; #define PG8_SCHED __builtin_amdgcn_sched_barrier(0)
; #define PG8_S2 do { PG8_STAGE(PG8_SB(0, 0), b2, voffB); PG8_STAGE(PG8_SB(0, 1), b2 + hstepB, voffB); PG8_STAGE(PG8_SA(0, 0), a2, voffA); } while (0)
; #define PG8_S3 PG8_STAGE(PG8_SA(0, 1), a2 + hstepA, voffA)
; template <class Epi, class SchedT, bool ALIGN_EPI, bool SP2, bool FP8 = false>
; __device__ __forceinline__ void gemm_phase(LAS unsigned char* lds, const Gemm g, const SchedT& S, const Epi& E, const int wid) {
;     ...
;             PG8_WAIT_V(8); PG8_WAIT_L(0); PG8_BAR; PG8_MMAP(0, 0, 0); PG8_BAR; PG8_SCHED;
;             PG8_LDA(At, 0, 1); PG8_S2;
;             PG8_WAIT_V(8); PG8_WAIT_L(0); PG8_BAR; PG8_MMAP(1, 0, 1); PG8_BAR; PG8_SCHED;
;             PG8_LDB(B0, 1, 0); PG8_LDB(B1, 1, 1); PG8_SCHED; PG8_LDA(At, 1, 0); PG8_S3;
;             PG8_WAIT_V(8); PG8_WAIT_L(0); PG8_BAR; PG8_MMAP(0, 1, 0); PG8_BAR; PG8_SCHED;
	v_mfma_f32_16x16x32_bf16 v[124:127], v[146:149], v[178:181], v[124:127]
	v_mfma_f32_16x16x32_bf16 v[120:123], v[154:157], v[178:181], v[120:123]
	v_mfma_f32_16x16x32_bf16 v[104:107], v[154:157], v[186:189], v[104:107]
	v_mfma_f32_16x16x32_bf16 v[108:111], v[146:149], v[186:189], v[108:111]
	v_mfma_f32_16x16x32_bf16 v[92:95], v[146:149], v[194:197], v[92:95]
	v_mfma_f32_16x16x32_bf16 v[88:91], v[154:157], v[194:197], v[88:91]
	v_mfma_f32_16x16x32_bf16 v[72:75], v[154:157], v[202:205], v[72:75]
	v_mfma_f32_16x16x32_bf16 v[76:79], v[146:149], v[202:205], v[76:79]
	v_mfma_f32_16x16x32_bf16 v[124:127], v[150:153], v[182:185], v[124:127]
	v_mfma_f32_16x16x32_bf16 v[120:123], v[158:161], v[182:185], v[120:123]
	v_mfma_f32_16x16x32_bf16 v[104:107], v[158:161], v[190:193], v[104:107]
	v_mfma_f32_16x16x32_bf16 v[108:111], v[150:153], v[190:193], v[108:111]
	v_mfma_f32_16x16x32_bf16 v[92:95], v[150:153], v[198:201], v[92:95]
	v_mfma_f32_16x16x32_bf16 v[88:91], v[158:161], v[198:201], v[88:91]
	v_mfma_f32_16x16x32_bf16 v[72:75], v[158:161], v[206:209], v[72:75]
	v_mfma_f32_16x16x32_bf16 v[76:79], v[150:153], v[206:209], v[76:79]
	s_setprio 0
	s_setprio 1
	v_mfma_f32_16x16x32_bf16 v[116:119], v[162:165], v[178:181], v[116:119]
	v_mfma_f32_16x16x32_bf16 v[112:115], v[170:173], v[178:181], v[112:115]
	v_mfma_f32_16x16x32_bf16 v[96:99], v[170:173], v[186:189], v[96:99]
	v_mfma_f32_16x16x32_bf16 v[100:103], v[162:165], v[186:189], v[100:103]
	v_mfma_f32_16x16x32_bf16 v[84:87], v[162:165], v[194:197], v[84:87]
	v_mfma_f32_16x16x32_bf16 v[80:83], v[170:173], v[194:197], v[80:83]
	v_mfma_f32_16x16x32_bf16 v[56:59], v[170:173], v[202:205], v[56:59]
	v_mfma_f32_16x16x32_bf16 v[60:63], v[162:165], v[202:205], v[60:63]
	v_mfma_f32_16x16x32_bf16 v[116:119], v[166:169], v[182:185], v[116:119]
	v_mfma_f32_16x16x32_bf16 v[112:115], v[174:177], v[182:185], v[112:115]
	v_mfma_f32_16x16x32_bf16 v[96:99], v[174:177], v[190:193], v[96:99]
	v_mfma_f32_16x16x32_bf16 v[100:103], v[166:169], v[190:193], v[100:103]
	v_mfma_f32_16x16x32_bf16 v[84:87], v[166:169], v[198:201], v[84:87]
	v_mfma_f32_16x16x32_bf16 v[80:83], v[174:177], v[198:201], v[80:83]
	v_mfma_f32_16x16x32_bf16 v[56:59], v[174:177], v[206:209], v[56:59]
	v_mfma_f32_16x16x32_bf16 v[60:63], v[166:169], v[206:209], v[60:63]
	s_barrier
	s_setprio 0
	v_mov_b32_e32 v128, v135
	s_add_i32 s6, s94, s86
	ds_read_b128 v[178:181], v143 offset:16384
	ds_read_b128 v[182:185], v143 offset:17408
	ds_read_b128 v[186:189], v143 offset:18432
	ds_read_b128 v[190:193], v143 offset:19456
	ds_read_b128 v[194:197], v143 offset:20480
	ds_read_b128 v[198:201], v143 offset:21504
	ds_read_b128 v[202:205], v143 offset:22528
	ds_read_b128 v[206:209], v143 offset:23552
	s_mov_b32 m0, s6
	s_nop 0
	global_load_lds_dwordx4 v128, s[66:67]
	v_mov_b32_e32 v128, v137
	s_add_i32 m0, s6, 0x2000
	s_add_u32 s60, s66, 0x40000
	global_load_lds_dwordx4 v128, s[66:67]
	s_addc_u32 s61, s67, 0
	v_mov_b32_e32 v128, v135
	s_add_i32 s6, s95, s86
	s_mov_b32 m0, s6
	s_nop 0
	global_load_lds_dwordx4 v128, s[60:61]
	v_mov_b32_e32 v128, v137
	s_add_i32 m0, s6, 0x2000
	s_nop 0
	global_load_lds_dwordx4 v128, s[60:61]
	v_mov_b32_e32 v128, v134
	s_mov_b32 m0, s87
	s_nop 0
	global_load_lds_dwordx4 v128, s[52:53]
	v_mov_b32_e32 v128, v136
	s_mov_b32 m0, s88
	s_nop 0
	global_load_lds_dwordx4 v128, s[52:53]
	s_waitcnt vmcnt(8)
	s_waitcnt lgkmcnt(0)
	s_setprio 1
	s_barrier
	v_mfma_f32_16x16x32_bf16 v[68:71], v[146:149], v[178:181], v[68:71]
	v_mfma_f32_16x16x32_bf16 v[64:67], v[154:157], v[178:181], v[64:67]
	v_mfma_f32_16x16x32_bf16 v[40:43], v[154:157], v[186:189], v[40:43]
	v_mfma_f32_16x16x32_bf16 v[44:47], v[146:149], v[186:189], v[44:47]
	v_mfma_f32_16x16x32_bf16 v[28:31], v[146:149], v[194:197], v[28:31]
	v_mfma_f32_16x16x32_bf16 v[24:27], v[154:157], v[194:197], v[24:27]
	v_mfma_f32_16x16x32_bf16 v[8:11], v[154:157], v[202:205], v[8:11]
	v_mfma_f32_16x16x32_bf16 v[12:15], v[146:149], v[202:205], v[12:15]
	v_mfma_f32_16x16x32_bf16 v[68:71], v[150:153], v[182:185], v[68:71]
	v_mfma_f32_16x16x32_bf16 v[64:67], v[158:161], v[182:185], v[64:67]
	v_mfma_f32_16x16x32_bf16 v[40:43], v[158:161], v[190:193], v[40:43]
	v_mfma_f32_16x16x32_bf16 v[44:47], v[150:153], v[190:193], v[44:47]
	v_mfma_f32_16x16x32_bf16 v[28:31], v[150:153], v[198:201], v[28:31]
	v_mfma_f32_16x16x32_bf16 v[24:27], v[158:161], v[198:201], v[24:27]
	v_mfma_f32_16x16x32_bf16 v[8:11], v[158:161], v[206:209], v[8:11]
	v_mfma_f32_16x16x32_bf16 v[12:15], v[150:153], v[206:209], v[12:15]
	s_setprio 0
	s_setprio 1
	v_mfma_f32_16x16x32_bf16 v[52:55], v[162:165], v[178:181], v[52:55]
	v_mfma_f32_16x16x32_bf16 v[48:51], v[170:173], v[178:181], v[48:51]
	v_mfma_f32_16x16x32_bf16 v[32:35], v[170:173], v[186:189], v[32:35]
	v_mfma_f32_16x16x32_bf16 v[36:39], v[162:165], v[186:189], v[36:39]
	v_mfma_f32_16x16x32_bf16 v[20:23], v[162:165], v[194:197], v[20:23]
	v_mfma_f32_16x16x32_bf16 v[16:19], v[170:173], v[194:197], v[16:19]
	v_mfma_f32_16x16x32_bf16 v[0:3], v[170:173], v[202:205], v[0:3]
	v_mfma_f32_16x16x32_bf16 v[4:7], v[162:165], v[202:205], v[4:7]
	v_mfma_f32_16x16x32_bf16 v[52:55], v[166:169], v[182:185], v[52:55]
	v_mfma_f32_16x16x32_bf16 v[48:51], v[174:177], v[182:185], v[48:51]
	v_mfma_f32_16x16x32_bf16 v[32:35], v[174:177], v[190:193], v[32:35]
	v_mfma_f32_16x16x32_bf16 v[36:39], v[166:169], v[190:193], v[36:39]
	v_mfma_f32_16x16x32_bf16 v[20:23], v[166:169], v[198:201], v[20:23]
	v_mfma_f32_16x16x32_bf16 v[16:19], v[174:177], v[198:201], v[16:19]
	v_mfma_f32_16x16x32_bf16 v[0:3], v[174:177], v[206:209], v[0:3]
	v_mfma_f32_16x16x32_bf16 v[4:7], v[166:169], v[206:209], v[4:7]
	s_barrier
; #define PG8_LDA(dst, b, h) do { if constexpr (FP8) { _Pragma("unroll") for (int m = 0; m < 4; ++m) dst##8[m] = PG8_LD8(PG8_SA(b, h), aoff, aoff1, m); } \
;         else { _Pragma("unroll") for (int m = 0; m < 4; ++m) _Pragma("unroll") for (int k = 0; k < 2; ++k) dst[m][k] = *(const LAS bf16x8*)(lds + PG8_SA(b, h) + (k ? aoff1 : aoff) + m * 2048); } } while (0)
; #define PG8_LDB(dst, b, h) do { if constexpr (FP8) { dst##8[0] = PG8_LD8(PG8_SB(b, h), boff, boff1, 0); dst##8[1] = PG8_LD8(PG8_SB(b, h), boff, boff1, 1); } \
;         else { _Pragma("unroll") for (int n = 0; n < 2; ++n) _Pragma("unroll") for (int k = 0; k < 2; ++k) dst[n][k] = *(const LAS bf16x8*)(lds + PG8_SB(b, h) + (k ? boff1 : boff) + n * 2048); } } while (0)
; #define PG8_WAIT_V(n) asm volatile("s_waitcnt vmcnt(" #n ")" ::: "memory")
; #define PG8_WAIT_L(n) asm volatile("s_waitcnt lgkmcnt(" #n ")" ::: "memory")
; #define PG8_BAR __builtin_amdgcn_s_barrier()
; #define PG8_SCHED __builtin_amdgcn_sched_barrier(0)
; #define PG8_S3 PG8_STAGE(PG8_SA(0, 1), a2 + hstepA, voffA)
; template <class Epi, class SchedT, bool ALIGN_EPI, bool SP2, bool FP8 = false>
; __device__ __forceinline__ void gemm_phase(LAS unsigned char* lds, const Gemm g, const SchedT& S, const Epi& E, const int wid) {
;     ...
;             PG8_LDB(B0, 1, 0); PG8_LDB(B1, 1, 1); PG8_SCHED; PG8_LDA(At, 1, 0); PG8_S3;
;             PG8_WAIT_V(8); PG8_WAIT_L(0); PG8_BAR; PG8_MMAP(0, 1, 0); PG8_BAR; PG8_SCHED;
	s_setprio 0
	s_add_i32 s6, 0, 0x18000
	v_add_u32_e32 v128, s6, v138
	s_add_i32 s7, 0, 0x1c000
	ds_read_b128 v[146:149], v128
	ds_read_b128 v[150:153], v128 offset:1024
	ds_read_b128 v[154:157], v144
	ds_read_b128 v[158:161], v144 offset:1024
	v_add_u32_e32 v128, s7, v138
	ds_read_b128 v[162:165], v128
	ds_read_b128 v[166:169], v128 offset:1024
	ds_read_b128 v[170:173], v145
	ds_read_b128 v[174:177], v145 offset:1024
	s_add_u32 s60, s52, 0x40000
	v_mov_b32_e32 v128, v134
	s_mov_b32 m0, s89
	ds_read_b128 v[178:181], v143 offset:32768
	ds_read_b128 v[182:185], v143 offset:33792
	ds_read_b128 v[186:189], v143 offset:34816
	ds_read_b128 v[190:193], v143 offset:35840
	ds_read_b128 v[194:197], v143 offset:36864
	ds_read_b128 v[198:201], v143 offset:37888
	ds_read_b128 v[202:205], v143 offset:38912
	ds_read_b128 v[206:209], v143 offset:39936
	s_addc_u32 s61, s53, 0
	s_nop 0
	global_load_lds_dwordx4 v128, s[60:61]
	v_mov_b32_e32 v128, v136
	s_mov_b32 m0, s90
	s_nop 0
	global_load_lds_dwordx4 v128, s[60:61]
	s_waitcnt vmcnt(8)
	s_waitcnt lgkmcnt(0)
	s_setprio 1
	s_barrier
	v_mfma_f32_16x16x32_bf16 v[124:127], v[146:149], v[178:181], v[124:127]
	v_mfma_f32_16x16x32_bf16 v[120:123], v[154:157], v[178:181], v[120:123]
	v_mfma_f32_16x16x32_bf16 v[104:107], v[154:157], v[186:189], v[104:107]
	v_mfma_f32_16x16x32_bf16 v[108:111], v[146:149], v[186:189], v[108:111]
	v_mfma_f32_16x16x32_bf16 v[92:95], v[146:149], v[194:197], v[92:95]
	v_mfma_f32_16x16x32_bf16 v[88:91], v[154:157], v[194:197], v[88:91]
	v_mfma_f32_16x16x32_bf16 v[72:75], v[154:157], v[202:205], v[72:75]
	v_mfma_f32_16x16x32_bf16 v[76:79], v[146:149], v[202:205], v[76:79]
	v_mfma_f32_16x16x32_bf16 v[124:127], v[150:153], v[182:185], v[124:127]
	v_mfma_f32_16x16x32_bf16 v[120:123], v[158:161], v[182:185], v[120:123]
	v_mfma_f32_16x16x32_bf16 v[104:107], v[158:161], v[190:193], v[104:107]
	v_mfma_f32_16x16x32_bf16 v[108:111], v[150:153], v[190:193], v[108:111]
	v_mfma_f32_16x16x32_bf16 v[92:95], v[150:153], v[198:201], v[92:95]
	v_mfma_f32_16x16x32_bf16 v[88:91], v[158:161], v[198:201], v[88:91]
	v_mfma_f32_16x16x32_bf16 v[72:75], v[158:161], v[206:209], v[72:75]
	v_mfma_f32_16x16x32_bf16 v[76:79], v[150:153], v[206:209], v[76:79]
	s_setprio 0
	s_setprio 1
	v_mfma_f32_16x16x32_bf16 v[116:119], v[162:165], v[178:181], v[116:119]
	v_mfma_f32_16x16x32_bf16 v[112:115], v[170:173], v[178:181], v[112:115]
	v_mfma_f32_16x16x32_bf16 v[96:99], v[170:173], v[186:189], v[96:99]
	v_mfma_f32_16x16x32_bf16 v[100:103], v[162:165], v[186:189], v[100:103]
	v_mfma_f32_16x16x32_bf16 v[84:87], v[162:165], v[194:197], v[84:87]
	v_mfma_f32_16x16x32_bf16 v[80:83], v[170:173], v[194:197], v[80:83]
	v_mfma_f32_16x16x32_bf16 v[56:59], v[170:173], v[202:205], v[56:59]
	v_mfma_f32_16x16x32_bf16 v[60:63], v[162:165], v[202:205], v[60:63]
	v_mfma_f32_16x16x32_bf16 v[116:119], v[166:169], v[182:185], v[116:119]
	v_mfma_f32_16x16x32_bf16 v[112:115], v[174:177], v[182:185], v[112:115]
	v_mfma_f32_16x16x32_bf16 v[96:99], v[174:177], v[190:193], v[96:99]
	v_mfma_f32_16x16x32_bf16 v[100:103], v[166:169], v[190:193], v[100:103]
	v_mfma_f32_16x16x32_bf16 v[84:87], v[166:169], v[198:201], v[84:87]
	v_mfma_f32_16x16x32_bf16 v[80:83], v[174:177], v[198:201], v[80:83]
	v_mfma_f32_16x16x32_bf16 v[56:59], v[174:177], v[206:209], v[56:59]
	v_mfma_f32_16x16x32_bf16 v[60:63], v[166:169], v[206:209], v[60:63]
	s_barrier
; #define PG8_LDA(dst, b, h) do { if constexpr (FP8) { _Pragma("unroll") for (int m = 0; m < 4; ++m) dst##8[m] = PG8_LD8(PG8_SA(b, h), aoff, aoff1, m); } \
;         else { _Pragma("unroll") for (int m = 0; m < 4; ++m) _Pragma("unroll") for (int k = 0; k < 2; ++k) dst[m][k] = *(const LAS bf16x8*)(lds + PG8_SA(b, h) + (k ? aoff1 : aoff) + m * 2048); } } while (0)
; #define PG8_WAIT_V(n) asm volatile("s_waitcnt vmcnt(" #n ")" ::: "memory")
; #define PG8_WAIT_L(n) asm volatile("s_waitcnt lgkmcnt(" #n ")" ::: "memory")
; #define PG8_BAR __builtin_amdgcn_s_barrier()
; #define PG8_SCHED __builtin_amdgcn_sched_barrier(0)
; #define PG8_S4 do { PG8_STAGE(PG8_SB(1, 0), b3, voffB); PG8_STAGE(PG8_SB(1, 1), b3 + hstepB, voffB); PG8_STAGE(PG8_SA(1, 0), a3, voffA); } while (0)
; template <class Epi, class SchedT, bool ALIGN_EPI, bool SP2, bool FP8 = false>
; __device__ __forceinline__ void gemm_phase(LAS unsigned char* lds, const Gemm g, const SchedT& S, const Epi& E, const int wid) {
;     ...
;             PG8_LDA(At, 1, 1); PG8_S4;
;             PG8_WAIT_V(8); PG8_WAIT_L(0); PG8_BAR; PG8_MMAP(1, 1, 1); PG8_BAR; PG8_SCHED;
	s_setprio 0
	v_mov_b32_e32 v128, v135
	ds_read_b128 v[178:181], v143 offset:49152
	ds_read_b128 v[182:185], v143 offset:50176
	ds_read_b128 v[186:189], v143 offset:51200
	ds_read_b128 v[190:193], v143 offset:52224
	ds_read_b128 v[194:197], v143 offset:53248
	ds_read_b128 v[198:201], v143 offset:54272
	ds_read_b128 v[202:205], v143 offset:55296
	ds_read_b128 v[206:209], v143 offset:56320
	s_add_i32 s6, s6, s86
	v_lshl_add_u64 v[210:211], s[66:67], 0, v[128:129]
	v_lshl_add_u64 v[210:211], v[210:211], 0, s[36:37]
	s_mov_b32 m0, s6
	v_mov_b32_e32 v128, v137
	global_load_lds_dwordx4 v[210:211], off
	s_add_i32 m0, s6, 0x2000
	s_add_u32 s60, s66, 0x40080
	v_lshl_add_u64 v[210:211], s[66:67], 0, v[128:129]
	v_lshl_add_u64 v[210:211], v[210:211], 0, s[36:37]
	s_addc_u32 s61, s67, 0
	v_mov_b32_e32 v128, v135
	s_add_i32 s6, s7, s86
	global_load_lds_dwordx4 v[210:211], off
	s_mov_b32 m0, s6
	s_nop 0
	global_load_lds_dwordx4 v128, s[60:61]
	v_mov_b32_e32 v128, v137
	s_add_i32 m0, s6, 0x2000
	s_nop 0
	global_load_lds_dwordx4 v128, s[60:61]
	v_mov_b32_e32 v128, v134
	s_mov_b32 m0, s92
	v_lshl_add_u64 v[210:211], s[52:53], 0, v[128:129]
	v_lshl_add_u64 v[210:211], v[210:211], 0, s[36:37]
	v_mov_b32_e32 v128, v136
	global_load_lds_dwordx4 v[210:211], off
	s_mov_b32 m0, s93
	v_lshl_add_u64 v[210:211], s[52:53], 0, v[128:129]
	v_lshl_add_u64 v[210:211], v[210:211], 0, s[36:37]
	global_load_lds_dwordx4 v[210:211], off
	s_waitcnt vmcnt(8)
	s_waitcnt lgkmcnt(0)
	s_setprio 1
	s_barrier
	v_mfma_f32_16x16x32_bf16 v[68:71], v[146:149], v[178:181], v[68:71]
	v_mfma_f32_16x16x32_bf16 v[64:67], v[154:157], v[178:181], v[64:67]
	v_mfma_f32_16x16x32_bf16 v[40:43], v[154:157], v[186:189], v[40:43]
	v_mfma_f32_16x16x32_bf16 v[44:47], v[146:149], v[186:189], v[44:47]
	v_mfma_f32_16x16x32_bf16 v[28:31], v[146:149], v[194:197], v[28:31]
	v_mfma_f32_16x16x32_bf16 v[24:27], v[154:157], v[194:197], v[24:27]
	v_mfma_f32_16x16x32_bf16 v[8:11], v[154:157], v[202:205], v[8:11]
	v_mfma_f32_16x16x32_bf16 v[12:15], v[146:149], v[202:205], v[12:15]
	v_mfma_f32_16x16x32_bf16 v[68:71], v[150:153], v[182:185], v[68:71]
	v_mfma_f32_16x16x32_bf16 v[64:67], v[158:161], v[182:185], v[64:67]
	v_mfma_f32_16x16x32_bf16 v[40:43], v[158:161], v[190:193], v[40:43]
	v_mfma_f32_16x16x32_bf16 v[44:47], v[150:153], v[190:193], v[44:47]
	v_mfma_f32_16x16x32_bf16 v[28:31], v[150:153], v[198:201], v[28:31]
	v_mfma_f32_16x16x32_bf16 v[24:27], v[158:161], v[198:201], v[24:27]
	v_mfma_f32_16x16x32_bf16 v[8:11], v[158:161], v[206:209], v[8:11]
	v_mfma_f32_16x16x32_bf16 v[12:15], v[150:153], v[206:209], v[12:15]
	s_setprio 0
	s_setprio 1
	v_mfma_f32_16x16x32_bf16 v[52:55], v[162:165], v[178:181], v[52:55]
	v_mfma_f32_16x16x32_bf16 v[48:51], v[170:173], v[178:181], v[48:51]
	v_mfma_f32_16x16x32_bf16 v[32:35], v[170:173], v[186:189], v[32:35]
	v_mfma_f32_16x16x32_bf16 v[36:39], v[162:165], v[186:189], v[36:39]
	v_mfma_f32_16x16x32_bf16 v[20:23], v[162:165], v[194:197], v[20:23]
	v_mfma_f32_16x16x32_bf16 v[16:19], v[170:173], v[194:197], v[16:19]
	v_mfma_f32_16x16x32_bf16 v[0:3], v[170:173], v[202:205], v[0:3]
	v_mfma_f32_16x16x32_bf16 v[4:7], v[162:165], v[202:205], v[4:7]
	v_mfma_f32_16x16x32_bf16 v[52:55], v[166:169], v[182:185], v[52:55]
	v_mfma_f32_16x16x32_bf16 v[48:51], v[174:177], v[182:185], v[48:51]
	v_mfma_f32_16x16x32_bf16 v[32:35], v[174:177], v[190:193], v[32:35]
	v_mfma_f32_16x16x32_bf16 v[36:39], v[166:169], v[190:193], v[36:39]
	v_mfma_f32_16x16x32_bf16 v[20:23], v[166:169], v[198:201], v[20:23]
	v_mfma_f32_16x16x32_bf16 v[16:19], v[174:177], v[198:201], v[16:19]
	v_mfma_f32_16x16x32_bf16 v[0:3], v[174:177], v[206:209], v[0:3]
	v_mfma_f32_16x16x32_bf16 v[4:7], v[166:169], v[206:209], v[4:7]
	s_barrier
	s_setprio 0
	s_add_u32 s50, s50, 0x100
	s_addc_u32 s51, s51, 0
	s_add_u32 s31, s31, 0x100
	s_addc_u32 s38, s38, 0
	s_cmp_ge_i32 s43, s8
	s_mov_b32 s39, s43
	s_cbranch_scc0 .LBB0_256

; #define PG8_LDA(dst, b, h) do { if constexpr (FP8) { _Pragma("unroll") for (int m = 0; m < 4; ++m) dst##8[m] = PG8_LD8(PG8_SA(b, h), aoff, aoff1, m); } \
;         else { _Pragma("unroll") for (int m = 0; m < 4; ++m) _Pragma("unroll") for (int k = 0; k < 2; ++k) dst[m][k] = *(const LAS bf16x8*)(lds + PG8_SA(b, h) + (k ? aoff1 : aoff) + m * 2048); } } while (0)
; #define PG8_LDB(dst, b, h) do { if constexpr (FP8) { dst##8[0] = PG8_LD8(PG8_SB(b, h), boff, boff1, 0); dst##8[1] = PG8_LD8(PG8_SB(b, h), boff, boff1, 1); } \
;         else { _Pragma("unroll") for (int n = 0; n < 2; ++n) _Pragma("unroll") for (int k = 0; k < 2; ++k) dst[n][k] = *(const LAS bf16x8*)(lds + PG8_SB(b, h) + (k ? boff1 : boff) + n * 2048); } } while (0)
; #define PG8_WAIT_V(n) asm volatile("s_waitcnt vmcnt(" #n ")" ::: "memory")
; #define PG8_BAR __builtin_amdgcn_s_barrier()
; template <class Epi, class SchedT, bool ALIGN_EPI, bool SP2, bool FP8 = false>
; __device__ __forceinline__ void gemm_phase(LAS unsigned char* lds, const Gemm g, const SchedT& S, const Epi& E, const int wid) {
;     ...
;     f32x4 acc[2][2][4][2];
; #pragma unroll
;     for (int a = 0; a < 2; ++a)
; #pragma unroll
;         for (int b = 0; b < 2; ++b)
; #pragma unroll
;             for (int m = 0; m < 4; ++m)
; #pragma unroll
;                 for (int n = 0; n < 2; ++n) acc[a][b][m][n] = (f32x4){0.f, 0.f, 0.f, 0.f};
;     ...
;         const bool has_next = S.next(ui + 1, nxt);
;         const char* nA = has_next ? (const char*)g.A + (size_t)nxt.pm * tstepA + (size_t)nxt.aoff * 2 : cA; const char* nB = has_next ? (const char*)g.Bt + (size_t)nxt.pn * tstepB + (size_t)nxt.boff * 2 : cB;
;         const int nt = cur.nt;
;         for (int t = 0; t < nt; t += 2) {
;             const bool last = (t == nt - 2);
;             const char* a1 = cA + (size_t)(t + 1) * kstep;
;             const char* a2 = last ? nA : cA + (size_t)(t + 2) * kstep; const char* b2 = last ? nB : cB + (size_t)(t + 2) * kstep;
;             const char* a3 = a2 + kstep; const char* b3 = b2 + kstep;
;             if constexpr (SP2) {
;     ...
;             PG8_LDB(B0, 0, 0); PG8_LDB(B1, 0, 1); PG8_SCHED; PG8_LDA(At, 0, 0); PG8_S1;
;             PG8_WAIT_V(8); PG8_WAIT_L(0); PG8_BAR; PG8_MMAP(0, 0, 0); PG8_BAR; PG8_SCHED;
;             PG8_LDA(At, 0, 1); PG8_S2;
;             PG8_WAIT_V(8); PG8_WAIT_L(0); PG8_BAR; PG8_MMAP(1, 0, 1); PG8_BAR; PG8_SCHED;
.LBB0_538:
	s_add_i32 s20, s71, -2
	s_add_u32 s8, s66, 0x90080
	s_addc_u32 s9, s67, 0
	s_add_u32 s21, s10, 0x100
	s_addc_u32 s24, s11, 0
	s_mov_b32 s10, 0
	ds_read_b128 v[134:137], v215
	ds_read_b128 v[138:141], v215 offset:16
	ds_read_b128 v[142:145], v215 offset:2048
	ds_read_b128 v[146:149], v215 offset:2064
	ds_read_b128 v[150:153], v216
	ds_read_b128 v[154:157], v216 offset:16
	ds_read_b128 v[158:161], v216 offset:2048
	ds_read_b128 v[162:165], v216 offset:2064
	s_add_i32 s30, s10, 2
	s_add_u32 s16, s8, 0xfff70080
	s_addc_u32 s11, s9, -1
	s_cmp_eq_u32 s20, s10
	s_cselect_b32 s10, s52, s16
	s_cselect_b32 s11, s53, s11
	v_mov_b32_e32 v128, v210
	ds_read_b128 v[166:169], v217
	ds_read_b128 v[170:173], v217 offset:16
	ds_read_b128 v[174:177], v217 offset:2048
	ds_read_b128 v[178:181], v217 offset:2064
	ds_read_b128 v[182:185], v217 offset:4096
	ds_read_b128 v[186:189], v217 offset:4112
	ds_read_b128 v[190:193], v217 offset:6144
	ds_read_b128 v[194:197], v217 offset:6160
	s_cselect_b32 s67, s65, s24
	s_cselect_b32 s66, s64, s21
	s_add_i32 m0, s87, 0xc000
	s_nop 0
	global_load_lds_dwordx4 v128, s[8:9]
	v_mov_b32_e32 v128, v212
	s_add_i32 m0, s87, 0xe000
	s_nop 0
	global_load_lds_dwordx4 v128, s[8:9]
	s_waitcnt vmcnt(8)
	s_waitcnt lgkmcnt(0)
	s_setprio 1
	s_barrier
	v_mfma_scale_f32_16x16x128_f8f6f4 v[124:127], v[134:141], v[166:173], 0, v218, v218 op_sel_hi:[0,0,0]
	v_mfma_scale_f32_16x16x128_f8f6f4 v[120:123], v[142:149], v[166:173], 0, v218, v218 op_sel_hi:[0,0,0]
	v_mfma_scale_f32_16x16x128_f8f6f4 v[116:119], v[134:141], v[174:181], 0, v218, v218 op_sel_hi:[0,0,0]
	v_mfma_scale_f32_16x16x128_f8f6f4 v[112:115], v[142:149], v[174:181], 0, v218, v218 op_sel_hi:[0,0,0]
	v_mfma_scale_f32_16x16x128_f8f6f4 v[108:111], v[134:141], v[182:189], 0, v218, v218 op_sel_hi:[0,0,0]
	v_mfma_scale_f32_16x16x128_f8f6f4 v[104:107], v[142:149], v[182:189], 0, v218, v218 op_sel_hi:[0,0,0]
	v_mfma_scale_f32_16x16x128_f8f6f4 v[100:103], v[134:141], v[190:197], 0, v218, v218 op_sel_hi:[0,0,0]
	v_mfma_scale_f32_16x16x128_f8f6f4 v[96:99], v[142:149], v[190:197], 0, v218, v218 op_sel_hi:[0,0,0]
	s_setprio 0
	s_setprio 1
	v_mfma_scale_f32_16x16x128_f8f6f4 v[198:201], v[150:157], v[166:173], 0, v218, v218 op_sel_hi:[0,0,0]
	v_mfma_scale_f32_16x16x128_f8f6f4 v[166:169], v[158:165], v[166:173], 0, v218, v218 op_sel_hi:[0,0,0]
	v_mfma_scale_f32_16x16x128_f8f6f4 v[170:173], v[150:157], v[174:181], 0, v218, v218 op_sel_hi:[0,0,0]
	v_mfma_scale_f32_16x16x128_f8f6f4 v[174:177], v[158:165], v[174:181], 0, v218, v218 op_sel_hi:[0,0,0]
	v_mfma_scale_f32_16x16x128_f8f6f4 v[178:181], v[150:157], v[182:189], 0, v218, v218 op_sel_hi:[0,0,0]
	v_mfma_scale_f32_16x16x128_f8f6f4 v[182:185], v[158:165], v[182:189], 0, v218, v218 op_sel_hi:[0,0,0]
	v_mfma_scale_f32_16x16x128_f8f6f4 v[186:189], v[150:157], v[190:197], 0, v218, v218 op_sel_hi:[0,0,0]
	v_mfma_scale_f32_16x16x128_f8f6f4 v[190:193], v[158:165], v[190:197], 0, v218, v218 op_sel_hi:[0,0,0]
	s_barrier
	s_setprio 0
	v_mov_b32_e32 v128, v211
	s_add_i32 s16, s94, s86
	s_nop 2
	ds_read_b128 v[64:67], v217 offset:16384
	ds_read_b128 v[68:71], v217 offset:16400
	ds_read_b128 v[72:75], v217 offset:18432
	ds_read_b128 v[76:79], v217 offset:18448
	ds_read_b128 v[80:83], v217 offset:20480
	ds_read_b128 v[84:87], v217 offset:20496
	ds_read_b128 v[88:91], v217 offset:22528
	ds_read_b128 v[92:95], v217 offset:22544
	s_mov_b32 m0, s16
	s_nop 0
	global_load_lds_dwordx4 v128, s[66:67]
	v_mov_b32_e32 v128, v213
	s_add_i32 m0, s16, 0x2000
	s_add_u32 s60, s66, 0x88000
	global_load_lds_dwordx4 v128, s[66:67]
	s_addc_u32 s61, s67, 0
	v_mov_b32_e32 v128, v211
	s_add_i32 s16, s95, s86
	s_mov_b32 m0, s16
	s_nop 0
	global_load_lds_dwordx4 v128, s[60:61]
	v_mov_b32_e32 v128, v213
	s_add_i32 m0, s16, 0x2000
	s_nop 0
	global_load_lds_dwordx4 v128, s[60:61]
	v_mov_b32_e32 v128, v210
	s_mov_b32 m0, s87
	s_nop 0
	global_load_lds_dwordx4 v128, s[10:11]
	v_mov_b32_e32 v128, v212
	s_mov_b32 m0, s88
	s_nop 0
	global_load_lds_dwordx4 v128, s[10:11]
	s_waitcnt vmcnt(8)
	s_waitcnt lgkmcnt(0)
	s_setprio 1
	s_barrier
	v_mfma_scale_f32_16x16x128_f8f6f4 v[60:63], v[134:141], v[64:71], 0, v218, v218 op_sel_hi:[0,0,0]
	v_mfma_scale_f32_16x16x128_f8f6f4 v[56:59], v[142:149], v[64:71], 0, v218, v218 op_sel_hi:[0,0,0]
	v_mfma_scale_f32_16x16x128_f8f6f4 v[52:55], v[134:141], v[72:79], 0, v218, v218 op_sel_hi:[0,0,0]
	v_mfma_scale_f32_16x16x128_f8f6f4 v[48:51], v[142:149], v[72:79], 0, v218, v218 op_sel_hi:[0,0,0]
	v_mfma_scale_f32_16x16x128_f8f6f4 v[44:47], v[134:141], v[80:87], 0, v218, v218 op_sel_hi:[0,0,0]
	v_mfma_scale_f32_16x16x128_f8f6f4 v[40:43], v[142:149], v[80:87], 0, v218, v218 op_sel_hi:[0,0,0]
	v_mfma_scale_f32_16x16x128_f8f6f4 v[194:197], v[150:157], v[64:71], 0, v218, v218 op_sel_hi:[0,0,0]
	v_mfma_scale_f32_16x16x128_f8f6f4 v[202:205], v[158:165], v[64:71], 0, v218, v218 op_sel_hi:[0,0,0]
	s_setprio 0
	s_setprio 1
	v_mfma_scale_f32_16x16x128_f8f6f4 v[206:209], v[150:157], v[72:79], 0, v218, v218 op_sel_hi:[0,0,0]
	v_mfma_scale_f32_16x16x128_f8f6f4 v[220:223], v[158:165], v[72:79], 0, v218, v218 op_sel_hi:[0,0,0]
	v_mfma_scale_f32_16x16x128_f8f6f4 v[224:227], v[150:157], v[80:87], 0, v218, v218 op_sel_hi:[0,0,0]
	v_mfma_scale_f32_16x16x128_f8f6f4 v[228:231], v[158:165], v[80:87], 0, v218, v218 op_sel_hi:[0,0,0]
	v_mfma_scale_f32_16x16x128_f8f6f4 v[232:235], v[134:141], v[88:95], 0, v218, v218 op_sel_hi:[0,0,0]
	v_mfma_scale_f32_16x16x128_f8f6f4 v[236:239], v[150:157], v[88:95], 0, v218, v218 op_sel_hi:[0,0,0]
	v_mfma_scale_f32_16x16x128_f8f6f4 v[240:243], v[142:149], v[88:95], 0, v218, v218 op_sel_hi:[0,0,0]
	v_mfma_scale_f32_16x16x128_f8f6f4 v[244:247], v[158:165], v[88:95], 0, v218, v218 op_sel_hi:[0,0,0]
	s_barrier
; #define PG8_LDA(dst, b, h) do { if constexpr (FP8) { _Pragma("unroll") for (int m = 0; m < 4; ++m) dst##8[m] = PG8_LD8(PG8_SA(b, h), aoff, aoff1, m); } \
;         else { _Pragma("unroll") for (int m = 0; m < 4; ++m) _Pragma("unroll") for (int k = 0; k < 2; ++k) dst[m][k] = *(const LAS bf16x8*)(lds + PG8_SA(b, h) + (k ? aoff1 : aoff) + m * 2048); } } while (0)
; #define PG8_LDB(dst, b, h) do { if constexpr (FP8) { dst##8[0] = PG8_LD8(PG8_SB(b, h), boff, boff1, 0); dst##8[1] = PG8_LD8(PG8_SB(b, h), boff, boff1, 1); } \
;         else { _Pragma("unroll") for (int n = 0; n < 2; ++n) _Pragma("unroll") for (int k = 0; k < 2; ++k) dst[n][k] = *(const LAS bf16x8*)(lds + PG8_SB(b, h) + (k ? boff1 : boff) + n * 2048); } } while (0)
; #define PG8_WAIT_V(n) asm volatile("s_waitcnt vmcnt(" #n ")" ::: "memory")
; #define PG8_WAIT_L(n) asm volatile("s_waitcnt lgkmcnt(" #n ")" ::: "memory")
; #define PG8_BAR __builtin_amdgcn_s_barrier()
; #define PG8_SCHED __builtin_amdgcn_sched_barrier(0)
; #define PG8_S1 PG8_STAGE(PG8_SA(1, 1), a1 + hstepA, voffA)
; #define PG8_S3 PG8_STAGE(PG8_SA(0, 1), a2 + hstepA, voffA)
; template <class Epi, class SchedT, bool ALIGN_EPI, bool SP2, bool FP8 = false>
; __device__ __forceinline__ void gemm_phase(LAS unsigned char* lds, const Gemm g, const SchedT& S, const Epi& E, const int wid) {
;     ...
;         for (int t = 0; t < nt; t += 2) {
;             const bool last = (t == nt - 2);
;             const char* a1 = cA + (size_t)(t + 1) * kstep;
;             const char* a2 = last ? nA : cA + (size_t)(t + 2) * kstep; const char* b2 = last ? nB : cB + (size_t)(t + 2) * kstep;
;             const char* a3 = a2 + kstep; const char* b3 = b2 + kstep;
;             if constexpr (SP2) {
;     ...
;             PG8_LDB(B0, 0, 0); PG8_LDB(B1, 0, 1); PG8_SCHED; PG8_LDA(At, 0, 0); PG8_S1;
;             PG8_WAIT_V(8); PG8_WAIT_L(0); PG8_BAR; PG8_MMAP(0, 0, 0); PG8_BAR; PG8_SCHED;
;             PG8_LDA(At, 0, 1); PG8_S2;
;             PG8_WAIT_V(8); PG8_WAIT_L(0); PG8_BAR; PG8_MMAP(1, 0, 1); PG8_BAR; PG8_SCHED;
;             PG8_LDB(B0, 1, 0); PG8_LDB(B1, 1, 1); PG8_SCHED; PG8_LDA(At, 1, 0); PG8_S3;
;             PG8_WAIT_V(8); PG8_WAIT_L(0); PG8_BAR; PG8_MMAP(0, 1, 0); PG8_BAR; PG8_SCHED;
;             PG8_LDA(At, 1, 1); PG8_S4;
;             PG8_WAIT_V(8); PG8_WAIT_L(0); PG8_BAR; PG8_MMAP(1, 1, 1); PG8_BAR; PG8_SCHED;
	s_setprio 0
	s_add_i32 s16, 0, 0x18000
	v_add_u32_e32 v8, s16, v214
	s_add_i32 s17, 0, 0x1c000
	s_nop 1
	ds_read_b128 v[0:3], v8
	ds_read_b128 v[4:7], v8 offset:16
	ds_read_b128 v[134:137], v8 offset:2048
	ds_read_b128 v[138:141], v8 offset:2064
	v_add_u32_e32 v8, s17, v214
	ds_read_b128 v[142:145], v8
	ds_read_b128 v[146:149], v8 offset:16
	ds_read_b128 v[150:153], v8 offset:2048
	ds_read_b128 v[154:157], v8 offset:2064
	s_add_u32 s60, s10, 0x90000
	v_mov_b32_e32 v64, v210
	s_mov_b32 m0, s89
	ds_read_b128 v[8:11], v217 offset:32768
	ds_read_b128 v[12:15], v217 offset:32784
	ds_read_b128 v[16:19], v217 offset:34816
	ds_read_b128 v[20:23], v217 offset:34832
	ds_read_b128 v[24:27], v217 offset:36864
	ds_read_b128 v[28:31], v217 offset:36880
	ds_read_b128 v[32:35], v217 offset:38912
	ds_read_b128 v[36:39], v217 offset:38928
	s_addc_u32 s61, s11, 0
	s_nop 0
	global_load_lds_dwordx4 v64, s[60:61]
	v_mov_b32_e32 v64, v212
	s_mov_b32 m0, s90
	s_nop 0
	global_load_lds_dwordx4 v64, s[60:61]
	s_waitcnt vmcnt(8)
	s_waitcnt lgkmcnt(0)
	s_setprio 1
	s_barrier
	v_mfma_scale_f32_16x16x128_f8f6f4 v[124:127], v[0:7], v[8:15], v[124:127], v218, v218 op_sel_hi:[0,0,0]
	v_mfma_scale_f32_16x16x128_f8f6f4 v[92:95], v[142:149], v[8:15], v[198:201], v218, v218 op_sel_hi:[0,0,0]
	v_mfma_scale_f32_16x16x128_f8f6f4 v[120:123], v[134:141], v[8:15], v[120:123], v218, v218 op_sel_hi:[0,0,0]
	v_mfma_scale_f32_16x16x128_f8f6f4 v[88:91], v[150:157], v[8:15], v[166:169], v218, v218 op_sel_hi:[0,0,0]
	v_mfma_scale_f32_16x16x128_f8f6f4 v[116:119], v[0:7], v[16:23], v[116:119], v218, v218 op_sel_hi:[0,0,0]
	v_mfma_scale_f32_16x16x128_f8f6f4 v[84:87], v[142:149], v[16:23], v[170:173], v218, v218 op_sel_hi:[0,0,0]
	v_mfma_scale_f32_16x16x128_f8f6f4 v[112:115], v[134:141], v[16:23], v[112:115], v218, v218 op_sel_hi:[0,0,0]
	v_mfma_scale_f32_16x16x128_f8f6f4 v[80:83], v[150:157], v[16:23], v[174:177], v218, v218 op_sel_hi:[0,0,0]
	s_setprio 0
	s_setprio 1
	v_mfma_scale_f32_16x16x128_f8f6f4 v[108:111], v[0:7], v[24:31], v[108:111], v218, v218 op_sel_hi:[0,0,0]
	v_mfma_scale_f32_16x16x128_f8f6f4 v[76:79], v[142:149], v[24:31], v[178:181], v218, v218 op_sel_hi:[0,0,0]
	v_mfma_scale_f32_16x16x128_f8f6f4 v[104:107], v[134:141], v[24:31], v[104:107], v218, v218 op_sel_hi:[0,0,0]
	v_mfma_scale_f32_16x16x128_f8f6f4 v[72:75], v[150:157], v[24:31], v[182:185], v218, v218 op_sel_hi:[0,0,0]
	v_mfma_scale_f32_16x16x128_f8f6f4 v[100:103], v[0:7], v[32:39], v[100:103], v218, v218 op_sel_hi:[0,0,0]
	v_mfma_scale_f32_16x16x128_f8f6f4 v[68:71], v[142:149], v[32:39], v[186:189], v218, v218 op_sel_hi:[0,0,0]
	v_mfma_scale_f32_16x16x128_f8f6f4 v[96:99], v[134:141], v[32:39], v[96:99], v218, v218 op_sel_hi:[0,0,0]
	v_mfma_scale_f32_16x16x128_f8f6f4 v[64:67], v[150:157], v[32:39], v[190:193], v218, v218 op_sel_hi:[0,0,0]
	s_barrier
	s_setprio 0
	v_mov_b32_e32 v128, v211
	ds_read_b128 v[8:11], v217 offset:49152
	ds_read_b128 v[12:15], v217 offset:49168
	ds_read_b128 v[32:35], v217 offset:51200
	ds_read_b128 v[36:39], v217 offset:51216
	ds_read_b128 v[158:161], v217 offset:53248
	ds_read_b128 v[162:165], v217 offset:53264
	ds_read_b128 v[166:169], v217 offset:55296
	ds_read_b128 v[170:173], v217 offset:55312
	s_add_i32 s16, s16, s86
	v_lshl_add_u64 v[16:17], s[66:67], 0, v[128:129]
	v_lshl_add_u64 v[16:17], v[16:17], 0, s[44:45]
	s_mov_b32 m0, s16
	v_mov_b32_e32 v128, v213
	global_load_lds_dwordx4 v[16:17], off
	s_add_i32 m0, s16, 0x2000
	v_lshl_add_u64 v[16:17], s[66:67], 0, v[128:129]
	v_lshl_add_u64 v[16:17], v[16:17], 0, s[44:45]
	s_add_u32 s60, s66, 0x88080
	global_load_lds_dwordx4 v[16:17], off
	s_addc_u32 s61, s67, 0
	v_mov_b32_e32 v16, v211
	s_add_i32 s16, s17, s86
	s_mov_b32 m0, s16
	v_mov_b32_e32 v128, v210
	global_load_lds_dwordx4 v16, s[60:61]
	v_mov_b32_e32 v16, v213
	s_add_i32 m0, s16, 0x2000
	s_nop 0
	global_load_lds_dwordx4 v16, s[60:61]
	s_mov_b32 m0, s92
	v_lshl_add_u64 v[16:17], s[10:11], 0, v[128:129]
	v_lshl_add_u64 v[16:17], v[16:17], 0, s[44:45]
	v_mov_b32_e32 v128, v212
	global_load_lds_dwordx4 v[16:17], off
	s_mov_b32 m0, s93
	v_lshl_add_u64 v[16:17], s[10:11], 0, v[128:129]
	v_lshl_add_u64 v[16:17], v[16:17], 0, s[44:45]
	global_load_lds_dwordx4 v[16:17], off
	s_waitcnt vmcnt(8)
	s_waitcnt lgkmcnt(0)
	s_setprio 1
	s_barrier
	v_mfma_scale_f32_16x16x128_f8f6f4 v[60:63], v[0:7], v[8:15], v[60:63], v218, v218 op_sel_hi:[0,0,0]
	v_mfma_scale_f32_16x16x128_f8f6f4 v[28:31], v[142:149], v[8:15], v[194:197], v218, v218 op_sel_hi:[0,0,0]
	v_mfma_scale_f32_16x16x128_f8f6f4 v[56:59], v[134:141], v[8:15], v[56:59], v218, v218 op_sel_hi:[0,0,0]
	v_mfma_scale_f32_16x16x128_f8f6f4 v[24:27], v[150:157], v[8:15], v[202:205], v218, v218 op_sel_hi:[0,0,0]
	v_mfma_scale_f32_16x16x128_f8f6f4 v[52:55], v[0:7], v[32:39], v[52:55], v218, v218 op_sel_hi:[0,0,0]
	v_mfma_scale_f32_16x16x128_f8f6f4 v[20:23], v[142:149], v[32:39], v[206:209], v218, v218 op_sel_hi:[0,0,0]
	v_mfma_scale_f32_16x16x128_f8f6f4 v[48:51], v[134:141], v[32:39], v[48:51], v218, v218 op_sel_hi:[0,0,0]
	v_mfma_scale_f32_16x16x128_f8f6f4 v[16:19], v[150:157], v[32:39], v[220:223], v218, v218 op_sel_hi:[0,0,0]
	s_setprio 0
	s_setprio 1
	v_mfma_scale_f32_16x16x128_f8f6f4 v[44:47], v[0:7], v[158:165], v[44:47], v218, v218 op_sel_hi:[0,0,0]
	v_mfma_scale_f32_16x16x128_f8f6f4 v[12:15], v[142:149], v[158:165], v[224:227], v218, v218 op_sel_hi:[0,0,0]
	v_mfma_scale_f32_16x16x128_f8f6f4 v[40:43], v[134:141], v[158:165], v[40:43], v218, v218 op_sel_hi:[0,0,0]
	v_mfma_scale_f32_16x16x128_f8f6f4 v[8:11], v[150:157], v[158:165], v[228:231], v218, v218 op_sel_hi:[0,0,0]
	v_mfma_scale_f32_16x16x128_f8f6f4 v[36:39], v[0:7], v[166:173], v[232:235], v218, v218 op_sel_hi:[0,0,0]
	v_mfma_scale_f32_16x16x128_f8f6f4 v[4:7], v[142:149], v[166:173], v[236:239], v218, v218 op_sel_hi:[0,0,0]
	v_mfma_scale_f32_16x16x128_f8f6f4 v[32:35], v[134:141], v[166:173], v[240:243], v218, v218 op_sel_hi:[0,0,0]
	v_mfma_scale_f32_16x16x128_f8f6f4 v[0:3], v[150:157], v[166:173], v[244:247], v218, v218 op_sel_hi:[0,0,0]
	s_barrier
	s_setprio 0
	s_add_u32 s8, s8, 0x100
	s_addc_u32 s9, s9, 0
	s_add_u32 s21, s21, 0x100
	s_addc_u32 s24, s24, 0
	s_cmp_ge_i32 s30, s71
	s_mov_b32 s10, s30
	s_cbranch_scc1 .Lpeel_exit_lbb0_539
; #define PG8_LDA(dst, b, h) do { if constexpr (FP8) { _Pragma("unroll") for (int m = 0; m < 4; ++m) dst##8[m] = PG8_LD8(PG8_SA(b, h), aoff, aoff1, m); } \
;         else { _Pragma("unroll") for (int m = 0; m < 4; ++m) _Pragma("unroll") for (int k = 0; k < 2; ++k) dst[m][k] = *(const LAS bf16x8*)(lds + PG8_SA(b, h) + (k ? aoff1 : aoff) + m * 2048); } } while (0)
; #define PG8_LDB(dst, b, h) do { if constexpr (FP8) { dst##8[0] = PG8_LD8(PG8_SB(b, h), boff, boff1, 0); dst##8[1] = PG8_LD8(PG8_SB(b, h), boff, boff1, 1); } \
;         else { _Pragma("unroll") for (int n = 0; n < 2; ++n) _Pragma("unroll") for (int k = 0; k < 2; ++k) dst[n][k] = *(const LAS bf16x8*)(lds + PG8_SB(b, h) + (k ? boff1 : boff) + n * 2048); } } while (0)
; #define PG8_WAIT_V(n) asm volatile("s_waitcnt vmcnt(" #n ")" ::: "memory")
; #define PG8_WAIT_L(n) asm volatile("s_waitcnt lgkmcnt(" #n ")" ::: "memory")
; #define PG8_BAR __builtin_amdgcn_s_barrier()
; #define PG8_SCHED __builtin_amdgcn_sched_barrier(0)
; #define PG8_S1 PG8_STAGE(PG8_SA(1, 1), a1 + hstepA, voffA)
; #define PG8_S2 do { PG8_STAGE(PG8_SB(0, 0), b2, voffB); PG8_STAGE(PG8_SB(0, 1), b2 + hstepB, voffB); PG8_STAGE(PG8_SA(0, 0), a2, voffA); } while (0)
; template <class Epi, class SchedT, bool ALIGN_EPI, bool SP2, bool FP8 = false>
; __device__ __forceinline__ void gemm_phase(LAS unsigned char* lds, const Gemm g, const SchedT& S, const Epi& E, const int wid) {
;     ...
;         for (int t = 0; t < nt; t += 2) {
;             const bool last = (t == nt - 2);
;             const char* a1 = cA + (size_t)(t + 1) * kstep;
;             const char* a2 = last ? nA : cA + (size_t)(t + 2) * kstep; const char* b2 = last ? nB : cB + (size_t)(t + 2) * kstep;
;             const char* a3 = a2 + kstep; const char* b3 = b2 + kstep;
;             if constexpr (SP2) {
;     ...
;             PG8_LDB(B0, 0, 0); PG8_LDB(B1, 0, 1); PG8_SCHED; PG8_LDA(At, 0, 0); PG8_S1;
;             PG8_WAIT_V(8); PG8_WAIT_L(0); PG8_BAR; PG8_MMAP(0, 0, 0); PG8_BAR; PG8_SCHED;
;             PG8_LDA(At, 0, 1); PG8_S2;
;             PG8_WAIT_V(8); PG8_WAIT_L(0); PG8_BAR; PG8_MMAP(1, 0, 1); PG8_BAR; PG8_SCHED;
.LBB0_539:
	ds_read_b128 v[134:137], v215
	ds_read_b128 v[138:141], v215 offset:16
	ds_read_b128 v[142:145], v215 offset:2048
	ds_read_b128 v[146:149], v215 offset:2064
	ds_read_b128 v[150:153], v216
	ds_read_b128 v[154:157], v216 offset:16
	ds_read_b128 v[158:161], v216 offset:2048
	ds_read_b128 v[162:165], v216 offset:2064
	s_add_i32 s30, s10, 2
	s_add_u32 s16, s8, 0xfff70080
	s_addc_u32 s11, s9, -1
	s_cmp_eq_u32 s20, s10
	s_cselect_b32 s10, s52, s16
	s_cselect_b32 s11, s53, s11
	v_mov_b32_e32 v128, v210
	ds_read_b128 v[166:169], v217
	ds_read_b128 v[170:173], v217 offset:16
	ds_read_b128 v[174:177], v217 offset:2048
	ds_read_b128 v[178:181], v217 offset:2064
	ds_read_b128 v[182:185], v217 offset:4096
	ds_read_b128 v[186:189], v217 offset:4112
	ds_read_b128 v[190:193], v217 offset:6144
	ds_read_b128 v[194:197], v217 offset:6160
	s_cselect_b32 s67, s65, s24
	s_cselect_b32 s66, s64, s21
	s_add_i32 m0, s87, 0xc000
	s_nop 0
	global_load_lds_dwordx4 v128, s[8:9]
	v_mov_b32_e32 v128, v212
	s_add_i32 m0, s87, 0xe000
	s_nop 0
	global_load_lds_dwordx4 v128, s[8:9]
	s_waitcnt vmcnt(8)
	s_waitcnt lgkmcnt(0)
	s_setprio 1
	s_barrier
	v_mfma_scale_f32_16x16x128_f8f6f4 v[124:127], v[134:141], v[166:173], v[124:127], v218, v218 op_sel_hi:[0,0,0]
	v_mfma_scale_f32_16x16x128_f8f6f4 v[120:123], v[142:149], v[166:173], v[120:123], v218, v218 op_sel_hi:[0,0,0]
	v_mfma_scale_f32_16x16x128_f8f6f4 v[116:119], v[134:141], v[174:181], v[116:119], v218, v218 op_sel_hi:[0,0,0]
	v_mfma_scale_f32_16x16x128_f8f6f4 v[112:115], v[142:149], v[174:181], v[112:115], v218, v218 op_sel_hi:[0,0,0]
	v_mfma_scale_f32_16x16x128_f8f6f4 v[108:111], v[134:141], v[182:189], v[108:111], v218, v218 op_sel_hi:[0,0,0]
	v_mfma_scale_f32_16x16x128_f8f6f4 v[104:107], v[142:149], v[182:189], v[104:107], v218, v218 op_sel_hi:[0,0,0]
	v_mfma_scale_f32_16x16x128_f8f6f4 v[100:103], v[134:141], v[190:197], v[100:103], v218, v218 op_sel_hi:[0,0,0]
	v_mfma_scale_f32_16x16x128_f8f6f4 v[96:99], v[142:149], v[190:197], v[96:99], v218, v218 op_sel_hi:[0,0,0]
	s_setprio 0
	s_setprio 1
	v_mfma_scale_f32_16x16x128_f8f6f4 v[198:201], v[150:157], v[166:173], v[92:95], v218, v218 op_sel_hi:[0,0,0]
	v_mfma_scale_f32_16x16x128_f8f6f4 v[166:169], v[158:165], v[166:173], v[88:91], v218, v218 op_sel_hi:[0,0,0]
	v_mfma_scale_f32_16x16x128_f8f6f4 v[170:173], v[150:157], v[174:181], v[84:87], v218, v218 op_sel_hi:[0,0,0]
	v_mfma_scale_f32_16x16x128_f8f6f4 v[174:177], v[158:165], v[174:181], v[80:83], v218, v218 op_sel_hi:[0,0,0]
	v_mfma_scale_f32_16x16x128_f8f6f4 v[178:181], v[150:157], v[182:189], v[76:79], v218, v218 op_sel_hi:[0,0,0]
	v_mfma_scale_f32_16x16x128_f8f6f4 v[182:185], v[158:165], v[182:189], v[72:75], v218, v218 op_sel_hi:[0,0,0]
	v_mfma_scale_f32_16x16x128_f8f6f4 v[186:189], v[150:157], v[190:197], v[68:71], v218, v218 op_sel_hi:[0,0,0]
	v_mfma_scale_f32_16x16x128_f8f6f4 v[190:193], v[158:165], v[190:197], v[64:67], v218, v218 op_sel_hi:[0,0,0]
	s_barrier
	s_setprio 0
	v_mov_b32_e32 v128, v211
	s_add_i32 s16, s94, s86
	s_nop 2
	ds_read_b128 v[64:67], v217 offset:16384
	ds_read_b128 v[68:71], v217 offset:16400
	ds_read_b128 v[72:75], v217 offset:18432
	ds_read_b128 v[76:79], v217 offset:18448
	ds_read_b128 v[80:83], v217 offset:20480
	ds_read_b128 v[84:87], v217 offset:20496
	ds_read_b128 v[88:91], v217 offset:22528
	ds_read_b128 v[92:95], v217 offset:22544
	s_mov_b32 m0, s16
	s_nop 0
	global_load_lds_dwordx4 v128, s[66:67]
	v_mov_b32_e32 v128, v213
	s_add_i32 m0, s16, 0x2000
	s_add_u32 s60, s66, 0x88000
	global_load_lds_dwordx4 v128, s[66:67]
	s_addc_u32 s61, s67, 0
	v_mov_b32_e32 v128, v211
	s_add_i32 s16, s95, s86
	s_mov_b32 m0, s16
	s_nop 0
	global_load_lds_dwordx4 v128, s[60:61]
	v_mov_b32_e32 v128, v213
	s_add_i32 m0, s16, 0x2000
	s_nop 0
	global_load_lds_dwordx4 v128, s[60:61]
	v_mov_b32_e32 v128, v210
	s_mov_b32 m0, s87
	s_nop 0
	global_load_lds_dwordx4 v128, s[10:11]
	v_mov_b32_e32 v128, v212
	s_mov_b32 m0, s88
	s_nop 0
	global_load_lds_dwordx4 v128, s[10:11]
	s_waitcnt vmcnt(8)
	s_waitcnt lgkmcnt(0)
	s_setprio 1
	s_barrier
	v_mfma_scale_f32_16x16x128_f8f6f4 v[60:63], v[134:141], v[64:71], v[60:63], v218, v218 op_sel_hi:[0,0,0]
	v_mfma_scale_f32_16x16x128_f8f6f4 v[56:59], v[142:149], v[64:71], v[56:59], v218, v218 op_sel_hi:[0,0,0]
	v_mfma_scale_f32_16x16x128_f8f6f4 v[52:55], v[134:141], v[72:79], v[52:55], v218, v218 op_sel_hi:[0,0,0]
	v_mfma_scale_f32_16x16x128_f8f6f4 v[48:51], v[142:149], v[72:79], v[48:51], v218, v218 op_sel_hi:[0,0,0]
	v_mfma_scale_f32_16x16x128_f8f6f4 v[44:47], v[134:141], v[80:87], v[44:47], v218, v218 op_sel_hi:[0,0,0]
	v_mfma_scale_f32_16x16x128_f8f6f4 v[40:43], v[142:149], v[80:87], v[40:43], v218, v218 op_sel_hi:[0,0,0]
	v_mfma_scale_f32_16x16x128_f8f6f4 v[194:197], v[150:157], v[64:71], v[28:31], v218, v218 op_sel_hi:[0,0,0]
	v_mfma_scale_f32_16x16x128_f8f6f4 v[202:205], v[158:165], v[64:71], v[24:27], v218, v218 op_sel_hi:[0,0,0]
	s_setprio 0
	s_setprio 1
	v_mfma_scale_f32_16x16x128_f8f6f4 v[206:209], v[150:157], v[72:79], v[20:23], v218, v218 op_sel_hi:[0,0,0]
	v_mfma_scale_f32_16x16x128_f8f6f4 v[220:223], v[158:165], v[72:79], v[16:19], v218, v218 op_sel_hi:[0,0,0]
	v_mfma_scale_f32_16x16x128_f8f6f4 v[224:227], v[150:157], v[80:87], v[12:15], v218, v218 op_sel_hi:[0,0,0]
	v_mfma_scale_f32_16x16x128_f8f6f4 v[228:231], v[158:165], v[80:87], v[8:11], v218, v218 op_sel_hi:[0,0,0]
	v_mfma_scale_f32_16x16x128_f8f6f4 v[232:235], v[134:141], v[88:95], v[36:39], v218, v218 op_sel_hi:[0,0,0]
	v_mfma_scale_f32_16x16x128_f8f6f4 v[236:239], v[150:157], v[88:95], v[4:7], v218, v218 op_sel_hi:[0,0,0]
	v_mfma_scale_f32_16x16x128_f8f6f4 v[240:243], v[142:149], v[88:95], v[32:35], v218, v218 op_sel_hi:[0,0,0]
	v_mfma_scale_f32_16x16x128_f8f6f4 v[244:247], v[158:165], v[88:95], v[0:3], v218, v218 op_sel_hi:[0,0,0]
	s_barrier
; #define PG8_LDA(dst, b, h) do { if constexpr (FP8) { _Pragma("unroll") for (int m = 0; m < 4; ++m) dst##8[m] = PG8_LD8(PG8_SA(b, h), aoff, aoff1, m); } \
;         else { _Pragma("unroll") for (int m = 0; m < 4; ++m) _Pragma("unroll") for (int k = 0; k < 2; ++k) dst[m][k] = *(const LAS bf16x8*)(lds + PG8_SA(b, h) + (k ? aoff1 : aoff) + m * 2048); } } while (0)
; #define PG8_LDB(dst, b, h) do { if constexpr (FP8) { dst##8[0] = PG8_LD8(PG8_SB(b, h), boff, boff1, 0); dst##8[1] = PG8_LD8(PG8_SB(b, h), boff, boff1, 1); } \
;         else { _Pragma("unroll") for (int n = 0; n < 2; ++n) _Pragma("unroll") for (int k = 0; k < 2; ++k) dst[n][k] = *(const LAS bf16x8*)(lds + PG8_SB(b, h) + (k ? boff1 : boff) + n * 2048); } } while (0)
; #define PG8_WAIT_V(n) asm volatile("s_waitcnt vmcnt(" #n ")" ::: "memory")
; #define PG8_WAIT_L(n) asm volatile("s_waitcnt lgkmcnt(" #n ")" ::: "memory")
; #define PG8_BAR __builtin_amdgcn_s_barrier()
; #define PG8_SCHED __builtin_amdgcn_sched_barrier(0)
; #define PG8_S3 PG8_STAGE(PG8_SA(0, 1), a2 + hstepA, voffA)
; #define PG8_S4 do { PG8_STAGE(PG8_SB(1, 0), b3, voffB); PG8_STAGE(PG8_SB(1, 1), b3 + hstepB, voffB); PG8_STAGE(PG8_SA(1, 0), a3, voffA); } while (0)
; template <class Epi, class SchedT, bool ALIGN_EPI, bool SP2, bool FP8 = false>
; __device__ __forceinline__ void gemm_phase(LAS unsigned char* lds, const Gemm g, const SchedT& S, const Epi& E, const int wid) {
;     ...
;         for (int t = 0; t < nt; t += 2) {
;             const bool last = (t == nt - 2);
;             const char* a1 = cA + (size_t)(t + 1) * kstep;
;             const char* a2 = last ? nA : cA + (size_t)(t + 2) * kstep; const char* b2 = last ? nB : cB + (size_t)(t + 2) * kstep;
;             const char* a3 = a2 + kstep; const char* b3 = b2 + kstep;
;     ...
;             PG8_LDB(B0, 1, 0); PG8_LDB(B1, 1, 1); PG8_SCHED; PG8_LDA(At, 1, 0); PG8_S3;
;             PG8_WAIT_V(8); PG8_WAIT_L(0); PG8_BAR; PG8_MMAP(0, 1, 0); PG8_BAR; PG8_SCHED;
;             PG8_LDA(At, 1, 1); PG8_S4;
;             PG8_WAIT_V(8); PG8_WAIT_L(0); PG8_BAR; PG8_MMAP(1, 1, 1); PG8_BAR; PG8_SCHED;
	s_setprio 0
	s_add_i32 s16, 0, 0x18000
	v_add_u32_e32 v8, s16, v214
	s_add_i32 s17, 0, 0x1c000
	s_nop 1
	ds_read_b128 v[0:3], v8
	ds_read_b128 v[4:7], v8 offset:16
	ds_read_b128 v[134:137], v8 offset:2048
	ds_read_b128 v[138:141], v8 offset:2064
	v_add_u32_e32 v8, s17, v214
	ds_read_b128 v[142:145], v8
	ds_read_b128 v[146:149], v8 offset:16
	ds_read_b128 v[150:153], v8 offset:2048
	ds_read_b128 v[154:157], v8 offset:2064
	s_add_u32 s60, s10, 0x90000
	v_mov_b32_e32 v64, v210
	s_mov_b32 m0, s89
	ds_read_b128 v[8:11], v217 offset:32768
	ds_read_b128 v[12:15], v217 offset:32784
	ds_read_b128 v[16:19], v217 offset:34816
	ds_read_b128 v[20:23], v217 offset:34832
	ds_read_b128 v[24:27], v217 offset:36864
	ds_read_b128 v[28:31], v217 offset:36880
	ds_read_b128 v[32:35], v217 offset:38912
	ds_read_b128 v[36:39], v217 offset:38928
	s_addc_u32 s61, s11, 0
	s_nop 0
	global_load_lds_dwordx4 v64, s[60:61]
	v_mov_b32_e32 v64, v212
	s_mov_b32 m0, s90
	s_nop 0
	global_load_lds_dwordx4 v64, s[60:61]
	s_waitcnt vmcnt(8)
	s_waitcnt lgkmcnt(0)
	s_setprio 1
	s_barrier
	v_mfma_scale_f32_16x16x128_f8f6f4 v[124:127], v[0:7], v[8:15], v[124:127], v218, v218 op_sel_hi:[0,0,0]
	v_mfma_scale_f32_16x16x128_f8f6f4 v[92:95], v[142:149], v[8:15], v[198:201], v218, v218 op_sel_hi:[0,0,0]
	v_mfma_scale_f32_16x16x128_f8f6f4 v[120:123], v[134:141], v[8:15], v[120:123], v218, v218 op_sel_hi:[0,0,0]
	v_mfma_scale_f32_16x16x128_f8f6f4 v[88:91], v[150:157], v[8:15], v[166:169], v218, v218 op_sel_hi:[0,0,0]
	v_mfma_scale_f32_16x16x128_f8f6f4 v[116:119], v[0:7], v[16:23], v[116:119], v218, v218 op_sel_hi:[0,0,0]
	v_mfma_scale_f32_16x16x128_f8f6f4 v[84:87], v[142:149], v[16:23], v[170:173], v218, v218 op_sel_hi:[0,0,0]
	v_mfma_scale_f32_16x16x128_f8f6f4 v[112:115], v[134:141], v[16:23], v[112:115], v218, v218 op_sel_hi:[0,0,0]
	v_mfma_scale_f32_16x16x128_f8f6f4 v[80:83], v[150:157], v[16:23], v[174:177], v218, v218 op_sel_hi:[0,0,0]
	s_setprio 0
	s_setprio 1
	v_mfma_scale_f32_16x16x128_f8f6f4 v[108:111], v[0:7], v[24:31], v[108:111], v218, v218 op_sel_hi:[0,0,0]
	v_mfma_scale_f32_16x16x128_f8f6f4 v[76:79], v[142:149], v[24:31], v[178:181], v218, v218 op_sel_hi:[0,0,0]
	v_mfma_scale_f32_16x16x128_f8f6f4 v[104:107], v[134:141], v[24:31], v[104:107], v218, v218 op_sel_hi:[0,0,0]
	v_mfma_scale_f32_16x16x128_f8f6f4 v[72:75], v[150:157], v[24:31], v[182:185], v218, v218 op_sel_hi:[0,0,0]
	v_mfma_scale_f32_16x16x128_f8f6f4 v[100:103], v[0:7], v[32:39], v[100:103], v218, v218 op_sel_hi:[0,0,0]
	v_mfma_scale_f32_16x16x128_f8f6f4 v[68:71], v[142:149], v[32:39], v[186:189], v218, v218 op_sel_hi:[0,0,0]
	v_mfma_scale_f32_16x16x128_f8f6f4 v[96:99], v[134:141], v[32:39], v[96:99], v218, v218 op_sel_hi:[0,0,0]
	v_mfma_scale_f32_16x16x128_f8f6f4 v[64:67], v[150:157], v[32:39], v[190:193], v218, v218 op_sel_hi:[0,0,0]
	s_barrier
	s_setprio 0
	v_mov_b32_e32 v128, v211
	ds_read_b128 v[8:11], v217 offset:49152
	ds_read_b128 v[12:15], v217 offset:49168
	ds_read_b128 v[32:35], v217 offset:51200
	ds_read_b128 v[36:39], v217 offset:51216
	ds_read_b128 v[158:161], v217 offset:53248
	ds_read_b128 v[162:165], v217 offset:53264
	ds_read_b128 v[166:169], v217 offset:55296
	ds_read_b128 v[170:173], v217 offset:55312
	s_add_i32 s16, s16, s86
	v_lshl_add_u64 v[16:17], s[66:67], 0, v[128:129]
	v_lshl_add_u64 v[16:17], v[16:17], 0, s[44:45]
	s_mov_b32 m0, s16
	v_mov_b32_e32 v128, v213
	global_load_lds_dwordx4 v[16:17], off
	s_add_i32 m0, s16, 0x2000
	v_lshl_add_u64 v[16:17], s[66:67], 0, v[128:129]
	v_lshl_add_u64 v[16:17], v[16:17], 0, s[44:45]
	s_add_u32 s60, s66, 0x88080
	global_load_lds_dwordx4 v[16:17], off
	s_addc_u32 s61, s67, 0
	v_mov_b32_e32 v16, v211
	s_add_i32 s16, s17, s86
	s_mov_b32 m0, s16
	v_mov_b32_e32 v128, v210
	global_load_lds_dwordx4 v16, s[60:61]
	v_mov_b32_e32 v16, v213
	s_add_i32 m0, s16, 0x2000
	s_nop 0
	global_load_lds_dwordx4 v16, s[60:61]
	s_mov_b32 m0, s92
	v_lshl_add_u64 v[16:17], s[10:11], 0, v[128:129]
	v_lshl_add_u64 v[16:17], v[16:17], 0, s[44:45]
	v_mov_b32_e32 v128, v212
	global_load_lds_dwordx4 v[16:17], off
	s_mov_b32 m0, s93
	v_lshl_add_u64 v[16:17], s[10:11], 0, v[128:129]
	v_lshl_add_u64 v[16:17], v[16:17], 0, s[44:45]
	global_load_lds_dwordx4 v[16:17], off
	s_waitcnt vmcnt(8)
	s_waitcnt lgkmcnt(0)
	s_setprio 1
	s_barrier
	v_mfma_scale_f32_16x16x128_f8f6f4 v[60:63], v[0:7], v[8:15], v[60:63], v218, v218 op_sel_hi:[0,0,0]
	v_mfma_scale_f32_16x16x128_f8f6f4 v[28:31], v[142:149], v[8:15], v[194:197], v218, v218 op_sel_hi:[0,0,0]
	v_mfma_scale_f32_16x16x128_f8f6f4 v[56:59], v[134:141], v[8:15], v[56:59], v218, v218 op_sel_hi:[0,0,0]
	v_mfma_scale_f32_16x16x128_f8f6f4 v[24:27], v[150:157], v[8:15], v[202:205], v218, v218 op_sel_hi:[0,0,0]
	v_mfma_scale_f32_16x16x128_f8f6f4 v[52:55], v[0:7], v[32:39], v[52:55], v218, v218 op_sel_hi:[0,0,0]
	v_mfma_scale_f32_16x16x128_f8f6f4 v[20:23], v[142:149], v[32:39], v[206:209], v218, v218 op_sel_hi:[0,0,0]
	v_mfma_scale_f32_16x16x128_f8f6f4 v[48:51], v[134:141], v[32:39], v[48:51], v218, v218 op_sel_hi:[0,0,0]
	v_mfma_scale_f32_16x16x128_f8f6f4 v[16:19], v[150:157], v[32:39], v[220:223], v218, v218 op_sel_hi:[0,0,0]
	s_setprio 0
	s_setprio 1
	v_mfma_scale_f32_16x16x128_f8f6f4 v[44:47], v[0:7], v[158:165], v[44:47], v218, v218 op_sel_hi:[0,0,0]
	v_mfma_scale_f32_16x16x128_f8f6f4 v[12:15], v[142:149], v[158:165], v[224:227], v218, v218 op_sel_hi:[0,0,0]
	v_mfma_scale_f32_16x16x128_f8f6f4 v[40:43], v[134:141], v[158:165], v[40:43], v218, v218 op_sel_hi:[0,0,0]
	v_mfma_scale_f32_16x16x128_f8f6f4 v[8:11], v[150:157], v[158:165], v[228:231], v218, v218 op_sel_hi:[0,0,0]
	v_mfma_scale_f32_16x16x128_f8f6f4 v[36:39], v[0:7], v[166:173], v[232:235], v218, v218 op_sel_hi:[0,0,0]
	v_mfma_scale_f32_16x16x128_f8f6f4 v[4:7], v[142:149], v[166:173], v[236:239], v218, v218 op_sel_hi:[0,0,0]
	v_mfma_scale_f32_16x16x128_f8f6f4 v[32:35], v[134:141], v[166:173], v[240:243], v218, v218 op_sel_hi:[0,0,0]
	v_mfma_scale_f32_16x16x128_f8f6f4 v[0:3], v[150:157], v[166:173], v[244:247], v218, v218 op_sel_hi:[0,0,0]
	s_barrier
	s_setprio 0
	s_add_u32 s8, s8, 0x100
	s_addc_u32 s9, s9, 0
	s_add_u32 s21, s21, 0x100
	s_addc_u32 s24, s24, 0
	s_cmp_ge_i32 s30, s71
	s_mov_b32 s10, s30
	s_cbranch_scc0 .LBB0_539

; #define PG8_LDA(dst, b, h) do { if constexpr (FP8) { _Pragma("unroll") for (int m = 0; m < 4; ++m) dst##8[m] = PG8_LD8(PG8_SA(b, h), aoff, aoff1, m); } \
;         else { _Pragma("unroll") for (int m = 0; m < 4; ++m) _Pragma("unroll") for (int k = 0; k < 2; ++k) dst[m][k] = *(const LAS bf16x8*)(lds + PG8_SA(b, h) + (k ? aoff1 : aoff) + m * 2048); } } while (0)
; #define PG8_LDB(dst, b, h) do { if constexpr (FP8) { dst##8[0] = PG8_LD8(PG8_SB(b, h), boff, boff1, 0); dst##8[1] = PG8_LD8(PG8_SB(b, h), boff, boff1, 1); } \
;         else { _Pragma("unroll") for (int n = 0; n < 2; ++n) _Pragma("unroll") for (int k = 0; k < 2; ++k) dst[n][k] = *(const LAS bf16x8*)(lds + PG8_SB(b, h) + (k ? boff1 : boff) + n * 2048); } } while (0)
; #define PG8_WAIT_V(n) asm volatile("s_waitcnt vmcnt(" #n ")" ::: "memory")
; #define PG8_WAIT_L(n) asm volatile("s_waitcnt lgkmcnt(" #n ")" ::: "memory")
; #define PG8_BAR __builtin_amdgcn_s_barrier()
; #define PG8_SCHED __builtin_amdgcn_sched_barrier(0)
; #define PG8_S1 PG8_STAGE(PG8_SA(1, 1), a1 + hstepA, voffA)
; template <class Epi, class SchedT, bool ALIGN_EPI, bool SP2, bool FP8 = false>
; __device__ __forceinline__ void gemm_phase(LAS unsigned char* lds, const Gemm g, const SchedT& S, const Epi& E, const int wid) {
;     ...
;     for (;;) {
;         const bool has_next = S.next(ui + 1, nxt);
;         const char* nA = has_next ? (const char*)g.A + (size_t)nxt.pm * tstepA + (size_t)nxt.aoff * 2 : cA; const char* nB = has_next ? (const char*)g.Bt + (size_t)nxt.pn * tstepB + (size_t)nxt.boff * 2 : cB;
;         const int nt = cur.nt;
;         for (int t = 0; t < nt; t += 2) {
;             const bool last = (t == nt - 2);
;             const char* a1 = cA + (size_t)(t + 1) * kstep;
;             const char* a2 = last ? nA : cA + (size_t)(t + 2) * kstep; const char* b2 = last ? nB : cB + (size_t)(t + 2) * kstep;
;             const char* a3 = a2 + kstep; const char* b3 = b2 + kstep;
;             if constexpr (SP2) {
;     ...
;             PG8_LDB(B0, 0, 0); PG8_LDB(B1, 0, 1); PG8_SCHED; PG8_LDA(At, 0, 0); PG8_S1;
;             PG8_WAIT_V(8); PG8_WAIT_L(0); PG8_BAR; PG8_MMAP(0, 0, 0); PG8_BAR; PG8_SCHED;
;             PG8_LDA(At, 0, 1); PG8_S2;
;             PG8_WAIT_V(8); PG8_WAIT_L(0); PG8_BAR; PG8_MMAP(1, 0, 1); PG8_BAR; PG8_SCHED;
.LBB0_777:
	s_ashr_i32 s47, s46, 31
	s_lshl_b64 s[22:23], s[46:47], 18
	s_add_u32 s48, s36, s22
	s_addc_u32 s49, s37, s23
	s_ashr_i32 s45, s44, 31
	s_lshl_b64 s[22:23], s[44:45], 18
	s_add_u32 s50, s12, s22
	s_addc_u32 s51, s13, s23
	s_cmp_lt_i32 s20, 1
	s_cbranch_scc1 .LBB0_833
	s_and_b64 s[22:23], s[6:7], exec
	s_cselect_b32 s9, s49, s53
	s_cselect_b32 s21, s48, s52
	s_cselect_b32 s22, s51, s65
	s_cselect_b32 s23, s50, s64
	s_add_i32 s24, s20, -2
	s_add_u32 s52, s52, 0x20080
	s_addc_u32 s53, s53, 0
	s_add_u32 s30, s64, 0x100
	s_addc_u32 s31, s65, 0
	s_mov_b32 s47, 0
	s_waitcnt lgkmcnt(0)
	ds_read_b128 v[134:137], v149
	ds_read_b128 v[138:141], v149 offset:16
	ds_read_b128 v[154:157], v149 offset:2048
	ds_read_b128 v[158:161], v149 offset:2064
	ds_read_b128 v[162:165], v150
	ds_read_b128 v[166:169], v150 offset:16
	ds_read_b128 v[170:173], v150 offset:2048
	ds_read_b128 v[174:177], v150 offset:2064
	s_add_i32 s45, s47, 2
	s_add_u32 s16, s52, 0xfffe0080
	s_addc_u32 s17, s53, -1
	s_cmp_eq_u32 s24, s47
	s_cselect_b32 s65, s9, s17
	s_cselect_b32 s64, s21, s16
	v_mov_b32_e32 v128, v146
	ds_read_b128 v[178:181], v151
	ds_read_b128 v[182:185], v151 offset:16
	ds_read_b128 v[186:189], v151 offset:2048
	ds_read_b128 v[190:193], v151 offset:2064
	ds_read_b128 v[194:197], v151 offset:4096
	ds_read_b128 v[198:201], v151 offset:4112
	ds_read_b128 v[202:205], v151 offset:6144
	ds_read_b128 v[206:209], v151 offset:6160
	s_cselect_b32 s67, s22, s31
	s_cselect_b32 s66, s23, s30
	s_add_i32 m0, s87, 0xc000
	s_nop 0
	global_load_lds_dwordx4 v128, s[52:53]
	v_mov_b32_e32 v128, v147
	s_add_i32 m0, s87, 0xe000
	s_nop 0
	global_load_lds_dwordx4 v128, s[52:53]
	s_waitcnt vmcnt(8)
	s_waitcnt lgkmcnt(0)
	s_setprio 1
	s_barrier
	v_mfma_scale_f32_16x16x128_f8f6f4 v[124:127], v[134:141], v[178:185], 0, v152, v152 op_sel_hi:[0,0,0]
	v_mfma_scale_f32_16x16x128_f8f6f4 v[108:111], v[162:169], v[178:185], 0, v152, v152 op_sel_hi:[0,0,0]
	v_mfma_scale_f32_16x16x128_f8f6f4 v[120:123], v[154:161], v[178:185], 0, v152, v152 op_sel_hi:[0,0,0]
	v_mfma_scale_f32_16x16x128_f8f6f4 v[100:103], v[170:177], v[178:185], 0, v152, v152 op_sel_hi:[0,0,0]
	v_mfma_scale_f32_16x16x128_f8f6f4 v[116:119], v[134:141], v[186:193], 0, v152, v152 op_sel_hi:[0,0,0]
	v_mfma_scale_f32_16x16x128_f8f6f4 v[112:115], v[154:161], v[186:193], 0, v152, v152 op_sel_hi:[0,0,0]
	v_mfma_scale_f32_16x16x128_f8f6f4 v[104:107], v[134:141], v[194:201], 0, v152, v152 op_sel_hi:[0,0,0]
	v_mfma_scale_f32_16x16x128_f8f6f4 v[60:63], v[170:177], v[202:209], 0, v152, v152 op_sel_hi:[0,0,0]
	s_setprio 0
	s_setprio 1
	v_mfma_scale_f32_16x16x128_f8f6f4 v[142:145], v[162:169], v[186:193], 0, v152, v152 op_sel_hi:[0,0,0]
	v_mfma_scale_f32_16x16x128_f8f6f4 v[178:181], v[170:177], v[186:193], 0, v152, v152 op_sel_hi:[0,0,0]
	v_mfma_scale_f32_16x16x128_f8f6f4 v[182:185], v[162:169], v[194:201], 0, v152, v152 op_sel_hi:[0,0,0]
	v_mfma_scale_f32_16x16x128_f8f6f4 v[186:189], v[154:161], v[194:201], 0, v152, v152 op_sel_hi:[0,0,0]
	v_mfma_scale_f32_16x16x128_f8f6f4 v[190:193], v[170:177], v[194:201], 0, v152, v152 op_sel_hi:[0,0,0]
	v_mfma_scale_f32_16x16x128_f8f6f4 v[194:197], v[134:141], v[202:209], 0, v152, v152 op_sel_hi:[0,0,0]
	v_mfma_scale_f32_16x16x128_f8f6f4 v[198:201], v[162:169], v[202:209], 0, v152, v152 op_sel_hi:[0,0,0]
	v_mfma_scale_f32_16x16x128_f8f6f4 v[210:213], v[154:161], v[202:209], 0, v152, v152 op_sel_hi:[0,0,0]
	s_barrier
	s_setprio 0
	v_mov_b32_e32 v128, v146
	s_add_i32 s16, s94, s86
	s_nop 1
	ds_read_b128 v[68:71], v151 offset:16384
	ds_read_b128 v[72:75], v151 offset:16400
	ds_read_b128 v[76:79], v151 offset:18432
	ds_read_b128 v[80:83], v151 offset:18448
	ds_read_b128 v[84:87], v151 offset:20480
	ds_read_b128 v[88:91], v151 offset:20496
	ds_read_b128 v[92:95], v151 offset:22528
	ds_read_b128 v[96:99], v151 offset:22544
	s_mov_b32 m0, s16
	s_nop 0
	global_load_lds_dwordx4 v128, s[66:67]
	v_mov_b32_e32 v128, v147
	s_add_i32 m0, s16, 0x2000
	s_add_u32 s60, s66, 0x20000
	global_load_lds_dwordx4 v128, s[66:67]
	s_addc_u32 s61, s67, 0
	v_mov_b32_e32 v128, v146
	s_add_i32 s16, s95, s86
	s_mov_b32 m0, s16
	s_nop 0
	global_load_lds_dwordx4 v128, s[60:61]
	v_mov_b32_e32 v128, v147
	s_add_i32 m0, s16, 0x2000
	s_nop 0
	global_load_lds_dwordx4 v128, s[60:61]
	v_mov_b32_e32 v128, v146
	s_mov_b32 m0, s87
	s_nop 0
	global_load_lds_dwordx4 v128, s[64:65]
	v_mov_b32_e32 v128, v147
	s_mov_b32 m0, s88
	s_nop 0
	global_load_lds_dwordx4 v128, s[64:65]
	s_waitcnt vmcnt(8)
	s_waitcnt lgkmcnt(0)
	s_setprio 1
	s_barrier
	v_mfma_scale_f32_16x16x128_f8f6f4 v[64:67], v[134:141], v[68:75], 0, v152, v152 op_sel_hi:[0,0,0]
	v_mfma_scale_f32_16x16x128_f8f6f4 v[44:47], v[162:169], v[68:75], 0, v152, v152 op_sel_hi:[0,0,0]
	v_mfma_scale_f32_16x16x128_f8f6f4 v[56:59], v[154:161], v[68:75], 0, v152, v152 op_sel_hi:[0,0,0]
	v_mfma_scale_f32_16x16x128_f8f6f4 v[52:55], v[134:141], v[76:83], 0, v152, v152 op_sel_hi:[0,0,0]
	v_mfma_scale_f32_16x16x128_f8f6f4 v[48:51], v[154:161], v[76:83], 0, v152, v152 op_sel_hi:[0,0,0]
	v_mfma_scale_f32_16x16x128_f8f6f4 v[40:43], v[134:141], v[84:91], 0, v152, v152 op_sel_hi:[0,0,0]
	v_mfma_scale_f32_16x16x128_f8f6f4 v[202:205], v[170:177], v[68:75], 0, v152, v152 op_sel_hi:[0,0,0]
	v_mfma_scale_f32_16x16x128_f8f6f4 v[206:209], v[162:169], v[76:83], 0, v152, v152 op_sel_hi:[0,0,0]
	s_setprio 0
	s_setprio 1
	v_mfma_scale_f32_16x16x128_f8f6f4 v[214:217], v[170:177], v[76:83], 0, v152, v152 op_sel_hi:[0,0,0]
	v_mfma_scale_f32_16x16x128_f8f6f4 v[218:221], v[162:169], v[84:91], 0, v152, v152 op_sel_hi:[0,0,0]
	v_mfma_scale_f32_16x16x128_f8f6f4 v[222:225], v[154:161], v[84:91], 0, v152, v152 op_sel_hi:[0,0,0]
	v_mfma_scale_f32_16x16x128_f8f6f4 v[226:229], v[170:177], v[84:91], 0, v152, v152 op_sel_hi:[0,0,0]
	v_mfma_scale_f32_16x16x128_f8f6f4 v[230:233], v[134:141], v[92:99], 0, v152, v152 op_sel_hi:[0,0,0]
	v_mfma_scale_f32_16x16x128_f8f6f4 v[234:237], v[162:169], v[92:99], 0, v152, v152 op_sel_hi:[0,0,0]
	v_mfma_scale_f32_16x16x128_f8f6f4 v[238:241], v[154:161], v[92:99], 0, v152, v152 op_sel_hi:[0,0,0]
	v_mfma_scale_f32_16x16x128_f8f6f4 v[242:245], v[170:177], v[92:99], 0, v152, v152 op_sel_hi:[0,0,0]
	s_barrier
; #define PG8_LDA(dst, b, h) do { if constexpr (FP8) { _Pragma("unroll") for (int m = 0; m < 4; ++m) dst##8[m] = PG8_LD8(PG8_SA(b, h), aoff, aoff1, m); } \
;         else { _Pragma("unroll") for (int m = 0; m < 4; ++m) _Pragma("unroll") for (int k = 0; k < 2; ++k) dst[m][k] = *(const LAS bf16x8*)(lds + PG8_SA(b, h) + (k ? aoff1 : aoff) + m * 2048); } } while (0)
; #define PG8_LDB(dst, b, h) do { if constexpr (FP8) { dst##8[0] = PG8_LD8(PG8_SB(b, h), boff, boff1, 0); dst##8[1] = PG8_LD8(PG8_SB(b, h), boff, boff1, 1); } \
;         else { _Pragma("unroll") for (int n = 0; n < 2; ++n) _Pragma("unroll") for (int k = 0; k < 2; ++k) dst[n][k] = *(const LAS bf16x8*)(lds + PG8_SB(b, h) + (k ? boff1 : boff) + n * 2048); } } while (0)
; #define PG8_WAIT_V(n) asm volatile("s_waitcnt vmcnt(" #n ")" ::: "memory")
; #define PG8_WAIT_L(n) asm volatile("s_waitcnt lgkmcnt(" #n ")" ::: "memory")
; #define PG8_BAR __builtin_amdgcn_s_barrier()
; #define PG8_SCHED __builtin_amdgcn_sched_barrier(0)
; #define PG8_S3 PG8_STAGE(PG8_SA(0, 1), a2 + hstepA, voffA)
; #define PG8_S4 do { PG8_STAGE(PG8_SB(1, 0), b3, voffB); PG8_STAGE(PG8_SB(1, 1), b3 + hstepB, voffB); PG8_STAGE(PG8_SA(1, 0), a3, voffA); } while (0)
; template <class Epi, class SchedT, bool ALIGN_EPI, bool SP2, bool FP8 = false>
; __device__ __forceinline__ void gemm_phase(LAS unsigned char* lds, const Gemm g, const SchedT& S, const Epi& E, const int wid) {
;     ...
;         for (int t = 0; t < nt; t += 2) {
;             const bool last = (t == nt - 2);
;             const char* a1 = cA + (size_t)(t + 1) * kstep;
;             const char* a2 = last ? nA : cA + (size_t)(t + 2) * kstep; const char* b2 = last ? nB : cB + (size_t)(t + 2) * kstep;
;             const char* a3 = a2 + kstep; const char* b3 = b2 + kstep;
;     ...
;             PG8_LDB(B0, 1, 0); PG8_LDB(B1, 1, 1); PG8_SCHED; PG8_LDA(At, 1, 0); PG8_S3;
;             PG8_WAIT_V(8); PG8_WAIT_L(0); PG8_BAR; PG8_MMAP(0, 1, 0); PG8_BAR; PG8_SCHED;
;             PG8_LDA(At, 1, 1); PG8_S4;
;             PG8_WAIT_V(8); PG8_WAIT_L(0); PG8_BAR; PG8_MMAP(1, 1, 1); PG8_BAR; PG8_SCHED;
	s_setprio 0
	s_add_i32 s16, 0, 0x18000
	v_add_u32_e32 v8, s16, v148
	s_add_i32 s17, 0, 0x1c000
	s_nop 1
	ds_read_b128 v[0:3], v8
	ds_read_b128 v[4:7], v8 offset:16
	ds_read_b128 v[134:137], v8 offset:2048
	ds_read_b128 v[138:141], v8 offset:2064
	v_add_u32_e32 v8, s17, v148
	ds_read_b128 v[154:157], v8
	ds_read_b128 v[158:161], v8 offset:16
	ds_read_b128 v[162:165], v8 offset:2048
	ds_read_b128 v[166:169], v8 offset:2064
	s_add_u32 s60, s64, 0x20000
	v_mov_b32_e32 v68, v146
	s_mov_b32 m0, s89
	ds_read_b128 v[8:11], v151 offset:32768
	ds_read_b128 v[12:15], v151 offset:32784
	ds_read_b128 v[16:19], v151 offset:34816
	ds_read_b128 v[20:23], v151 offset:34832
	ds_read_b128 v[24:27], v151 offset:36864
	ds_read_b128 v[28:31], v151 offset:36880
	ds_read_b128 v[32:35], v151 offset:38912
	ds_read_b128 v[36:39], v151 offset:38928
	s_addc_u32 s61, s65, 0
	s_nop 0
	global_load_lds_dwordx4 v68, s[60:61]
	v_mov_b32_e32 v68, v147
	s_mov_b32 m0, s90
	s_nop 0
	global_load_lds_dwordx4 v68, s[60:61]
	s_waitcnt vmcnt(8)
	s_waitcnt lgkmcnt(0)
	s_setprio 1
	s_barrier
	v_mfma_scale_f32_16x16x128_f8f6f4 v[124:127], v[0:7], v[8:15], v[124:127], v152, v152 op_sel_hi:[0,0,0]
	v_mfma_scale_f32_16x16x128_f8f6f4 v[108:111], v[154:161], v[8:15], v[108:111], v152, v152 op_sel_hi:[0,0,0]
	v_mfma_scale_f32_16x16x128_f8f6f4 v[120:123], v[134:141], v[8:15], v[120:123], v152, v152 op_sel_hi:[0,0,0]
	v_mfma_scale_f32_16x16x128_f8f6f4 v[100:103], v[162:169], v[8:15], v[100:103], v152, v152 op_sel_hi:[0,0,0]
	v_mfma_scale_f32_16x16x128_f8f6f4 v[116:119], v[0:7], v[16:23], v[116:119], v152, v152 op_sel_hi:[0,0,0]
	v_mfma_scale_f32_16x16x128_f8f6f4 v[92:95], v[154:161], v[16:23], v[142:145], v152, v152 op_sel_hi:[0,0,0]
	v_mfma_scale_f32_16x16x128_f8f6f4 v[112:115], v[134:141], v[16:23], v[112:115], v152, v152 op_sel_hi:[0,0,0]
	v_mfma_scale_f32_16x16x128_f8f6f4 v[84:87], v[162:169], v[16:23], v[178:181], v152, v152 op_sel_hi:[0,0,0]
	s_setprio 0
	s_setprio 1
	v_mfma_scale_f32_16x16x128_f8f6f4 v[104:107], v[0:7], v[24:31], v[104:107], v152, v152 op_sel_hi:[0,0,0]
	v_mfma_scale_f32_16x16x128_f8f6f4 v[76:79], v[154:161], v[24:31], v[182:185], v152, v152 op_sel_hi:[0,0,0]
	v_mfma_scale_f32_16x16x128_f8f6f4 v[96:99], v[134:141], v[24:31], v[186:189], v152, v152 op_sel_hi:[0,0,0]
	v_mfma_scale_f32_16x16x128_f8f6f4 v[72:75], v[162:169], v[24:31], v[190:193], v152, v152 op_sel_hi:[0,0,0]
	v_mfma_scale_f32_16x16x128_f8f6f4 v[88:91], v[0:7], v[32:39], v[194:197], v152, v152 op_sel_hi:[0,0,0]
	v_mfma_scale_f32_16x16x128_f8f6f4 v[68:71], v[154:161], v[32:39], v[198:201], v152, v152 op_sel_hi:[0,0,0]
	v_mfma_scale_f32_16x16x128_f8f6f4 v[80:83], v[134:141], v[32:39], v[210:213], v152, v152 op_sel_hi:[0,0,0]
	v_mfma_scale_f32_16x16x128_f8f6f4 v[60:63], v[162:169], v[32:39], v[60:63], v152, v152 op_sel_hi:[0,0,0]
	s_barrier
	s_setprio 0
	v_mov_b32_e32 v128, v146
	ds_read_b128 v[8:11], v151 offset:49152
	ds_read_b128 v[12:15], v151 offset:49168
	ds_read_b128 v[16:19], v151 offset:51200
	ds_read_b128 v[20:23], v151 offset:51216
	ds_read_b128 v[170:173], v151 offset:53248
	ds_read_b128 v[174:177], v151 offset:53264
	ds_read_b128 v[178:181], v151 offset:55296
	ds_read_b128 v[182:185], v151 offset:55312
	s_add_i32 s16, s16, s86
	v_lshl_add_u64 v[24:25], s[66:67], 0, v[128:129]
	v_lshl_add_u64 v[24:25], v[24:25], 0, s[26:27]
	s_mov_b32 m0, s16
	v_mov_b32_e32 v128, v147
	global_load_lds_dwordx4 v[24:25], off
	s_add_i32 m0, s16, 0x2000
	v_lshl_add_u64 v[24:25], s[66:67], 0, v[128:129]
	v_lshl_add_u64 v[24:25], v[24:25], 0, s[26:27]
	s_add_u32 s60, s66, 0x20080
	global_load_lds_dwordx4 v[24:25], off
	s_addc_u32 s61, s67, 0
	v_mov_b32_e32 v24, v146
	s_add_i32 s16, s17, s86
	s_mov_b32 m0, s16
	v_mov_b32_e32 v128, v146
	global_load_lds_dwordx4 v24, s[60:61]
	v_mov_b32_e32 v24, v147
	s_add_i32 m0, s16, 0x2000
	s_nop 0
	global_load_lds_dwordx4 v24, s[60:61]
	s_mov_b32 m0, s92
	v_lshl_add_u64 v[24:25], s[64:65], 0, v[128:129]
	v_lshl_add_u64 v[24:25], v[24:25], 0, s[26:27]
	v_mov_b32_e32 v128, v147
	global_load_lds_dwordx4 v[24:25], off
	s_mov_b32 m0, s93
	v_lshl_add_u64 v[24:25], s[64:65], 0, v[128:129]
	v_lshl_add_u64 v[24:25], v[24:25], 0, s[26:27]
	global_load_lds_dwordx4 v[24:25], off
	s_waitcnt vmcnt(8)
	s_waitcnt lgkmcnt(0)
	s_setprio 1
	s_barrier
	v_mfma_scale_f32_16x16x128_f8f6f4 v[64:67], v[0:7], v[8:15], v[64:67], v152, v152 op_sel_hi:[0,0,0]
	v_mfma_scale_f32_16x16x128_f8f6f4 v[44:47], v[154:161], v[8:15], v[44:47], v152, v152 op_sel_hi:[0,0,0]
	v_mfma_scale_f32_16x16x128_f8f6f4 v[56:59], v[134:141], v[8:15], v[56:59], v152, v152 op_sel_hi:[0,0,0]
	v_mfma_scale_f32_16x16x128_f8f6f4 v[36:39], v[162:169], v[8:15], v[202:205], v152, v152 op_sel_hi:[0,0,0]
	v_mfma_scale_f32_16x16x128_f8f6f4 v[52:55], v[0:7], v[16:23], v[52:55], v152, v152 op_sel_hi:[0,0,0]
	v_mfma_scale_f32_16x16x128_f8f6f4 v[28:31], v[154:161], v[16:23], v[206:209], v152, v152 op_sel_hi:[0,0,0]
	v_mfma_scale_f32_16x16x128_f8f6f4 v[48:51], v[134:141], v[16:23], v[48:51], v152, v152 op_sel_hi:[0,0,0]
	v_mfma_scale_f32_16x16x128_f8f6f4 v[20:23], v[162:169], v[16:23], v[214:217], v152, v152 op_sel_hi:[0,0,0]
	s_setprio 0
	s_setprio 1
	v_mfma_scale_f32_16x16x128_f8f6f4 v[40:43], v[0:7], v[170:177], v[40:43], v152, v152 op_sel_hi:[0,0,0]
	v_mfma_scale_f32_16x16x128_f8f6f4 v[12:15], v[154:161], v[170:177], v[218:221], v152, v152 op_sel_hi:[0,0,0]
	v_mfma_scale_f32_16x16x128_f8f6f4 v[32:35], v[134:141], v[170:177], v[222:225], v152, v152 op_sel_hi:[0,0,0]
	v_mfma_scale_f32_16x16x128_f8f6f4 v[8:11], v[162:169], v[170:177], v[226:229], v152, v152 op_sel_hi:[0,0,0]
	v_mfma_scale_f32_16x16x128_f8f6f4 v[24:27], v[0:7], v[178:185], v[230:233], v152, v152 op_sel_hi:[0,0,0]
	v_mfma_scale_f32_16x16x128_f8f6f4 v[4:7], v[154:161], v[178:185], v[234:237], v152, v152 op_sel_hi:[0,0,0]
	v_mfma_scale_f32_16x16x128_f8f6f4 v[16:19], v[134:141], v[178:185], v[238:241], v152, v152 op_sel_hi:[0,0,0]
	v_mfma_scale_f32_16x16x128_f8f6f4 v[0:3], v[162:169], v[178:185], v[242:245], v152, v152 op_sel_hi:[0,0,0]
	s_barrier
	s_setprio 0
	s_add_u32 s52, s52, 0x100
	s_addc_u32 s53, s53, 0
	s_add_u32 s30, s30, 0x100
	s_addc_u32 s31, s31, 0
	s_cmp_ge_i32 s45, s20
	s_mov_b32 s47, s45
	s_cbranch_scc1 .Lpeel_exit_lbb0_779
; #define PG8_LDA(dst, b, h) do { if constexpr (FP8) { _Pragma("unroll") for (int m = 0; m < 4; ++m) dst##8[m] = PG8_LD8(PG8_SA(b, h), aoff, aoff1, m); } \
;         else { _Pragma("unroll") for (int m = 0; m < 4; ++m) _Pragma("unroll") for (int k = 0; k < 2; ++k) dst[m][k] = *(const LAS bf16x8*)(lds + PG8_SA(b, h) + (k ? aoff1 : aoff) + m * 2048); } } while (0)
; #define PG8_LDB(dst, b, h) do { if constexpr (FP8) { dst##8[0] = PG8_LD8(PG8_SB(b, h), boff, boff1, 0); dst##8[1] = PG8_LD8(PG8_SB(b, h), boff, boff1, 1); } \
;         else { _Pragma("unroll") for (int n = 0; n < 2; ++n) _Pragma("unroll") for (int k = 0; k < 2; ++k) dst[n][k] = *(const LAS bf16x8*)(lds + PG8_SB(b, h) + (k ? boff1 : boff) + n * 2048); } } while (0)
; #define PG8_WAIT_V(n) asm volatile("s_waitcnt vmcnt(" #n ")" ::: "memory")
; #define PG8_WAIT_L(n) asm volatile("s_waitcnt lgkmcnt(" #n ")" ::: "memory")
; #define PG8_BAR __builtin_amdgcn_s_barrier()
; #define PG8_SCHED __builtin_amdgcn_sched_barrier(0)
; #define PG8_S1 PG8_STAGE(PG8_SA(1, 1), a1 + hstepA, voffA)
; #define PG8_S2 do { PG8_STAGE(PG8_SB(0, 0), b2, voffB); PG8_STAGE(PG8_SB(0, 1), b2 + hstepB, voffB); PG8_STAGE(PG8_SA(0, 0), a2, voffA); } while (0)
; template <class Epi, class SchedT, bool ALIGN_EPI, bool SP2, bool FP8 = false>
; __device__ __forceinline__ void gemm_phase(LAS unsigned char* lds, const Gemm g, const SchedT& S, const Epi& E, const int wid) {
;     ...
;         for (int t = 0; t < nt; t += 2) {
;             const bool last = (t == nt - 2);
;             const char* a1 = cA + (size_t)(t + 1) * kstep;
;             const char* a2 = last ? nA : cA + (size_t)(t + 2) * kstep; const char* b2 = last ? nB : cB + (size_t)(t + 2) * kstep;
;             const char* a3 = a2 + kstep; const char* b3 = b2 + kstep;
;             if constexpr (SP2) {
;     ...
;             PG8_LDB(B0, 0, 0); PG8_LDB(B1, 0, 1); PG8_SCHED; PG8_LDA(At, 0, 0); PG8_S1;
;             PG8_WAIT_V(8); PG8_WAIT_L(0); PG8_BAR; PG8_MMAP(0, 0, 0); PG8_BAR; PG8_SCHED;
;             PG8_LDA(At, 0, 1); PG8_S2;
;             PG8_WAIT_V(8); PG8_WAIT_L(0); PG8_BAR; PG8_MMAP(1, 0, 1); PG8_BAR; PG8_SCHED;
.LBB0_779:
	ds_read_b128 v[134:137], v149
	ds_read_b128 v[138:141], v149 offset:16
	ds_read_b128 v[154:157], v149 offset:2048
	ds_read_b128 v[158:161], v149 offset:2064
	ds_read_b128 v[162:165], v150
	ds_read_b128 v[166:169], v150 offset:16
	ds_read_b128 v[170:173], v150 offset:2048
	ds_read_b128 v[174:177], v150 offset:2064
	s_add_i32 s45, s47, 2
	s_add_u32 s16, s52, 0xfffe0080
	s_addc_u32 s17, s53, -1
	s_cmp_eq_u32 s24, s47
	s_cselect_b32 s65, s9, s17
	s_cselect_b32 s64, s21, s16
	v_mov_b32_e32 v128, v146
	ds_read_b128 v[178:181], v151
	ds_read_b128 v[182:185], v151 offset:16
	ds_read_b128 v[186:189], v151 offset:2048
	ds_read_b128 v[190:193], v151 offset:2064
	ds_read_b128 v[194:197], v151 offset:4096
	ds_read_b128 v[198:201], v151 offset:4112
	ds_read_b128 v[202:205], v151 offset:6144
	ds_read_b128 v[206:209], v151 offset:6160
	s_cselect_b32 s67, s22, s31
	s_cselect_b32 s66, s23, s30
	s_add_i32 m0, s87, 0xc000
	s_nop 0
	global_load_lds_dwordx4 v128, s[52:53]
	v_mov_b32_e32 v128, v147
	s_add_i32 m0, s87, 0xe000
	s_nop 0
	global_load_lds_dwordx4 v128, s[52:53]
	s_waitcnt vmcnt(8)
	s_waitcnt lgkmcnt(0)
	s_setprio 1
	s_barrier
	v_mfma_scale_f32_16x16x128_f8f6f4 v[124:127], v[134:141], v[178:185], v[124:127], v152, v152 op_sel_hi:[0,0,0]
	v_mfma_scale_f32_16x16x128_f8f6f4 v[108:111], v[162:169], v[178:185], v[108:111], v152, v152 op_sel_hi:[0,0,0]
	v_mfma_scale_f32_16x16x128_f8f6f4 v[120:123], v[154:161], v[178:185], v[120:123], v152, v152 op_sel_hi:[0,0,0]
	v_mfma_scale_f32_16x16x128_f8f6f4 v[100:103], v[170:177], v[178:185], v[100:103], v152, v152 op_sel_hi:[0,0,0]
	v_mfma_scale_f32_16x16x128_f8f6f4 v[116:119], v[134:141], v[186:193], v[116:119], v152, v152 op_sel_hi:[0,0,0]
	v_mfma_scale_f32_16x16x128_f8f6f4 v[112:115], v[154:161], v[186:193], v[112:115], v152, v152 op_sel_hi:[0,0,0]
	v_mfma_scale_f32_16x16x128_f8f6f4 v[104:107], v[134:141], v[194:201], v[104:107], v152, v152 op_sel_hi:[0,0,0]
	v_mfma_scale_f32_16x16x128_f8f6f4 v[60:63], v[170:177], v[202:209], v[60:63], v152, v152 op_sel_hi:[0,0,0]
	s_setprio 0
	s_setprio 1
	v_mfma_scale_f32_16x16x128_f8f6f4 v[142:145], v[162:169], v[186:193], v[92:95], v152, v152 op_sel_hi:[0,0,0]
	v_mfma_scale_f32_16x16x128_f8f6f4 v[178:181], v[170:177], v[186:193], v[84:87], v152, v152 op_sel_hi:[0,0,0]
	v_mfma_scale_f32_16x16x128_f8f6f4 v[182:185], v[162:169], v[194:201], v[76:79], v152, v152 op_sel_hi:[0,0,0]
	v_mfma_scale_f32_16x16x128_f8f6f4 v[186:189], v[154:161], v[194:201], v[96:99], v152, v152 op_sel_hi:[0,0,0]
	v_mfma_scale_f32_16x16x128_f8f6f4 v[190:193], v[170:177], v[194:201], v[72:75], v152, v152 op_sel_hi:[0,0,0]
	v_mfma_scale_f32_16x16x128_f8f6f4 v[194:197], v[134:141], v[202:209], v[88:91], v152, v152 op_sel_hi:[0,0,0]
	v_mfma_scale_f32_16x16x128_f8f6f4 v[198:201], v[162:169], v[202:209], v[68:71], v152, v152 op_sel_hi:[0,0,0]
	v_mfma_scale_f32_16x16x128_f8f6f4 v[210:213], v[154:161], v[202:209], v[80:83], v152, v152 op_sel_hi:[0,0,0]
	s_barrier
	s_setprio 0
	v_mov_b32_e32 v128, v146
	s_add_i32 s16, s94, s86
	s_nop 1
	ds_read_b128 v[68:71], v151 offset:16384
	ds_read_b128 v[72:75], v151 offset:16400
	ds_read_b128 v[76:79], v151 offset:18432
	ds_read_b128 v[80:83], v151 offset:18448
	ds_read_b128 v[84:87], v151 offset:20480
	ds_read_b128 v[88:91], v151 offset:20496
	ds_read_b128 v[92:95], v151 offset:22528
	ds_read_b128 v[96:99], v151 offset:22544
	s_mov_b32 m0, s16
	s_nop 0
	global_load_lds_dwordx4 v128, s[66:67]
	v_mov_b32_e32 v128, v147
	s_add_i32 m0, s16, 0x2000
	s_add_u32 s60, s66, 0x20000
	global_load_lds_dwordx4 v128, s[66:67]
	s_addc_u32 s61, s67, 0
	v_mov_b32_e32 v128, v146
	s_add_i32 s16, s95, s86
	s_mov_b32 m0, s16
	s_nop 0
	global_load_lds_dwordx4 v128, s[60:61]
	v_mov_b32_e32 v128, v147
	s_add_i32 m0, s16, 0x2000
	s_nop 0
	global_load_lds_dwordx4 v128, s[60:61]
	v_mov_b32_e32 v128, v146
	s_mov_b32 m0, s87
	s_nop 0
	global_load_lds_dwordx4 v128, s[64:65]
	v_mov_b32_e32 v128, v147
	s_mov_b32 m0, s88
	s_nop 0
	global_load_lds_dwordx4 v128, s[64:65]
	s_waitcnt vmcnt(8)
	s_waitcnt lgkmcnt(0)
	s_setprio 1
	s_barrier
	v_mfma_scale_f32_16x16x128_f8f6f4 v[64:67], v[134:141], v[68:75], v[64:67], v152, v152 op_sel_hi:[0,0,0]
	v_mfma_scale_f32_16x16x128_f8f6f4 v[44:47], v[162:169], v[68:75], v[44:47], v152, v152 op_sel_hi:[0,0,0]
	v_mfma_scale_f32_16x16x128_f8f6f4 v[56:59], v[154:161], v[68:75], v[56:59], v152, v152 op_sel_hi:[0,0,0]
	v_mfma_scale_f32_16x16x128_f8f6f4 v[52:55], v[134:141], v[76:83], v[52:55], v152, v152 op_sel_hi:[0,0,0]
	v_mfma_scale_f32_16x16x128_f8f6f4 v[48:51], v[154:161], v[76:83], v[48:51], v152, v152 op_sel_hi:[0,0,0]
	v_mfma_scale_f32_16x16x128_f8f6f4 v[40:43], v[134:141], v[84:91], v[40:43], v152, v152 op_sel_hi:[0,0,0]
	v_mfma_scale_f32_16x16x128_f8f6f4 v[202:205], v[170:177], v[68:75], v[36:39], v152, v152 op_sel_hi:[0,0,0]
	v_mfma_scale_f32_16x16x128_f8f6f4 v[206:209], v[162:169], v[76:83], v[28:31], v152, v152 op_sel_hi:[0,0,0]
	s_setprio 0
	s_setprio 1
	v_mfma_scale_f32_16x16x128_f8f6f4 v[214:217], v[170:177], v[76:83], v[20:23], v152, v152 op_sel_hi:[0,0,0]
	v_mfma_scale_f32_16x16x128_f8f6f4 v[218:221], v[162:169], v[84:91], v[12:15], v152, v152 op_sel_hi:[0,0,0]
	v_mfma_scale_f32_16x16x128_f8f6f4 v[222:225], v[154:161], v[84:91], v[32:35], v152, v152 op_sel_hi:[0,0,0]
	v_mfma_scale_f32_16x16x128_f8f6f4 v[226:229], v[170:177], v[84:91], v[8:11], v152, v152 op_sel_hi:[0,0,0]
	v_mfma_scale_f32_16x16x128_f8f6f4 v[230:233], v[134:141], v[92:99], v[24:27], v152, v152 op_sel_hi:[0,0,0]
	v_mfma_scale_f32_16x16x128_f8f6f4 v[234:237], v[162:169], v[92:99], v[4:7], v152, v152 op_sel_hi:[0,0,0]
	v_mfma_scale_f32_16x16x128_f8f6f4 v[238:241], v[154:161], v[92:99], v[16:19], v152, v152 op_sel_hi:[0,0,0]
	v_mfma_scale_f32_16x16x128_f8f6f4 v[242:245], v[170:177], v[92:99], v[0:3], v152, v152 op_sel_hi:[0,0,0]
	s_barrier
; #define PG8_LDA(dst, b, h) do { if constexpr (FP8) { _Pragma("unroll") for (int m = 0; m < 4; ++m) dst##8[m] = PG8_LD8(PG8_SA(b, h), aoff, aoff1, m); } \
;         else { _Pragma("unroll") for (int m = 0; m < 4; ++m) _Pragma("unroll") for (int k = 0; k < 2; ++k) dst[m][k] = *(const LAS bf16x8*)(lds + PG8_SA(b, h) + (k ? aoff1 : aoff) + m * 2048); } } while (0)
; #define PG8_LDB(dst, b, h) do { if constexpr (FP8) { dst##8[0] = PG8_LD8(PG8_SB(b, h), boff, boff1, 0); dst##8[1] = PG8_LD8(PG8_SB(b, h), boff, boff1, 1); } \
;         else { _Pragma("unroll") for (int n = 0; n < 2; ++n) _Pragma("unroll") for (int k = 0; k < 2; ++k) dst[n][k] = *(const LAS bf16x8*)(lds + PG8_SB(b, h) + (k ? boff1 : boff) + n * 2048); } } while (0)
; #define PG8_WAIT_V(n) asm volatile("s_waitcnt vmcnt(" #n ")" ::: "memory")
; #define PG8_WAIT_L(n) asm volatile("s_waitcnt lgkmcnt(" #n ")" ::: "memory")
; #define PG8_BAR __builtin_amdgcn_s_barrier()
; #define PG8_SCHED __builtin_amdgcn_sched_barrier(0)
; #define PG8_S3 PG8_STAGE(PG8_SA(0, 1), a2 + hstepA, voffA)
; #define PG8_S4 do { PG8_STAGE(PG8_SB(1, 0), b3, voffB); PG8_STAGE(PG8_SB(1, 1), b3 + hstepB, voffB); PG8_STAGE(PG8_SA(1, 0), a3, voffA); } while (0)
; template <class Epi, class SchedT, bool ALIGN_EPI, bool SP2, bool FP8 = false>
; __device__ __forceinline__ void gemm_phase(LAS unsigned char* lds, const Gemm g, const SchedT& S, const Epi& E, const int wid) {
;     ...
;         for (int t = 0; t < nt; t += 2) {
;             const bool last = (t == nt - 2);
;             const char* a1 = cA + (size_t)(t + 1) * kstep;
;             const char* a2 = last ? nA : cA + (size_t)(t + 2) * kstep; const char* b2 = last ? nB : cB + (size_t)(t + 2) * kstep;
;             const char* a3 = a2 + kstep; const char* b3 = b2 + kstep;
;     ...
;             PG8_LDB(B0, 1, 0); PG8_LDB(B1, 1, 1); PG8_SCHED; PG8_LDA(At, 1, 0); PG8_S3;
;             PG8_WAIT_V(8); PG8_WAIT_L(0); PG8_BAR; PG8_MMAP(0, 1, 0); PG8_BAR; PG8_SCHED;
;             PG8_LDA(At, 1, 1); PG8_S4;
;             PG8_WAIT_V(8); PG8_WAIT_L(0); PG8_BAR; PG8_MMAP(1, 1, 1); PG8_BAR; PG8_SCHED;
	s_setprio 0
	s_add_i32 s16, 0, 0x18000
	v_add_u32_e32 v8, s16, v148
	s_add_i32 s17, 0, 0x1c000
	s_nop 1
	ds_read_b128 v[0:3], v8
	ds_read_b128 v[4:7], v8 offset:16
	ds_read_b128 v[134:137], v8 offset:2048
	ds_read_b128 v[138:141], v8 offset:2064
	v_add_u32_e32 v8, s17, v148
	ds_read_b128 v[154:157], v8
	ds_read_b128 v[158:161], v8 offset:16
	ds_read_b128 v[162:165], v8 offset:2048
	ds_read_b128 v[166:169], v8 offset:2064
	s_add_u32 s60, s64, 0x20000
	v_mov_b32_e32 v68, v146
	s_mov_b32 m0, s89
	ds_read_b128 v[8:11], v151 offset:32768
	ds_read_b128 v[12:15], v151 offset:32784
	ds_read_b128 v[16:19], v151 offset:34816
	ds_read_b128 v[20:23], v151 offset:34832
	ds_read_b128 v[24:27], v151 offset:36864
	ds_read_b128 v[28:31], v151 offset:36880
	ds_read_b128 v[32:35], v151 offset:38912
	ds_read_b128 v[36:39], v151 offset:38928
	s_addc_u32 s61, s65, 0
	s_nop 0
	global_load_lds_dwordx4 v68, s[60:61]
	v_mov_b32_e32 v68, v147
	s_mov_b32 m0, s90
	s_nop 0
	global_load_lds_dwordx4 v68, s[60:61]
	s_waitcnt vmcnt(8)
	s_waitcnt lgkmcnt(0)
	s_setprio 1
	s_barrier
	v_mfma_scale_f32_16x16x128_f8f6f4 v[124:127], v[0:7], v[8:15], v[124:127], v152, v152 op_sel_hi:[0,0,0]
	v_mfma_scale_f32_16x16x128_f8f6f4 v[108:111], v[154:161], v[8:15], v[108:111], v152, v152 op_sel_hi:[0,0,0]
	v_mfma_scale_f32_16x16x128_f8f6f4 v[120:123], v[134:141], v[8:15], v[120:123], v152, v152 op_sel_hi:[0,0,0]
	v_mfma_scale_f32_16x16x128_f8f6f4 v[100:103], v[162:169], v[8:15], v[100:103], v152, v152 op_sel_hi:[0,0,0]
	v_mfma_scale_f32_16x16x128_f8f6f4 v[116:119], v[0:7], v[16:23], v[116:119], v152, v152 op_sel_hi:[0,0,0]
	v_mfma_scale_f32_16x16x128_f8f6f4 v[92:95], v[154:161], v[16:23], v[142:145], v152, v152 op_sel_hi:[0,0,0]
	v_mfma_scale_f32_16x16x128_f8f6f4 v[112:115], v[134:141], v[16:23], v[112:115], v152, v152 op_sel_hi:[0,0,0]
	v_mfma_scale_f32_16x16x128_f8f6f4 v[84:87], v[162:169], v[16:23], v[178:181], v152, v152 op_sel_hi:[0,0,0]
	s_setprio 0
	s_setprio 1
	v_mfma_scale_f32_16x16x128_f8f6f4 v[104:107], v[0:7], v[24:31], v[104:107], v152, v152 op_sel_hi:[0,0,0]
	v_mfma_scale_f32_16x16x128_f8f6f4 v[76:79], v[154:161], v[24:31], v[182:185], v152, v152 op_sel_hi:[0,0,0]
	v_mfma_scale_f32_16x16x128_f8f6f4 v[96:99], v[134:141], v[24:31], v[186:189], v152, v152 op_sel_hi:[0,0,0]
	v_mfma_scale_f32_16x16x128_f8f6f4 v[72:75], v[162:169], v[24:31], v[190:193], v152, v152 op_sel_hi:[0,0,0]
	v_mfma_scale_f32_16x16x128_f8f6f4 v[88:91], v[0:7], v[32:39], v[194:197], v152, v152 op_sel_hi:[0,0,0]
	v_mfma_scale_f32_16x16x128_f8f6f4 v[68:71], v[154:161], v[32:39], v[198:201], v152, v152 op_sel_hi:[0,0,0]
	v_mfma_scale_f32_16x16x128_f8f6f4 v[80:83], v[134:141], v[32:39], v[210:213], v152, v152 op_sel_hi:[0,0,0]
	v_mfma_scale_f32_16x16x128_f8f6f4 v[60:63], v[162:169], v[32:39], v[60:63], v152, v152 op_sel_hi:[0,0,0]
	s_barrier
	s_setprio 0
	v_mov_b32_e32 v128, v146
	ds_read_b128 v[8:11], v151 offset:49152
	ds_read_b128 v[12:15], v151 offset:49168
	ds_read_b128 v[16:19], v151 offset:51200
	ds_read_b128 v[20:23], v151 offset:51216
	ds_read_b128 v[170:173], v151 offset:53248
	ds_read_b128 v[174:177], v151 offset:53264
	ds_read_b128 v[178:181], v151 offset:55296
	ds_read_b128 v[182:185], v151 offset:55312
	s_add_i32 s16, s16, s86
	v_lshl_add_u64 v[24:25], s[66:67], 0, v[128:129]
	v_lshl_add_u64 v[24:25], v[24:25], 0, s[26:27]
	s_mov_b32 m0, s16
	v_mov_b32_e32 v128, v147
	global_load_lds_dwordx4 v[24:25], off
	s_add_i32 m0, s16, 0x2000
	v_lshl_add_u64 v[24:25], s[66:67], 0, v[128:129]
	v_lshl_add_u64 v[24:25], v[24:25], 0, s[26:27]
	s_add_u32 s60, s66, 0x20080
	global_load_lds_dwordx4 v[24:25], off
	s_addc_u32 s61, s67, 0
	v_mov_b32_e32 v24, v146
	s_add_i32 s16, s17, s86
	s_mov_b32 m0, s16
	v_mov_b32_e32 v128, v146
	global_load_lds_dwordx4 v24, s[60:61]
	v_mov_b32_e32 v24, v147
	s_add_i32 m0, s16, 0x2000
	s_nop 0
	global_load_lds_dwordx4 v24, s[60:61]
	s_mov_b32 m0, s92
	v_lshl_add_u64 v[24:25], s[64:65], 0, v[128:129]
	v_lshl_add_u64 v[24:25], v[24:25], 0, s[26:27]
	v_mov_b32_e32 v128, v147
	global_load_lds_dwordx4 v[24:25], off
	s_mov_b32 m0, s93
	v_lshl_add_u64 v[24:25], s[64:65], 0, v[128:129]
	v_lshl_add_u64 v[24:25], v[24:25], 0, s[26:27]
	global_load_lds_dwordx4 v[24:25], off
	s_waitcnt vmcnt(8)
	s_waitcnt lgkmcnt(0)
	s_setprio 1
	s_barrier
	v_mfma_scale_f32_16x16x128_f8f6f4 v[64:67], v[0:7], v[8:15], v[64:67], v152, v152 op_sel_hi:[0,0,0]
	v_mfma_scale_f32_16x16x128_f8f6f4 v[44:47], v[154:161], v[8:15], v[44:47], v152, v152 op_sel_hi:[0,0,0]
	v_mfma_scale_f32_16x16x128_f8f6f4 v[56:59], v[134:141], v[8:15], v[56:59], v152, v152 op_sel_hi:[0,0,0]
	v_mfma_scale_f32_16x16x128_f8f6f4 v[36:39], v[162:169], v[8:15], v[202:205], v152, v152 op_sel_hi:[0,0,0]
	v_mfma_scale_f32_16x16x128_f8f6f4 v[52:55], v[0:7], v[16:23], v[52:55], v152, v152 op_sel_hi:[0,0,0]
	v_mfma_scale_f32_16x16x128_f8f6f4 v[28:31], v[154:161], v[16:23], v[206:209], v152, v152 op_sel_hi:[0,0,0]
	v_mfma_scale_f32_16x16x128_f8f6f4 v[48:51], v[134:141], v[16:23], v[48:51], v152, v152 op_sel_hi:[0,0,0]
	v_mfma_scale_f32_16x16x128_f8f6f4 v[20:23], v[162:169], v[16:23], v[214:217], v152, v152 op_sel_hi:[0,0,0]
	s_setprio 0
	s_setprio 1
	v_mfma_scale_f32_16x16x128_f8f6f4 v[40:43], v[0:7], v[170:177], v[40:43], v152, v152 op_sel_hi:[0,0,0]
	v_mfma_scale_f32_16x16x128_f8f6f4 v[12:15], v[154:161], v[170:177], v[218:221], v152, v152 op_sel_hi:[0,0,0]
	v_mfma_scale_f32_16x16x128_f8f6f4 v[32:35], v[134:141], v[170:177], v[222:225], v152, v152 op_sel_hi:[0,0,0]
	v_mfma_scale_f32_16x16x128_f8f6f4 v[8:11], v[162:169], v[170:177], v[226:229], v152, v152 op_sel_hi:[0,0,0]
	v_mfma_scale_f32_16x16x128_f8f6f4 v[24:27], v[0:7], v[178:185], v[230:233], v152, v152 op_sel_hi:[0,0,0]
	v_mfma_scale_f32_16x16x128_f8f6f4 v[4:7], v[154:161], v[178:185], v[234:237], v152, v152 op_sel_hi:[0,0,0]
	v_mfma_scale_f32_16x16x128_f8f6f4 v[16:19], v[134:141], v[178:185], v[238:241], v152, v152 op_sel_hi:[0,0,0]
	v_mfma_scale_f32_16x16x128_f8f6f4 v[0:3], v[162:169], v[178:185], v[242:245], v152, v152 op_sel_hi:[0,0,0]
	s_barrier
	s_setprio 0
	s_add_u32 s52, s52, 0x100
	s_addc_u32 s53, s53, 0
	s_add_u32 s30, s30, 0x100
	s_addc_u32 s31, s31, 0
	s_cmp_ge_i32 s45, s20
	s_mov_b32 s47, s45
	s_cbranch_scc0 .LBB0_779

; #define PG8_LDA(dst, b, h) do { if constexpr (FP8) { _Pragma("unroll") for (int m = 0; m < 4; ++m) dst##8[m] = PG8_LD8(PG8_SA(b, h), aoff, aoff1, m); } \
;         else { _Pragma("unroll") for (int m = 0; m < 4; ++m) _Pragma("unroll") for (int k = 0; k < 2; ++k) dst[m][k] = *(const LAS bf16x8*)(lds + PG8_SA(b, h) + (k ? aoff1 : aoff) + m * 2048); } } while (0)
; #define PG8_LDB(dst, b, h) do { if constexpr (FP8) { dst##8[0] = PG8_LD8(PG8_SB(b, h), boff, boff1, 0); dst##8[1] = PG8_LD8(PG8_SB(b, h), boff, boff1, 1); } \
;         else { _Pragma("unroll") for (int n = 0; n < 2; ++n) _Pragma("unroll") for (int k = 0; k < 2; ++k) dst[n][k] = *(const LAS bf16x8*)(lds + PG8_SB(b, h) + (k ? boff1 : boff) + n * 2048); } } while (0)
; #define PG8_WAIT_V(n) asm volatile("s_waitcnt vmcnt(" #n ")" ::: "memory")
; #define PG8_WAIT_L(n) asm volatile("s_waitcnt lgkmcnt(" #n ")" ::: "memory")
; #define PG8_BAR __builtin_amdgcn_s_barrier()
; #define PG8_SCHED __builtin_amdgcn_sched_barrier(0)
; #define PG8_S1 PG8_STAGE(PG8_SA(1, 1), a1 + hstepA, voffA)
; template <class Epi, class SchedT, bool ALIGN_EPI, bool SP2, bool FP8 = false>
; __device__ __forceinline__ void gemm_phase(LAS unsigned char* lds, const Gemm g, const SchedT& S, const Epi& E, const int wid) {
;     ...
;     for (;;) {
;         const bool has_next = S.next(ui + 1, nxt);
;         const char* nA = has_next ? (const char*)g.A + (size_t)nxt.pm * tstepA + (size_t)nxt.aoff * 2 : cA; const char* nB = has_next ? (const char*)g.Bt + (size_t)nxt.pn * tstepB + (size_t)nxt.boff * 2 : cB;
;         const int nt = cur.nt;
;         for (int t = 0; t < nt; t += 2) {
;             const bool last = (t == nt - 2);
;             const char* a1 = cA + (size_t)(t + 1) * kstep;
;             const char* a2 = last ? nA : cA + (size_t)(t + 2) * kstep; const char* b2 = last ? nB : cB + (size_t)(t + 2) * kstep;
;             const char* a3 = a2 + kstep; const char* b3 = b2 + kstep;
;             if constexpr (SP2) {
;     ...
;             PG8_LDB(B0, 0, 0); PG8_LDB(B1, 0, 1); PG8_SCHED; PG8_LDA(At, 0, 0); PG8_S1;
;             PG8_WAIT_V(8); PG8_WAIT_L(0); PG8_BAR; PG8_MMAP(0, 0, 0); PG8_BAR; PG8_SCHED;
;             PG8_LDA(At, 0, 1); PG8_S2;
;             PG8_WAIT_V(8); PG8_WAIT_L(0); PG8_BAR; PG8_MMAP(1, 0, 1); PG8_BAR; PG8_SCHED;
.LBB0_897:
	s_ashr_i32 s27, s26, 31
	s_lshl_b64 s[24:25], s[26:27], 19
	s_add_u32 s40, s2, s24
	s_addc_u32 s41, s3, s25
	s_ashr_i32 s15, s14, 31
	s_lshl_b64 s[24:25], s[14:15], 19
	s_add_u32 s42, s18, s24
	s_addc_u32 s43, s19, s25
	s_cmp_lt_i32 s20, 1
	s_cbranch_scc1 .LBB0_893
	v_cmp_lt_i64_e32 vcc, s[52:53], v[146:147]
	s_and_b64 s[24:25], vcc, exec
	s_cselect_b32 s15, s41, s49
	s_cselect_b32 s21, s40, s48
	s_cselect_b32 s24, s43, s51
	s_cselect_b32 s25, s42, s50
	s_add_i32 s27, s20, -2
	s_add_u32 s48, s48, 0x40080
	s_addc_u32 s49, s49, 0
	s_add_u32 s30, s50, 0x100
	s_addc_u32 s31, s51, 0
	s_mov_b32 s34, 0
	ds_read_b128 v[128:131], v173
	ds_read_b128 v[132:135], v173 offset:1024
	ds_read_b128 v[136:139], v174
	ds_read_b128 v[140:143], v174 offset:1024
	ds_read_b128 v[150:153], v175
	ds_read_b128 v[154:157], v175 offset:1024
	ds_read_b128 v[158:161], v176
	ds_read_b128 v[162:165], v176 offset:1024
	s_add_i32 s35, s34, 2
	s_add_u32 s16, s48, 0xfffc0080
	s_addc_u32 s17, s49, -1
	s_cmp_eq_u32 s27, s34
	s_cselect_b32 s51, s15, s17
	s_cselect_b32 s50, s21, s16
	s_cselect_b32 s53, s24, s31
	s_cselect_b32 s52, s25, s30
	v_mov_b32_e32 v144, v168
	ds_read_b128 v[182:185], v177
	ds_read_b128 v[186:189], v177 offset:1024
	ds_read_b128 v[190:193], v177 offset:2048
	ds_read_b128 v[194:197], v177 offset:3072
	ds_read_b128 v[198:201], v177 offset:4096
	ds_read_b128 v[202:205], v177 offset:5120
	ds_read_b128 v[206:209], v177 offset:6144
	ds_read_b128 v[210:213], v177 offset:7168
	s_add_i32 m0, s87, 0xc000
	s_nop 0
	global_load_lds_dwordx4 v144, s[48:49]
	v_mov_b32_e32 v144, v170
	s_add_i32 m0, s87, 0xe000
	s_nop 0
	global_load_lds_dwordx4 v144, s[48:49]
	s_waitcnt vmcnt(8)
	s_waitcnt lgkmcnt(0)
	s_setprio 1
	s_barrier
	v_mfma_f32_16x16x32_bf16 v[124:127], v[128:131], v[182:185], 0
	v_mfma_f32_16x16x32_bf16 v[120:123], v[136:139], v[182:185], 0
	v_mfma_f32_16x16x32_bf16 v[104:107], v[136:139], v[190:193], 0
	v_mfma_f32_16x16x32_bf16 v[108:111], v[128:131], v[190:193], 0
	v_mfma_f32_16x16x32_bf16 v[92:95], v[128:131], v[198:201], 0
	v_mfma_f32_16x16x32_bf16 v[88:91], v[136:139], v[198:201], 0
	v_mfma_f32_16x16x32_bf16 v[72:75], v[136:139], v[206:209], 0
	v_mfma_f32_16x16x32_bf16 v[76:79], v[128:131], v[206:209], 0
	s_setprio 0
	s_setprio 1
	v_mfma_f32_16x16x32_bf16 v[124:127], v[132:135], v[186:189], v[124:127]
	v_mfma_f32_16x16x32_bf16 v[120:123], v[140:143], v[186:189], v[120:123]
	v_mfma_f32_16x16x32_bf16 v[104:107], v[140:143], v[194:197], v[104:107]
	v_mfma_f32_16x16x32_bf16 v[108:111], v[132:135], v[194:197], v[108:111]
	v_mfma_f32_16x16x32_bf16 v[92:95], v[132:135], v[202:205], v[92:95]
	v_mfma_f32_16x16x32_bf16 v[88:91], v[140:143], v[202:205], v[88:91]
	v_mfma_f32_16x16x32_bf16 v[72:75], v[140:143], v[210:213], v[72:75]
	v_mfma_f32_16x16x32_bf16 v[76:79], v[132:135], v[210:213], v[76:79]
	s_setprio 0
	s_setprio 1
	v_mfma_f32_16x16x32_bf16 v[116:119], v[150:153], v[182:185], 0
	v_mfma_f32_16x16x32_bf16 v[112:115], v[158:161], v[182:185], 0
	v_mfma_f32_16x16x32_bf16 v[96:99], v[158:161], v[190:193], 0
	v_mfma_f32_16x16x32_bf16 v[100:103], v[150:153], v[190:193], 0
	v_mfma_f32_16x16x32_bf16 v[84:87], v[150:153], v[198:201], 0
	v_mfma_f32_16x16x32_bf16 v[80:83], v[158:161], v[198:201], 0
	v_mfma_f32_16x16x32_bf16 v[64:67], v[158:161], v[206:209], 0
	v_mfma_f32_16x16x32_bf16 v[68:71], v[150:153], v[206:209], 0
	s_setprio 0
	s_setprio 1
	v_mfma_f32_16x16x32_bf16 v[116:119], v[154:157], v[186:189], v[116:119]
	v_mfma_f32_16x16x32_bf16 v[112:115], v[162:165], v[186:189], v[112:115]
	v_mfma_f32_16x16x32_bf16 v[96:99], v[162:165], v[194:197], v[96:99]
	v_mfma_f32_16x16x32_bf16 v[100:103], v[154:157], v[194:197], v[100:103]
	v_mfma_f32_16x16x32_bf16 v[84:87], v[154:157], v[202:205], v[84:87]
	v_mfma_f32_16x16x32_bf16 v[80:83], v[162:165], v[202:205], v[80:83]
	v_mfma_f32_16x16x32_bf16 v[64:67], v[162:165], v[210:213], v[64:67]
	v_mfma_f32_16x16x32_bf16 v[68:71], v[154:157], v[210:213], v[68:71]
	s_barrier
	s_setprio 0
	v_mov_b32_e32 v144, v169
	s_add_i32 s16, s94, s86
	ds_read_b128 v[182:185], v177 offset:16384
	ds_read_b128 v[186:189], v177 offset:17408
	ds_read_b128 v[190:193], v177 offset:18432
	ds_read_b128 v[194:197], v177 offset:19456
	ds_read_b128 v[198:201], v177 offset:20480
	ds_read_b128 v[202:205], v177 offset:21504
	ds_read_b128 v[206:209], v177 offset:22528
	ds_read_b128 v[210:213], v177 offset:23552
	s_mov_b32 m0, s16
	s_nop 0
	global_load_lds_dwordx4 v144, s[52:53]
	v_mov_b32_e32 v144, v171
	s_add_i32 m0, s16, 0x2000
	s_add_u32 s60, s52, 0x40000
	global_load_lds_dwordx4 v144, s[52:53]
	s_addc_u32 s61, s53, 0
	v_mov_b32_e32 v144, v169
	s_add_i32 s16, s95, s86
	s_mov_b32 m0, s16
	s_nop 0
	global_load_lds_dwordx4 v144, s[60:61]
	v_mov_b32_e32 v144, v171
	s_add_i32 m0, s16, 0x2000
	s_nop 0
	global_load_lds_dwordx4 v144, s[60:61]
	v_mov_b32_e32 v144, v168
	s_mov_b32 m0, s87
	s_nop 0
	global_load_lds_dwordx4 v144, s[50:51]
	v_mov_b32_e32 v144, v170
	s_mov_b32 m0, s88
	s_nop 0
	global_load_lds_dwordx4 v144, s[50:51]
	s_waitcnt vmcnt(8)
	s_waitcnt lgkmcnt(0)
	s_setprio 1
	s_barrier
; #define PG8_LDA(dst, b, h) do { if constexpr (FP8) { _Pragma("unroll") for (int m = 0; m < 4; ++m) dst##8[m] = PG8_LD8(PG8_SA(b, h), aoff, aoff1, m); } \
;         else { _Pragma("unroll") for (int m = 0; m < 4; ++m) _Pragma("unroll") for (int k = 0; k < 2; ++k) dst[m][k] = *(const LAS bf16x8*)(lds + PG8_SA(b, h) + (k ? aoff1 : aoff) + m * 2048); } } while (0)
; #define PG8_LDB(dst, b, h) do { if constexpr (FP8) { dst##8[0] = PG8_LD8(PG8_SB(b, h), boff, boff1, 0); dst##8[1] = PG8_LD8(PG8_SB(b, h), boff, boff1, 1); } \
;         else { _Pragma("unroll") for (int n = 0; n < 2; ++n) _Pragma("unroll") for (int k = 0; k < 2; ++k) dst[n][k] = *(const LAS bf16x8*)(lds + PG8_SB(b, h) + (k ? boff1 : boff) + n * 2048); } } while (0)
; #define PG8_WAIT_V(n) asm volatile("s_waitcnt vmcnt(" #n ")" ::: "memory")
; #define PG8_WAIT_L(n) asm volatile("s_waitcnt lgkmcnt(" #n ")" ::: "memory")
; #define PG8_BAR __builtin_amdgcn_s_barrier()
; #define PG8_SCHED __builtin_amdgcn_sched_barrier(0)
; #define PG8_S2 do { PG8_STAGE(PG8_SB(0, 0), b2, voffB); PG8_STAGE(PG8_SB(0, 1), b2 + hstepB, voffB); PG8_STAGE(PG8_SA(0, 0), a2, voffA); } while (0)
; #define PG8_S3 PG8_STAGE(PG8_SA(0, 1), a2 + hstepA, voffA)
; #define PG8_S4 do { PG8_STAGE(PG8_SB(1, 0), b3, voffB); PG8_STAGE(PG8_SB(1, 1), b3 + hstepB, voffB); PG8_STAGE(PG8_SA(1, 0), a3, voffA); } while (0)
; template <class Epi, class SchedT, bool ALIGN_EPI, bool SP2, bool FP8 = false>
; __device__ __forceinline__ void gemm_phase(LAS unsigned char* lds, const Gemm g, const SchedT& S, const Epi& E, const int wid) {
;     ...
;             PG8_LDA(At, 0, 1); PG8_S2;
;             PG8_WAIT_V(8); PG8_WAIT_L(0); PG8_BAR; PG8_MMAP(1, 0, 1); PG8_BAR; PG8_SCHED;
;             PG8_LDB(B0, 1, 0); PG8_LDB(B1, 1, 1); PG8_SCHED; PG8_LDA(At, 1, 0); PG8_S3;
;             PG8_WAIT_V(8); PG8_WAIT_L(0); PG8_BAR; PG8_MMAP(0, 1, 0); PG8_BAR; PG8_SCHED;
;             PG8_LDA(At, 1, 1); PG8_S4;
;             PG8_WAIT_V(8); PG8_WAIT_L(0); PG8_BAR; PG8_MMAP(1, 1, 1); PG8_BAR; PG8_SCHED;
	v_mfma_f32_16x16x32_bf16 v[60:63], v[128:131], v[182:185], 0
	v_mfma_f32_16x16x32_bf16 v[56:59], v[136:139], v[182:185], 0
	v_mfma_f32_16x16x32_bf16 v[40:43], v[136:139], v[190:193], 0
	v_mfma_f32_16x16x32_bf16 v[44:47], v[128:131], v[190:193], 0
	v_mfma_f32_16x16x32_bf16 v[28:31], v[128:131], v[198:201], 0
	v_mfma_f32_16x16x32_bf16 v[24:27], v[136:139], v[198:201], 0
	v_mfma_f32_16x16x32_bf16 v[8:11], v[136:139], v[206:209], 0
	v_mfma_f32_16x16x32_bf16 v[12:15], v[128:131], v[206:209], 0
	s_setprio 0
	s_setprio 1
	v_mfma_f32_16x16x32_bf16 v[60:63], v[132:135], v[186:189], v[60:63]
	v_mfma_f32_16x16x32_bf16 v[56:59], v[140:143], v[186:189], v[56:59]
	v_mfma_f32_16x16x32_bf16 v[40:43], v[140:143], v[194:197], v[40:43]
	v_mfma_f32_16x16x32_bf16 v[44:47], v[132:135], v[194:197], v[44:47]
	v_mfma_f32_16x16x32_bf16 v[28:31], v[132:135], v[202:205], v[28:31]
	v_mfma_f32_16x16x32_bf16 v[24:27], v[140:143], v[202:205], v[24:27]
	v_mfma_f32_16x16x32_bf16 v[8:11], v[140:143], v[210:213], v[8:11]
	v_mfma_f32_16x16x32_bf16 v[12:15], v[132:135], v[210:213], v[12:15]
	s_setprio 0
	s_setprio 1
	v_mfma_f32_16x16x32_bf16 v[52:55], v[150:153], v[182:185], 0
	v_mfma_f32_16x16x32_bf16 v[48:51], v[158:161], v[182:185], 0
	v_mfma_f32_16x16x32_bf16 v[32:35], v[158:161], v[190:193], 0
	v_mfma_f32_16x16x32_bf16 v[36:39], v[150:153], v[190:193], 0
	v_mfma_f32_16x16x32_bf16 v[20:23], v[150:153], v[198:201], 0
	v_mfma_f32_16x16x32_bf16 v[16:19], v[158:161], v[198:201], 0
	v_mfma_f32_16x16x32_bf16 v[0:3], v[158:161], v[206:209], 0
	v_mfma_f32_16x16x32_bf16 v[4:7], v[150:153], v[206:209], 0
	s_setprio 0
	s_setprio 1
	v_mfma_f32_16x16x32_bf16 v[52:55], v[154:157], v[186:189], v[52:55]
	v_mfma_f32_16x16x32_bf16 v[48:51], v[162:165], v[186:189], v[48:51]
	v_mfma_f32_16x16x32_bf16 v[32:35], v[162:165], v[194:197], v[32:35]
	v_mfma_f32_16x16x32_bf16 v[36:39], v[154:157], v[194:197], v[36:39]
	v_mfma_f32_16x16x32_bf16 v[20:23], v[154:157], v[202:205], v[20:23]
	v_mfma_f32_16x16x32_bf16 v[16:19], v[162:165], v[202:205], v[16:19]
	v_mfma_f32_16x16x32_bf16 v[0:3], v[162:165], v[210:213], v[0:3]
	v_mfma_f32_16x16x32_bf16 v[4:7], v[154:157], v[210:213], v[4:7]
	s_barrier
	s_setprio 0
	s_add_i32 s16, 0, 0x18000
	s_add_i32 s17, 0, 0x1c000
	v_add_u32_e32 v132, s16, v172
	v_add_u32_e32 v144, s17, v172
	ds_read_b128 v[128:131], v132
	ds_read_b128 v[132:135], v132 offset:1024
	ds_read_b128 v[136:139], v178
	ds_read_b128 v[140:143], v178 offset:1024
	ds_read_b128 v[150:153], v144
	ds_read_b128 v[154:157], v144 offset:1024
	ds_read_b128 v[158:161], v179
	ds_read_b128 v[162:165], v179 offset:1024
	s_add_u32 s60, s50, 0x40000
	v_mov_b32_e32 v144, v168
	s_mov_b32 m0, s89
	ds_read_b128 v[182:185], v177 offset:32768
	ds_read_b128 v[186:189], v177 offset:33792
	ds_read_b128 v[190:193], v177 offset:34816
	ds_read_b128 v[194:197], v177 offset:35840
	ds_read_b128 v[198:201], v177 offset:36864
	ds_read_b128 v[202:205], v177 offset:37888
	ds_read_b128 v[206:209], v177 offset:38912
	ds_read_b128 v[210:213], v177 offset:39936
	s_addc_u32 s61, s51, 0
	s_nop 0
	global_load_lds_dwordx4 v144, s[60:61]
	v_mov_b32_e32 v144, v170
	s_mov_b32 m0, s90
	s_nop 0
	global_load_lds_dwordx4 v144, s[60:61]
	s_waitcnt vmcnt(8)
	s_waitcnt lgkmcnt(0)
	s_setprio 1
	s_barrier
	v_mfma_f32_16x16x32_bf16 v[124:127], v[128:131], v[182:185], v[124:127]
	v_mfma_f32_16x16x32_bf16 v[120:123], v[136:139], v[182:185], v[120:123]
	v_mfma_f32_16x16x32_bf16 v[104:107], v[136:139], v[190:193], v[104:107]
	v_mfma_f32_16x16x32_bf16 v[108:111], v[128:131], v[190:193], v[108:111]
	v_mfma_f32_16x16x32_bf16 v[92:95], v[128:131], v[198:201], v[92:95]
	v_mfma_f32_16x16x32_bf16 v[88:91], v[136:139], v[198:201], v[88:91]
	v_mfma_f32_16x16x32_bf16 v[72:75], v[136:139], v[206:209], v[72:75]
	v_mfma_f32_16x16x32_bf16 v[76:79], v[128:131], v[206:209], v[76:79]
	s_setprio 0
	s_setprio 1
	v_mfma_f32_16x16x32_bf16 v[124:127], v[132:135], v[186:189], v[124:127]
	v_mfma_f32_16x16x32_bf16 v[120:123], v[140:143], v[186:189], v[120:123]
	v_mfma_f32_16x16x32_bf16 v[104:107], v[140:143], v[194:197], v[104:107]
	v_mfma_f32_16x16x32_bf16 v[108:111], v[132:135], v[194:197], v[108:111]
	v_mfma_f32_16x16x32_bf16 v[92:95], v[132:135], v[202:205], v[92:95]
	v_mfma_f32_16x16x32_bf16 v[88:91], v[140:143], v[202:205], v[88:91]
	v_mfma_f32_16x16x32_bf16 v[72:75], v[140:143], v[210:213], v[72:75]
	v_mfma_f32_16x16x32_bf16 v[76:79], v[132:135], v[210:213], v[76:79]
	s_setprio 0
	s_setprio 1
	v_mfma_f32_16x16x32_bf16 v[116:119], v[150:153], v[182:185], v[116:119]
	v_mfma_f32_16x16x32_bf16 v[112:115], v[158:161], v[182:185], v[112:115]
	v_mfma_f32_16x16x32_bf16 v[96:99], v[158:161], v[190:193], v[96:99]
	v_mfma_f32_16x16x32_bf16 v[100:103], v[150:153], v[190:193], v[100:103]
	v_mfma_f32_16x16x32_bf16 v[84:87], v[150:153], v[198:201], v[84:87]
	v_mfma_f32_16x16x32_bf16 v[80:83], v[158:161], v[198:201], v[80:83]
	v_mfma_f32_16x16x32_bf16 v[64:67], v[158:161], v[206:209], v[64:67]
	v_mfma_f32_16x16x32_bf16 v[68:71], v[150:153], v[206:209], v[68:71]
	s_setprio 0
	s_setprio 1
	v_mfma_f32_16x16x32_bf16 v[116:119], v[154:157], v[186:189], v[116:119]
	v_mfma_f32_16x16x32_bf16 v[112:115], v[162:165], v[186:189], v[112:115]
	v_mfma_f32_16x16x32_bf16 v[96:99], v[162:165], v[194:197], v[96:99]
	v_mfma_f32_16x16x32_bf16 v[100:103], v[154:157], v[194:197], v[100:103]
	v_mfma_f32_16x16x32_bf16 v[84:87], v[154:157], v[202:205], v[84:87]
	v_mfma_f32_16x16x32_bf16 v[80:83], v[162:165], v[202:205], v[80:83]
	v_mfma_f32_16x16x32_bf16 v[64:67], v[162:165], v[210:213], v[64:67]
	v_mfma_f32_16x16x32_bf16 v[68:71], v[154:157], v[210:213], v[68:71]
	s_barrier
; #define PG8_LDA(dst, b, h) do { if constexpr (FP8) { _Pragma("unroll") for (int m = 0; m < 4; ++m) dst##8[m] = PG8_LD8(PG8_SA(b, h), aoff, aoff1, m); } \
;         else { _Pragma("unroll") for (int m = 0; m < 4; ++m) _Pragma("unroll") for (int k = 0; k < 2; ++k) dst[m][k] = *(const LAS bf16x8*)(lds + PG8_SA(b, h) + (k ? aoff1 : aoff) + m * 2048); } } while (0)
; #define PG8_LDB(dst, b, h) do { if constexpr (FP8) { dst##8[0] = PG8_LD8(PG8_SB(b, h), boff, boff1, 0); dst##8[1] = PG8_LD8(PG8_SB(b, h), boff, boff1, 1); } \
;         else { _Pragma("unroll") for (int n = 0; n < 2; ++n) _Pragma("unroll") for (int k = 0; k < 2; ++k) dst[n][k] = *(const LAS bf16x8*)(lds + PG8_SB(b, h) + (k ? boff1 : boff) + n * 2048); } } while (0)
; #define PG8_WAIT_V(n) asm volatile("s_waitcnt vmcnt(" #n ")" ::: "memory")
; #define PG8_WAIT_L(n) asm volatile("s_waitcnt lgkmcnt(" #n ")" ::: "memory")
; #define PG8_BAR __builtin_amdgcn_s_barrier()
; #define PG8_SCHED __builtin_amdgcn_sched_barrier(0)
; #define PG8_S1 PG8_STAGE(PG8_SA(1, 1), a1 + hstepA, voffA)
; #define PG8_S4 do { PG8_STAGE(PG8_SB(1, 0), b3, voffB); PG8_STAGE(PG8_SB(1, 1), b3 + hstepB, voffB); PG8_STAGE(PG8_SA(1, 0), a3, voffA); } while (0)
; template <class Epi, class SchedT, bool ALIGN_EPI, bool SP2, bool FP8 = false>
; __device__ __forceinline__ void gemm_phase(LAS unsigned char* lds, const Gemm g, const SchedT& S, const Epi& E, const int wid) {
;     ...
;         for (int t = 0; t < nt; t += 2) {
;             const bool last = (t == nt - 2);
;             const char* a1 = cA + (size_t)(t + 1) * kstep;
;             const char* a2 = last ? nA : cA + (size_t)(t + 2) * kstep; const char* b2 = last ? nB : cB + (size_t)(t + 2) * kstep;
;             const char* a3 = a2 + kstep; const char* b3 = b2 + kstep;
;             if constexpr (SP2) {
;     ...
;             PG8_LDB(B0, 0, 0); PG8_LDB(B1, 0, 1); PG8_SCHED; PG8_LDA(At, 0, 0); PG8_S1;
;             PG8_WAIT_V(8); PG8_WAIT_L(0); PG8_BAR; PG8_MMAP(0, 0, 0); PG8_BAR; PG8_SCHED;
;     ...
;             PG8_LDA(At, 1, 1); PG8_S4;
;             PG8_WAIT_V(8); PG8_WAIT_L(0); PG8_BAR; PG8_MMAP(1, 1, 1); PG8_BAR; PG8_SCHED;
	s_setprio 0
	v_mov_b32_e32 v144, v169
	ds_read_b128 v[182:185], v177 offset:49152
	ds_read_b128 v[186:189], v177 offset:50176
	ds_read_b128 v[190:193], v177 offset:51200
	ds_read_b128 v[194:197], v177 offset:52224
	ds_read_b128 v[198:201], v177 offset:53248
	ds_read_b128 v[202:205], v177 offset:54272
	ds_read_b128 v[206:209], v177 offset:55296
	ds_read_b128 v[210:213], v177 offset:56320
	s_add_i32 s16, s16, s86
	v_lshl_add_u64 v[166:167], s[52:53], 0, v[144:145]
	v_lshl_add_u64 v[166:167], v[166:167], 0, s[6:7]
	s_mov_b32 m0, s16
	v_mov_b32_e32 v144, v171
	global_load_lds_dwordx4 v[166:167], off
	s_add_i32 m0, s16, 0x2000
	s_nop 0
	v_lshl_add_u64 v[166:167], s[52:53], 0, v[144:145]
	s_add_u32 s52, s52, 0x40080
	v_lshl_add_u64 v[166:167], v[166:167], 0, s[6:7]
	s_addc_u32 s53, s53, 0
	v_mov_b32_e32 v144, v169
	s_add_i32 s16, s17, s86
	global_load_lds_dwordx4 v[166:167], off
	s_mov_b32 m0, s16
	s_nop 0
	global_load_lds_dwordx4 v144, s[52:53]
	v_mov_b32_e32 v144, v171
	s_add_i32 m0, s16, 0x2000
	s_nop 0
	global_load_lds_dwordx4 v144, s[52:53]
	v_mov_b32_e32 v144, v168
	s_mov_b32 m0, s92
	v_lshl_add_u64 v[166:167], s[50:51], 0, v[144:145]
	v_lshl_add_u64 v[166:167], v[166:167], 0, s[6:7]
	v_mov_b32_e32 v144, v170
	global_load_lds_dwordx4 v[166:167], off
	s_mov_b32 m0, s93
	v_lshl_add_u64 v[166:167], s[50:51], 0, v[144:145]
	v_lshl_add_u64 v[166:167], v[166:167], 0, s[6:7]
	global_load_lds_dwordx4 v[166:167], off
	s_waitcnt vmcnt(8)
	s_waitcnt lgkmcnt(0)
	s_setprio 1
	s_barrier
	v_mfma_f32_16x16x32_bf16 v[60:63], v[128:131], v[182:185], v[60:63]
	v_mfma_f32_16x16x32_bf16 v[56:59], v[136:139], v[182:185], v[56:59]
	v_mfma_f32_16x16x32_bf16 v[40:43], v[136:139], v[190:193], v[40:43]
	v_mfma_f32_16x16x32_bf16 v[44:47], v[128:131], v[190:193], v[44:47]
	v_mfma_f32_16x16x32_bf16 v[28:31], v[128:131], v[198:201], v[28:31]
	v_mfma_f32_16x16x32_bf16 v[24:27], v[136:139], v[198:201], v[24:27]
	v_mfma_f32_16x16x32_bf16 v[8:11], v[136:139], v[206:209], v[8:11]
	v_mfma_f32_16x16x32_bf16 v[12:15], v[128:131], v[206:209], v[12:15]
	s_setprio 0
	s_setprio 1
	v_mfma_f32_16x16x32_bf16 v[60:63], v[132:135], v[186:189], v[60:63]
	v_mfma_f32_16x16x32_bf16 v[56:59], v[140:143], v[186:189], v[56:59]
	v_mfma_f32_16x16x32_bf16 v[40:43], v[140:143], v[194:197], v[40:43]
	v_mfma_f32_16x16x32_bf16 v[44:47], v[132:135], v[194:197], v[44:47]
	v_mfma_f32_16x16x32_bf16 v[28:31], v[132:135], v[202:205], v[28:31]
	v_mfma_f32_16x16x32_bf16 v[24:27], v[140:143], v[202:205], v[24:27]
	v_mfma_f32_16x16x32_bf16 v[8:11], v[140:143], v[210:213], v[8:11]
	v_mfma_f32_16x16x32_bf16 v[12:15], v[132:135], v[210:213], v[12:15]
	s_setprio 0
	s_setprio 1
	v_mfma_f32_16x16x32_bf16 v[52:55], v[150:153], v[182:185], v[52:55]
	v_mfma_f32_16x16x32_bf16 v[48:51], v[158:161], v[182:185], v[48:51]
	v_mfma_f32_16x16x32_bf16 v[32:35], v[158:161], v[190:193], v[32:35]
	v_mfma_f32_16x16x32_bf16 v[36:39], v[150:153], v[190:193], v[36:39]
	v_mfma_f32_16x16x32_bf16 v[20:23], v[150:153], v[198:201], v[20:23]
	v_mfma_f32_16x16x32_bf16 v[16:19], v[158:161], v[198:201], v[16:19]
	v_mfma_f32_16x16x32_bf16 v[0:3], v[158:161], v[206:209], v[0:3]
	v_mfma_f32_16x16x32_bf16 v[4:7], v[150:153], v[206:209], v[4:7]
	s_setprio 0
	s_setprio 1
	v_mfma_f32_16x16x32_bf16 v[52:55], v[154:157], v[186:189], v[52:55]
	v_mfma_f32_16x16x32_bf16 v[48:51], v[162:165], v[186:189], v[48:51]
	v_mfma_f32_16x16x32_bf16 v[32:35], v[162:165], v[194:197], v[32:35]
	v_mfma_f32_16x16x32_bf16 v[36:39], v[154:157], v[194:197], v[36:39]
	v_mfma_f32_16x16x32_bf16 v[20:23], v[154:157], v[202:205], v[20:23]
	v_mfma_f32_16x16x32_bf16 v[16:19], v[162:165], v[202:205], v[16:19]
	v_mfma_f32_16x16x32_bf16 v[0:3], v[162:165], v[210:213], v[0:3]
	v_mfma_f32_16x16x32_bf16 v[4:7], v[154:157], v[210:213], v[4:7]
	s_barrier
	s_setprio 0
	s_add_u32 s48, s48, 0x100
	s_addc_u32 s49, s49, 0
	s_add_u32 s30, s30, 0x100
	s_addc_u32 s31, s31, 0
	s_cmp_ge_i32 s35, s20
	s_mov_b32 s34, s35
	s_cbranch_scc1 .Lpeel_exit_lbb0_899
.LBB0_899:
	ds_read_b128 v[128:131], v173
	ds_read_b128 v[132:135], v173 offset:1024
	ds_read_b128 v[136:139], v174
	ds_read_b128 v[140:143], v174 offset:1024
	ds_read_b128 v[150:153], v175
	ds_read_b128 v[154:157], v175 offset:1024
	ds_read_b128 v[158:161], v176
	ds_read_b128 v[162:165], v176 offset:1024
	s_add_i32 s35, s34, 2
	s_add_u32 s16, s48, 0xfffc0080
	s_addc_u32 s17, s49, -1
	s_cmp_eq_u32 s27, s34
	s_cselect_b32 s51, s15, s17
	s_cselect_b32 s50, s21, s16
	s_cselect_b32 s53, s24, s31
	s_cselect_b32 s52, s25, s30
	v_mov_b32_e32 v144, v168
	ds_read_b128 v[182:185], v177
	ds_read_b128 v[186:189], v177 offset:1024
	ds_read_b128 v[190:193], v177 offset:2048
	ds_read_b128 v[194:197], v177 offset:3072
	ds_read_b128 v[198:201], v177 offset:4096
	ds_read_b128 v[202:205], v177 offset:5120
	ds_read_b128 v[206:209], v177 offset:6144
	ds_read_b128 v[210:213], v177 offset:7168
	s_add_i32 m0, s87, 0xc000
	s_nop 0
	global_load_lds_dwordx4 v144, s[48:49]
	v_mov_b32_e32 v144, v170
	s_add_i32 m0, s87, 0xe000
	s_nop 0
	global_load_lds_dwordx4 v144, s[48:49]
	s_waitcnt vmcnt(8)
	s_waitcnt lgkmcnt(0)
	s_setprio 1
	s_barrier
; #define PG8_LDA(dst, b, h) do { if constexpr (FP8) { _Pragma("unroll") for (int m = 0; m < 4; ++m) dst##8[m] = PG8_LD8(PG8_SA(b, h), aoff, aoff1, m); } \
;         else { _Pragma("unroll") for (int m = 0; m < 4; ++m) _Pragma("unroll") for (int k = 0; k < 2; ++k) dst[m][k] = *(const LAS bf16x8*)(lds + PG8_SA(b, h) + (k ? aoff1 : aoff) + m * 2048); } } while (0)
; #define PG8_LDB(dst, b, h) do { if constexpr (FP8) { dst##8[0] = PG8_LD8(PG8_SB(b, h), boff, boff1, 0); dst##8[1] = PG8_LD8(PG8_SB(b, h), boff, boff1, 1); } \
;         else { _Pragma("unroll") for (int n = 0; n < 2; ++n) _Pragma("unroll") for (int k = 0; k < 2; ++k) dst[n][k] = *(const LAS bf16x8*)(lds + PG8_SB(b, h) + (k ? boff1 : boff) + n * 2048); } } while (0)
; #define PG8_WAIT_V(n) asm volatile("s_waitcnt vmcnt(" #n ")" ::: "memory")
; #define PG8_WAIT_L(n) asm volatile("s_waitcnt lgkmcnt(" #n ")" ::: "memory")
; #define PG8_BAR __builtin_amdgcn_s_barrier()
; #define PG8_SCHED __builtin_amdgcn_sched_barrier(0)
; #define PG8_S1 PG8_STAGE(PG8_SA(1, 1), a1 + hstepA, voffA)
; #define PG8_S2 do { PG8_STAGE(PG8_SB(0, 0), b2, voffB); PG8_STAGE(PG8_SB(0, 1), b2 + hstepB, voffB); PG8_STAGE(PG8_SA(0, 0), a2, voffA); } while (0)
; template <class Epi, class SchedT, bool ALIGN_EPI, bool SP2, bool FP8 = false>
; __device__ __forceinline__ void gemm_phase(LAS unsigned char* lds, const Gemm g, const SchedT& S, const Epi& E, const int wid) {
;     ...
;             PG8_LDB(B0, 0, 0); PG8_LDB(B1, 0, 1); PG8_SCHED; PG8_LDA(At, 0, 0); PG8_S1;
;             PG8_WAIT_V(8); PG8_WAIT_L(0); PG8_BAR; PG8_MMAP(0, 0, 0); PG8_BAR; PG8_SCHED;
;             PG8_LDA(At, 0, 1); PG8_S2;
;             PG8_WAIT_V(8); PG8_WAIT_L(0); PG8_BAR; PG8_MMAP(1, 0, 1); PG8_BAR; PG8_SCHED;
	v_mfma_f32_16x16x32_bf16 v[124:127], v[128:131], v[182:185], v[124:127]
	v_mfma_f32_16x16x32_bf16 v[120:123], v[136:139], v[182:185], v[120:123]
	v_mfma_f32_16x16x32_bf16 v[104:107], v[136:139], v[190:193], v[104:107]
	v_mfma_f32_16x16x32_bf16 v[108:111], v[128:131], v[190:193], v[108:111]
	v_mfma_f32_16x16x32_bf16 v[92:95], v[128:131], v[198:201], v[92:95]
	v_mfma_f32_16x16x32_bf16 v[88:91], v[136:139], v[198:201], v[88:91]
	v_mfma_f32_16x16x32_bf16 v[72:75], v[136:139], v[206:209], v[72:75]
	v_mfma_f32_16x16x32_bf16 v[76:79], v[128:131], v[206:209], v[76:79]
	s_setprio 0
	s_setprio 1
	v_mfma_f32_16x16x32_bf16 v[124:127], v[132:135], v[186:189], v[124:127]
	v_mfma_f32_16x16x32_bf16 v[120:123], v[140:143], v[186:189], v[120:123]
	v_mfma_f32_16x16x32_bf16 v[104:107], v[140:143], v[194:197], v[104:107]
	v_mfma_f32_16x16x32_bf16 v[108:111], v[132:135], v[194:197], v[108:111]
	v_mfma_f32_16x16x32_bf16 v[92:95], v[132:135], v[202:205], v[92:95]
	v_mfma_f32_16x16x32_bf16 v[88:91], v[140:143], v[202:205], v[88:91]
	v_mfma_f32_16x16x32_bf16 v[72:75], v[140:143], v[210:213], v[72:75]
	v_mfma_f32_16x16x32_bf16 v[76:79], v[132:135], v[210:213], v[76:79]
	s_setprio 0
	s_setprio 1
	v_mfma_f32_16x16x32_bf16 v[116:119], v[150:153], v[182:185], v[116:119]
	v_mfma_f32_16x16x32_bf16 v[112:115], v[158:161], v[182:185], v[112:115]
	v_mfma_f32_16x16x32_bf16 v[96:99], v[158:161], v[190:193], v[96:99]
	v_mfma_f32_16x16x32_bf16 v[100:103], v[150:153], v[190:193], v[100:103]
	v_mfma_f32_16x16x32_bf16 v[84:87], v[150:153], v[198:201], v[84:87]
	v_mfma_f32_16x16x32_bf16 v[80:83], v[158:161], v[198:201], v[80:83]
	v_mfma_f32_16x16x32_bf16 v[64:67], v[158:161], v[206:209], v[64:67]
	v_mfma_f32_16x16x32_bf16 v[68:71], v[150:153], v[206:209], v[68:71]
	s_setprio 0
	s_setprio 1
	v_mfma_f32_16x16x32_bf16 v[116:119], v[154:157], v[186:189], v[116:119]
	v_mfma_f32_16x16x32_bf16 v[112:115], v[162:165], v[186:189], v[112:115]
	v_mfma_f32_16x16x32_bf16 v[96:99], v[162:165], v[194:197], v[96:99]
	v_mfma_f32_16x16x32_bf16 v[100:103], v[154:157], v[194:197], v[100:103]
	v_mfma_f32_16x16x32_bf16 v[84:87], v[154:157], v[202:205], v[84:87]
	v_mfma_f32_16x16x32_bf16 v[80:83], v[162:165], v[202:205], v[80:83]
	v_mfma_f32_16x16x32_bf16 v[64:67], v[162:165], v[210:213], v[64:67]
	v_mfma_f32_16x16x32_bf16 v[68:71], v[154:157], v[210:213], v[68:71]
	s_barrier
	s_setprio 0
	v_mov_b32_e32 v144, v169
	s_add_i32 s16, s94, s86
	ds_read_b128 v[182:185], v177 offset:16384
	ds_read_b128 v[186:189], v177 offset:17408
	ds_read_b128 v[190:193], v177 offset:18432
	ds_read_b128 v[194:197], v177 offset:19456
	ds_read_b128 v[198:201], v177 offset:20480
	ds_read_b128 v[202:205], v177 offset:21504
	ds_read_b128 v[206:209], v177 offset:22528
	ds_read_b128 v[210:213], v177 offset:23552
	s_mov_b32 m0, s16
	s_nop 0
	global_load_lds_dwordx4 v144, s[52:53]
	v_mov_b32_e32 v144, v171
	s_add_i32 m0, s16, 0x2000
	s_add_u32 s60, s52, 0x40000
	global_load_lds_dwordx4 v144, s[52:53]
	s_addc_u32 s61, s53, 0
	v_mov_b32_e32 v144, v169
	s_add_i32 s16, s95, s86
	s_mov_b32 m0, s16
	s_nop 0
	global_load_lds_dwordx4 v144, s[60:61]
	v_mov_b32_e32 v144, v171
	s_add_i32 m0, s16, 0x2000
	s_nop 0
	global_load_lds_dwordx4 v144, s[60:61]
	v_mov_b32_e32 v144, v168
	s_mov_b32 m0, s87
	s_nop 0
	global_load_lds_dwordx4 v144, s[50:51]
	v_mov_b32_e32 v144, v170
	s_mov_b32 m0, s88
	s_nop 0
	global_load_lds_dwordx4 v144, s[50:51]
	s_waitcnt vmcnt(8)
	s_waitcnt lgkmcnt(0)
	s_setprio 1
	s_barrier
	v_mfma_f32_16x16x32_bf16 v[60:63], v[128:131], v[182:185], v[60:63]
	v_mfma_f32_16x16x32_bf16 v[56:59], v[136:139], v[182:185], v[56:59]
	v_mfma_f32_16x16x32_bf16 v[40:43], v[136:139], v[190:193], v[40:43]
	v_mfma_f32_16x16x32_bf16 v[44:47], v[128:131], v[190:193], v[44:47]
	v_mfma_f32_16x16x32_bf16 v[28:31], v[128:131], v[198:201], v[28:31]
	v_mfma_f32_16x16x32_bf16 v[24:27], v[136:139], v[198:201], v[24:27]
	v_mfma_f32_16x16x32_bf16 v[8:11], v[136:139], v[206:209], v[8:11]
	v_mfma_f32_16x16x32_bf16 v[12:15], v[128:131], v[206:209], v[12:15]
	s_setprio 0
	s_setprio 1
	v_mfma_f32_16x16x32_bf16 v[60:63], v[132:135], v[186:189], v[60:63]
	v_mfma_f32_16x16x32_bf16 v[56:59], v[140:143], v[186:189], v[56:59]
	v_mfma_f32_16x16x32_bf16 v[40:43], v[140:143], v[194:197], v[40:43]
	v_mfma_f32_16x16x32_bf16 v[44:47], v[132:135], v[194:197], v[44:47]
	v_mfma_f32_16x16x32_bf16 v[28:31], v[132:135], v[202:205], v[28:31]
	v_mfma_f32_16x16x32_bf16 v[24:27], v[140:143], v[202:205], v[24:27]
	v_mfma_f32_16x16x32_bf16 v[8:11], v[140:143], v[210:213], v[8:11]
	v_mfma_f32_16x16x32_bf16 v[12:15], v[132:135], v[210:213], v[12:15]
	s_setprio 0
	s_setprio 1
	v_mfma_f32_16x16x32_bf16 v[52:55], v[150:153], v[182:185], v[52:55]
	v_mfma_f32_16x16x32_bf16 v[48:51], v[158:161], v[182:185], v[48:51]
	v_mfma_f32_16x16x32_bf16 v[32:35], v[158:161], v[190:193], v[32:35]
	v_mfma_f32_16x16x32_bf16 v[36:39], v[150:153], v[190:193], v[36:39]
	v_mfma_f32_16x16x32_bf16 v[20:23], v[150:153], v[198:201], v[20:23]
	v_mfma_f32_16x16x32_bf16 v[16:19], v[158:161], v[198:201], v[16:19]
	v_mfma_f32_16x16x32_bf16 v[0:3], v[158:161], v[206:209], v[0:3]
	v_mfma_f32_16x16x32_bf16 v[4:7], v[150:153], v[206:209], v[4:7]
	s_setprio 0
	s_setprio 1
	v_mfma_f32_16x16x32_bf16 v[52:55], v[154:157], v[186:189], v[52:55]
	v_mfma_f32_16x16x32_bf16 v[48:51], v[162:165], v[186:189], v[48:51]
	v_mfma_f32_16x16x32_bf16 v[32:35], v[162:165], v[194:197], v[32:35]
	v_mfma_f32_16x16x32_bf16 v[36:39], v[154:157], v[194:197], v[36:39]
	v_mfma_f32_16x16x32_bf16 v[20:23], v[154:157], v[202:205], v[20:23]
	v_mfma_f32_16x16x32_bf16 v[16:19], v[162:165], v[202:205], v[16:19]
	v_mfma_f32_16x16x32_bf16 v[0:3], v[162:165], v[210:213], v[0:3]
	v_mfma_f32_16x16x32_bf16 v[4:7], v[154:157], v[210:213], v[4:7]
	s_barrier
; #define PG8_LDA(dst, b, h) do { if constexpr (FP8) { _Pragma("unroll") for (int m = 0; m < 4; ++m) dst##8[m] = PG8_LD8(PG8_SA(b, h), aoff, aoff1, m); } \
;         else { _Pragma("unroll") for (int m = 0; m < 4; ++m) _Pragma("unroll") for (int k = 0; k < 2; ++k) dst[m][k] = *(const LAS bf16x8*)(lds + PG8_SA(b, h) + (k ? aoff1 : aoff) + m * 2048); } } while (0)
; #define PG8_LDB(dst, b, h) do { if constexpr (FP8) { dst##8[0] = PG8_LD8(PG8_SB(b, h), boff, boff1, 0); dst##8[1] = PG8_LD8(PG8_SB(b, h), boff, boff1, 1); } \
;         else { _Pragma("unroll") for (int n = 0; n < 2; ++n) _Pragma("unroll") for (int k = 0; k < 2; ++k) dst[n][k] = *(const LAS bf16x8*)(lds + PG8_SB(b, h) + (k ? boff1 : boff) + n * 2048); } } while (0)
; #define PG8_WAIT_V(n) asm volatile("s_waitcnt vmcnt(" #n ")" ::: "memory")
; #define PG8_WAIT_L(n) asm volatile("s_waitcnt lgkmcnt(" #n ")" ::: "memory")
; #define PG8_BAR __builtin_amdgcn_s_barrier()
; #define PG8_SCHED __builtin_amdgcn_sched_barrier(0)
; #define PG8_S3 PG8_STAGE(PG8_SA(0, 1), a2 + hstepA, voffA)
; template <class Epi, class SchedT, bool ALIGN_EPI, bool SP2, bool FP8 = false>
; __device__ __forceinline__ void gemm_phase(LAS unsigned char* lds, const Gemm g, const SchedT& S, const Epi& E, const int wid) {
;     ...
;             PG8_LDB(B0, 1, 0); PG8_LDB(B1, 1, 1); PG8_SCHED; PG8_LDA(At, 1, 0); PG8_S3;
;             PG8_WAIT_V(8); PG8_WAIT_L(0); PG8_BAR; PG8_MMAP(0, 1, 0); PG8_BAR; PG8_SCHED;
	s_setprio 0
	s_add_i32 s16, 0, 0x18000
	s_add_i32 s17, 0, 0x1c000
	v_add_u32_e32 v132, s16, v172
	v_add_u32_e32 v144, s17, v172
	ds_read_b128 v[128:131], v132
	ds_read_b128 v[132:135], v132 offset:1024
	ds_read_b128 v[136:139], v178
	ds_read_b128 v[140:143], v178 offset:1024
	ds_read_b128 v[150:153], v144
	ds_read_b128 v[154:157], v144 offset:1024
	ds_read_b128 v[158:161], v179
	ds_read_b128 v[162:165], v179 offset:1024
	s_add_u32 s60, s50, 0x40000
	v_mov_b32_e32 v144, v168
	s_mov_b32 m0, s89
	ds_read_b128 v[182:185], v177 offset:32768
	ds_read_b128 v[186:189], v177 offset:33792
	ds_read_b128 v[190:193], v177 offset:34816
	ds_read_b128 v[194:197], v177 offset:35840
	ds_read_b128 v[198:201], v177 offset:36864
	ds_read_b128 v[202:205], v177 offset:37888
	ds_read_b128 v[206:209], v177 offset:38912
	ds_read_b128 v[210:213], v177 offset:39936
	s_addc_u32 s61, s51, 0
	s_nop 0
	global_load_lds_dwordx4 v144, s[60:61]
	v_mov_b32_e32 v144, v170
	s_mov_b32 m0, s90
	s_nop 0
	global_load_lds_dwordx4 v144, s[60:61]
	s_waitcnt vmcnt(8)
	s_waitcnt lgkmcnt(0)
	s_setprio 1
	s_barrier
	v_mfma_f32_16x16x32_bf16 v[124:127], v[128:131], v[182:185], v[124:127]
	v_mfma_f32_16x16x32_bf16 v[120:123], v[136:139], v[182:185], v[120:123]
	v_mfma_f32_16x16x32_bf16 v[104:107], v[136:139], v[190:193], v[104:107]
	v_mfma_f32_16x16x32_bf16 v[108:111], v[128:131], v[190:193], v[108:111]
	v_mfma_f32_16x16x32_bf16 v[92:95], v[128:131], v[198:201], v[92:95]
	v_mfma_f32_16x16x32_bf16 v[88:91], v[136:139], v[198:201], v[88:91]
	v_mfma_f32_16x16x32_bf16 v[72:75], v[136:139], v[206:209], v[72:75]
	v_mfma_f32_16x16x32_bf16 v[76:79], v[128:131], v[206:209], v[76:79]
	s_setprio 0
	s_setprio 1
	v_mfma_f32_16x16x32_bf16 v[124:127], v[132:135], v[186:189], v[124:127]
	v_mfma_f32_16x16x32_bf16 v[120:123], v[140:143], v[186:189], v[120:123]
	v_mfma_f32_16x16x32_bf16 v[104:107], v[140:143], v[194:197], v[104:107]
	v_mfma_f32_16x16x32_bf16 v[108:111], v[132:135], v[194:197], v[108:111]
	v_mfma_f32_16x16x32_bf16 v[92:95], v[132:135], v[202:205], v[92:95]
	v_mfma_f32_16x16x32_bf16 v[88:91], v[140:143], v[202:205], v[88:91]
	v_mfma_f32_16x16x32_bf16 v[72:75], v[140:143], v[210:213], v[72:75]
	v_mfma_f32_16x16x32_bf16 v[76:79], v[132:135], v[210:213], v[76:79]
	s_setprio 0
	s_setprio 1
	v_mfma_f32_16x16x32_bf16 v[116:119], v[150:153], v[182:185], v[116:119]
	v_mfma_f32_16x16x32_bf16 v[112:115], v[158:161], v[182:185], v[112:115]
	v_mfma_f32_16x16x32_bf16 v[96:99], v[158:161], v[190:193], v[96:99]
	v_mfma_f32_16x16x32_bf16 v[100:103], v[150:153], v[190:193], v[100:103]
	v_mfma_f32_16x16x32_bf16 v[84:87], v[150:153], v[198:201], v[84:87]
	v_mfma_f32_16x16x32_bf16 v[80:83], v[158:161], v[198:201], v[80:83]
	v_mfma_f32_16x16x32_bf16 v[64:67], v[158:161], v[206:209], v[64:67]
	v_mfma_f32_16x16x32_bf16 v[68:71], v[150:153], v[206:209], v[68:71]
	s_setprio 0
	s_setprio 1
	v_mfma_f32_16x16x32_bf16 v[116:119], v[154:157], v[186:189], v[116:119]
	v_mfma_f32_16x16x32_bf16 v[112:115], v[162:165], v[186:189], v[112:115]
	v_mfma_f32_16x16x32_bf16 v[96:99], v[162:165], v[194:197], v[96:99]
	v_mfma_f32_16x16x32_bf16 v[100:103], v[154:157], v[194:197], v[100:103]
	v_mfma_f32_16x16x32_bf16 v[84:87], v[154:157], v[202:205], v[84:87]
	v_mfma_f32_16x16x32_bf16 v[80:83], v[162:165], v[202:205], v[80:83]
	v_mfma_f32_16x16x32_bf16 v[64:67], v[162:165], v[210:213], v[64:67]
	v_mfma_f32_16x16x32_bf16 v[68:71], v[154:157], v[210:213], v[68:71]
	s_barrier
; #define PG8_LDA(dst, b, h) do { if constexpr (FP8) { _Pragma("unroll") for (int m = 0; m < 4; ++m) dst##8[m] = PG8_LD8(PG8_SA(b, h), aoff, aoff1, m); } \
;         else { _Pragma("unroll") for (int m = 0; m < 4; ++m) _Pragma("unroll") for (int k = 0; k < 2; ++k) dst[m][k] = *(const LAS bf16x8*)(lds + PG8_SA(b, h) + (k ? aoff1 : aoff) + m * 2048); } } while (0)
; #define PG8_WAIT_V(n) asm volatile("s_waitcnt vmcnt(" #n ")" ::: "memory")
; #define PG8_WAIT_L(n) asm volatile("s_waitcnt lgkmcnt(" #n ")" ::: "memory")
; #define PG8_BAR __builtin_amdgcn_s_barrier()
; #define PG8_SCHED __builtin_amdgcn_sched_barrier(0)
; #define PG8_S4 do { PG8_STAGE(PG8_SB(1, 0), b3, voffB); PG8_STAGE(PG8_SB(1, 1), b3 + hstepB, voffB); PG8_STAGE(PG8_SA(1, 0), a3, voffA); } while (0)
; template <class Epi, class SchedT, bool ALIGN_EPI, bool SP2, bool FP8 = false>
; __device__ __forceinline__ void gemm_phase(LAS unsigned char* lds, const Gemm g, const SchedT& S, const Epi& E, const int wid) {
;     ...
;         for (int t = 0; t < nt; t += 2) {
;     ...
;             PG8_LDA(At, 1, 1); PG8_S4;
;             PG8_WAIT_V(8); PG8_WAIT_L(0); PG8_BAR; PG8_MMAP(1, 1, 1); PG8_BAR; PG8_SCHED;
	s_setprio 0
	v_mov_b32_e32 v144, v169
	ds_read_b128 v[182:185], v177 offset:49152
	ds_read_b128 v[186:189], v177 offset:50176
	ds_read_b128 v[190:193], v177 offset:51200
	ds_read_b128 v[194:197], v177 offset:52224
	ds_read_b128 v[198:201], v177 offset:53248
	ds_read_b128 v[202:205], v177 offset:54272
	ds_read_b128 v[206:209], v177 offset:55296
	ds_read_b128 v[210:213], v177 offset:56320
	s_add_i32 s16, s16, s86
	v_lshl_add_u64 v[166:167], s[52:53], 0, v[144:145]
	v_lshl_add_u64 v[166:167], v[166:167], 0, s[6:7]
	s_mov_b32 m0, s16
	v_mov_b32_e32 v144, v171
	global_load_lds_dwordx4 v[166:167], off
	s_add_i32 m0, s16, 0x2000
	s_nop 0
	v_lshl_add_u64 v[166:167], s[52:53], 0, v[144:145]
	s_add_u32 s52, s52, 0x40080
	v_lshl_add_u64 v[166:167], v[166:167], 0, s[6:7]
	s_addc_u32 s53, s53, 0
	v_mov_b32_e32 v144, v169
	s_add_i32 s16, s17, s86
	global_load_lds_dwordx4 v[166:167], off
	s_mov_b32 m0, s16
	s_nop 0
	global_load_lds_dwordx4 v144, s[52:53]
	v_mov_b32_e32 v144, v171
	s_add_i32 m0, s16, 0x2000
	s_nop 0
	global_load_lds_dwordx4 v144, s[52:53]
	v_mov_b32_e32 v144, v168
	s_mov_b32 m0, s92
	v_lshl_add_u64 v[166:167], s[50:51], 0, v[144:145]
	v_lshl_add_u64 v[166:167], v[166:167], 0, s[6:7]
	v_mov_b32_e32 v144, v170
	global_load_lds_dwordx4 v[166:167], off
	s_mov_b32 m0, s93
	v_lshl_add_u64 v[166:167], s[50:51], 0, v[144:145]
	v_lshl_add_u64 v[166:167], v[166:167], 0, s[6:7]
	global_load_lds_dwordx4 v[166:167], off
	s_waitcnt vmcnt(8)
	s_waitcnt lgkmcnt(0)
	s_setprio 1
	s_barrier
	v_mfma_f32_16x16x32_bf16 v[60:63], v[128:131], v[182:185], v[60:63]
	v_mfma_f32_16x16x32_bf16 v[56:59], v[136:139], v[182:185], v[56:59]
	v_mfma_f32_16x16x32_bf16 v[40:43], v[136:139], v[190:193], v[40:43]
	v_mfma_f32_16x16x32_bf16 v[44:47], v[128:131], v[190:193], v[44:47]
	v_mfma_f32_16x16x32_bf16 v[28:31], v[128:131], v[198:201], v[28:31]
	v_mfma_f32_16x16x32_bf16 v[24:27], v[136:139], v[198:201], v[24:27]
	v_mfma_f32_16x16x32_bf16 v[8:11], v[136:139], v[206:209], v[8:11]
	v_mfma_f32_16x16x32_bf16 v[12:15], v[128:131], v[206:209], v[12:15]
	s_setprio 0
	s_setprio 1
	v_mfma_f32_16x16x32_bf16 v[60:63], v[132:135], v[186:189], v[60:63]
	v_mfma_f32_16x16x32_bf16 v[56:59], v[140:143], v[186:189], v[56:59]
	v_mfma_f32_16x16x32_bf16 v[40:43], v[140:143], v[194:197], v[40:43]
	v_mfma_f32_16x16x32_bf16 v[44:47], v[132:135], v[194:197], v[44:47]
	v_mfma_f32_16x16x32_bf16 v[28:31], v[132:135], v[202:205], v[28:31]
	v_mfma_f32_16x16x32_bf16 v[24:27], v[140:143], v[202:205], v[24:27]
	v_mfma_f32_16x16x32_bf16 v[8:11], v[140:143], v[210:213], v[8:11]
	v_mfma_f32_16x16x32_bf16 v[12:15], v[132:135], v[210:213], v[12:15]
	s_setprio 0
	s_setprio 1
	v_mfma_f32_16x16x32_bf16 v[52:55], v[150:153], v[182:185], v[52:55]
	v_mfma_f32_16x16x32_bf16 v[48:51], v[158:161], v[182:185], v[48:51]
	v_mfma_f32_16x16x32_bf16 v[32:35], v[158:161], v[190:193], v[32:35]
	v_mfma_f32_16x16x32_bf16 v[36:39], v[150:153], v[190:193], v[36:39]
	v_mfma_f32_16x16x32_bf16 v[20:23], v[150:153], v[198:201], v[20:23]
	v_mfma_f32_16x16x32_bf16 v[16:19], v[158:161], v[198:201], v[16:19]
	v_mfma_f32_16x16x32_bf16 v[0:3], v[158:161], v[206:209], v[0:3]
	v_mfma_f32_16x16x32_bf16 v[4:7], v[150:153], v[206:209], v[4:7]
	s_setprio 0
	s_setprio 1
	v_mfma_f32_16x16x32_bf16 v[52:55], v[154:157], v[186:189], v[52:55]
	v_mfma_f32_16x16x32_bf16 v[48:51], v[162:165], v[186:189], v[48:51]
	v_mfma_f32_16x16x32_bf16 v[32:35], v[162:165], v[194:197], v[32:35]
	v_mfma_f32_16x16x32_bf16 v[36:39], v[154:157], v[194:197], v[36:39]
	v_mfma_f32_16x16x32_bf16 v[20:23], v[154:157], v[202:205], v[20:23]
	v_mfma_f32_16x16x32_bf16 v[16:19], v[162:165], v[202:205], v[16:19]
	v_mfma_f32_16x16x32_bf16 v[0:3], v[162:165], v[210:213], v[0:3]
	v_mfma_f32_16x16x32_bf16 v[4:7], v[154:157], v[210:213], v[4:7]
	s_barrier
	s_setprio 0
	s_add_u32 s48, s48, 0x100
	s_addc_u32 s49, s49, 0
	s_add_u32 s30, s30, 0x100
	s_addc_u32 s31, s31, 0
	s_cmp_ge_i32 s35, s20
	s_mov_b32 s34, s35
	s_cbranch_scc0 .LBB0_899

; #define PG8_LDA(dst, b, h) do { if constexpr (FP8) { _Pragma("unroll") for (int m = 0; m < 4; ++m) dst##8[m] = PG8_LD8(PG8_SA(b, h), aoff, aoff1, m); } \
;         else { _Pragma("unroll") for (int m = 0; m < 4; ++m) _Pragma("unroll") for (int k = 0; k < 2; ++k) dst[m][k] = *(const LAS bf16x8*)(lds + PG8_SA(b, h) + (k ? aoff1 : aoff) + m * 2048); } } while (0)
; #define PG8_LDB(dst, b, h) do { if constexpr (FP8) { dst##8[0] = PG8_LD8(PG8_SB(b, h), boff, boff1, 0); dst##8[1] = PG8_LD8(PG8_SB(b, h), boff, boff1, 1); } \
;         else { _Pragma("unroll") for (int n = 0; n < 2; ++n) _Pragma("unroll") for (int k = 0; k < 2; ++k) dst[n][k] = *(const LAS bf16x8*)(lds + PG8_SB(b, h) + (k ? boff1 : boff) + n * 2048); } } while (0)
; #define PG8_WAIT_V(n) asm volatile("s_waitcnt vmcnt(" #n ")" ::: "memory")
; #define PG8_WAIT_L(n) asm volatile("s_waitcnt lgkmcnt(" #n ")" ::: "memory")
; #define PG8_BAR __builtin_amdgcn_s_barrier()
; #define PG8_SCHED __builtin_amdgcn_sched_barrier(0)
; #define PG8_S1 PG8_STAGE(PG8_SA(1, 1), a1 + hstepA, voffA)
; template <class Epi, class SchedT, bool ALIGN_EPI, bool SP2, bool FP8 = false>
; __device__ __forceinline__ void gemm_phase(LAS unsigned char* lds, const Gemm g, const SchedT& S, const Epi& E, const int wid) {
;     ...
;     for (;;) {
;         const bool has_next = S.next(ui + 1, nxt);
;         const char* nA = has_next ? (const char*)g.A + (size_t)nxt.pm * tstepA + (size_t)nxt.aoff * 2 : cA; const char* nB = has_next ? (const char*)g.Bt + (size_t)nxt.pn * tstepB + (size_t)nxt.boff * 2 : cB;
;         const int nt = cur.nt;
;         for (int t = 0; t < nt; t += 2) {
;             const bool last = (t == nt - 2);
;             const char* a1 = cA + (size_t)(t + 1) * kstep;
;             const char* a2 = last ? nA : cA + (size_t)(t + 2) * kstep; const char* b2 = last ? nB : cB + (size_t)(t + 2) * kstep;
;             const char* a3 = a2 + kstep; const char* b3 = b2 + kstep;
;             if constexpr (SP2) {
;     ...
;             PG8_LDB(B0, 0, 0); PG8_LDB(B1, 0, 1); PG8_SCHED; PG8_LDA(At, 0, 0); PG8_S1;
;             PG8_WAIT_V(8); PG8_WAIT_L(0); PG8_BAR; PG8_MMAP(0, 0, 0); PG8_BAR; PG8_SCHED;
;             PG8_LDA(At, 0, 1); PG8_S2;
;             PG8_WAIT_V(8); PG8_WAIT_L(0); PG8_BAR; PG8_MMAP(1, 0, 1); PG8_BAR; PG8_SCHED;
.LBB0_968:
	s_ashr_i32 s15, s14, 31
	s_lshl_b64 s[20:21], s[14:15], 21
	s_add_u32 s20, s36, s20
	s_addc_u32 s21, s37, s21
	s_ashr_i32 s13, s12, 31
	s_lshl_b64 s[22:23], s[12:13], 21
	s_add_u32 s22, s52, s22
	s_addc_u32 s23, s53, s23
	s_cmp_lt_i32 s30, 1
	s_cbranch_scc1 .LBB0_997
	s_and_b64 s[38:39], s[4:5], exec
	s_cselect_b32 s13, s21, s25
	s_cselect_b32 s15, s20, s24
	s_cselect_b32 s27, s23, s35
	s_cselect_b32 s31, s22, s34
	s_add_i32 s45, s30, -2
	s_add_u32 s24, s24, 0x100080
	s_addc_u32 s25, s25, 0
	s_add_u32 s46, s34, 0x100
	s_addc_u32 s47, s35, 0
	s_mov_b32 s34, 0
	ds_read_b128 v[134:137], v175
	ds_read_b128 v[138:141], v175 offset:1024
	ds_read_b128 v[142:145], v176
	ds_read_b128 v[146:149], v176 offset:1024
	ds_read_b128 v[150:153], v177
	ds_read_b128 v[154:157], v177 offset:1024
	ds_read_b128 v[158:161], v178
	ds_read_b128 v[162:165], v178 offset:1024
	s_add_i32 s48, s34, 2
	s_add_u32 s16, s24, 0xfff00080
	s_addc_u32 s17, s25, -1
	s_cmp_eq_u32 s45, s34
	s_cselect_b32 s34, s15, s16
	s_cselect_b32 s35, s13, s17
	s_cselect_b32 s39, s27, s47
	s_cselect_b32 s38, s31, s46
	v_mov_b32_e32 v128, v172
	ds_read_b128 v[166:169], v179
	ds_read_b128 v[184:187], v179 offset:1024
	ds_read_b128 v[188:191], v179 offset:2048
	ds_read_b128 v[192:195], v179 offset:3072
	ds_read_b128 v[196:199], v179 offset:4096
	ds_read_b128 v[200:203], v179 offset:5120
	ds_read_b128 v[204:207], v179 offset:6144
	ds_read_b128 v[208:211], v179 offset:7168
	s_add_i32 m0, s87, 0xc000
	s_nop 0
	global_load_lds_dwordx4 v128, s[24:25]
	v_mov_b32_e32 v128, v173
	s_add_i32 m0, s87, 0xe000
	s_nop 0
	global_load_lds_dwordx4 v128, s[24:25]
	s_waitcnt vmcnt(8)
	s_waitcnt lgkmcnt(0)
	s_setprio 1
	s_barrier
	v_mfma_f32_16x16x32_bf16 v[124:127], v[134:137], v[166:169], 0
	v_mfma_f32_16x16x32_bf16 v[120:123], v[142:145], v[166:169], 0
	v_mfma_f32_16x16x32_bf16 v[104:107], v[142:145], v[188:191], 0
	v_mfma_f32_16x16x32_bf16 v[108:111], v[134:137], v[188:191], 0
	v_mfma_f32_16x16x32_bf16 v[92:95], v[134:137], v[196:199], 0
	v_mfma_f32_16x16x32_bf16 v[88:91], v[142:145], v[196:199], 0
	v_mfma_f32_16x16x32_bf16 v[72:75], v[142:145], v[204:207], 0
	v_mfma_f32_16x16x32_bf16 v[76:79], v[134:137], v[204:207], 0
	s_setprio 0
	s_setprio 1
	v_mfma_f32_16x16x32_bf16 v[124:127], v[138:141], v[184:187], v[124:127]
	v_mfma_f32_16x16x32_bf16 v[120:123], v[146:149], v[184:187], v[120:123]
	v_mfma_f32_16x16x32_bf16 v[104:107], v[146:149], v[192:195], v[104:107]
	v_mfma_f32_16x16x32_bf16 v[108:111], v[138:141], v[192:195], v[108:111]
	v_mfma_f32_16x16x32_bf16 v[92:95], v[138:141], v[200:203], v[92:95]
	v_mfma_f32_16x16x32_bf16 v[88:91], v[146:149], v[200:203], v[88:91]
	v_mfma_f32_16x16x32_bf16 v[72:75], v[146:149], v[208:211], v[72:75]
	v_mfma_f32_16x16x32_bf16 v[76:79], v[138:141], v[208:211], v[76:79]
	s_setprio 0
	s_setprio 1
	v_mfma_f32_16x16x32_bf16 v[116:119], v[150:153], v[166:169], 0
	v_mfma_f32_16x16x32_bf16 v[112:115], v[158:161], v[166:169], 0
	v_mfma_f32_16x16x32_bf16 v[96:99], v[158:161], v[188:191], 0
	v_mfma_f32_16x16x32_bf16 v[100:103], v[150:153], v[188:191], 0
	v_mfma_f32_16x16x32_bf16 v[84:87], v[150:153], v[196:199], 0
	v_mfma_f32_16x16x32_bf16 v[80:83], v[158:161], v[196:199], 0
	v_mfma_f32_16x16x32_bf16 v[64:67], v[158:161], v[204:207], 0
	v_mfma_f32_16x16x32_bf16 v[68:71], v[150:153], v[204:207], 0
	s_setprio 0
	s_setprio 1
	v_mfma_f32_16x16x32_bf16 v[116:119], v[154:157], v[184:187], v[116:119]
	v_mfma_f32_16x16x32_bf16 v[112:115], v[162:165], v[184:187], v[112:115]
	v_mfma_f32_16x16x32_bf16 v[96:99], v[162:165], v[192:195], v[96:99]
	v_mfma_f32_16x16x32_bf16 v[100:103], v[154:157], v[192:195], v[100:103]
	v_mfma_f32_16x16x32_bf16 v[84:87], v[154:157], v[200:203], v[84:87]
	v_mfma_f32_16x16x32_bf16 v[80:83], v[162:165], v[200:203], v[80:83]
	v_mfma_f32_16x16x32_bf16 v[64:67], v[162:165], v[208:211], v[64:67]
	v_mfma_f32_16x16x32_bf16 v[68:71], v[154:157], v[208:211], v[68:71]
	s_barrier
	s_setprio 0
	v_mov_b32_e32 v128, v172
	s_add_i32 s16, s94, s86
	ds_read_b128 v[166:169], v179 offset:16384
	ds_read_b128 v[184:187], v179 offset:17408
	ds_read_b128 v[188:191], v179 offset:18432
	ds_read_b128 v[192:195], v179 offset:19456
	ds_read_b128 v[196:199], v179 offset:20480
	ds_read_b128 v[200:203], v179 offset:21504
	ds_read_b128 v[204:207], v179 offset:22528
	ds_read_b128 v[208:211], v179 offset:23552
	s_mov_b32 m0, s16
	s_nop 0
	global_load_lds_dwordx4 v128, s[38:39]
	v_mov_b32_e32 v128, v173
	s_add_i32 m0, s16, 0x2000
	s_add_u32 s50, s38, 0x100000
	global_load_lds_dwordx4 v128, s[38:39]
	s_addc_u32 s51, s39, 0
	v_mov_b32_e32 v128, v172
	s_add_i32 s16, s95, s86
	s_mov_b32 m0, s16
	s_nop 0
	global_load_lds_dwordx4 v128, s[50:51]
	v_mov_b32_e32 v128, v173
	s_add_i32 m0, s16, 0x2000
	s_nop 0
	global_load_lds_dwordx4 v128, s[50:51]
	v_mov_b32_e32 v128, v172
	s_mov_b32 m0, s87
	s_nop 0
	global_load_lds_dwordx4 v128, s[34:35]
	v_mov_b32_e32 v128, v173
	s_mov_b32 m0, s88
	s_nop 0
	global_load_lds_dwordx4 v128, s[34:35]
	s_waitcnt vmcnt(8)
	s_waitcnt lgkmcnt(0)
	s_setprio 1
	s_barrier
; #define PG8_LDA(dst, b, h) do { if constexpr (FP8) { _Pragma("unroll") for (int m = 0; m < 4; ++m) dst##8[m] = PG8_LD8(PG8_SA(b, h), aoff, aoff1, m); } \
;         else { _Pragma("unroll") for (int m = 0; m < 4; ++m) _Pragma("unroll") for (int k = 0; k < 2; ++k) dst[m][k] = *(const LAS bf16x8*)(lds + PG8_SA(b, h) + (k ? aoff1 : aoff) + m * 2048); } } while (0)
; #define PG8_LDB(dst, b, h) do { if constexpr (FP8) { dst##8[0] = PG8_LD8(PG8_SB(b, h), boff, boff1, 0); dst##8[1] = PG8_LD8(PG8_SB(b, h), boff, boff1, 1); } \
;         else { _Pragma("unroll") for (int n = 0; n < 2; ++n) _Pragma("unroll") for (int k = 0; k < 2; ++k) dst[n][k] = *(const LAS bf16x8*)(lds + PG8_SB(b, h) + (k ? boff1 : boff) + n * 2048); } } while (0)
; #define PG8_WAIT_V(n) asm volatile("s_waitcnt vmcnt(" #n ")" ::: "memory")
; #define PG8_WAIT_L(n) asm volatile("s_waitcnt lgkmcnt(" #n ")" ::: "memory")
; #define PG8_BAR __builtin_amdgcn_s_barrier()
; #define PG8_SCHED __builtin_amdgcn_sched_barrier(0)
; #define PG8_S2 do { PG8_STAGE(PG8_SB(0, 0), b2, voffB); PG8_STAGE(PG8_SB(0, 1), b2 + hstepB, voffB); PG8_STAGE(PG8_SA(0, 0), a2, voffA); } while (0)
; #define PG8_S3 PG8_STAGE(PG8_SA(0, 1), a2 + hstepA, voffA)
; #define PG8_S4 do { PG8_STAGE(PG8_SB(1, 0), b3, voffB); PG8_STAGE(PG8_SB(1, 1), b3 + hstepB, voffB); PG8_STAGE(PG8_SA(1, 0), a3, voffA); } while (0)
; template <class Epi, class SchedT, bool ALIGN_EPI, bool SP2, bool FP8 = false>
; __device__ __forceinline__ void gemm_phase(LAS unsigned char* lds, const Gemm g, const SchedT& S, const Epi& E, const int wid) {
;     ...
;             PG8_LDA(At, 0, 1); PG8_S2;
;             PG8_WAIT_V(8); PG8_WAIT_L(0); PG8_BAR; PG8_MMAP(1, 0, 1); PG8_BAR; PG8_SCHED;
;             PG8_LDB(B0, 1, 0); PG8_LDB(B1, 1, 1); PG8_SCHED; PG8_LDA(At, 1, 0); PG8_S3;
;             PG8_WAIT_V(8); PG8_WAIT_L(0); PG8_BAR; PG8_MMAP(0, 1, 0); PG8_BAR; PG8_SCHED;
;             PG8_LDA(At, 1, 1); PG8_S4;
;             PG8_WAIT_V(8); PG8_WAIT_L(0); PG8_BAR; PG8_MMAP(1, 1, 1); PG8_BAR; PG8_SCHED;
	v_mfma_f32_16x16x32_bf16 v[60:63], v[134:137], v[166:169], 0
	v_mfma_f32_16x16x32_bf16 v[56:59], v[142:145], v[166:169], 0
	v_mfma_f32_16x16x32_bf16 v[40:43], v[142:145], v[188:191], 0
	v_mfma_f32_16x16x32_bf16 v[44:47], v[134:137], v[188:191], 0
	v_mfma_f32_16x16x32_bf16 v[28:31], v[134:137], v[196:199], 0
	v_mfma_f32_16x16x32_bf16 v[24:27], v[142:145], v[196:199], 0
	v_mfma_f32_16x16x32_bf16 v[8:11], v[142:145], v[204:207], 0
	v_mfma_f32_16x16x32_bf16 v[12:15], v[134:137], v[204:207], 0
	s_setprio 0
	s_setprio 1
	v_mfma_f32_16x16x32_bf16 v[60:63], v[138:141], v[184:187], v[60:63]
	v_mfma_f32_16x16x32_bf16 v[56:59], v[146:149], v[184:187], v[56:59]
	v_mfma_f32_16x16x32_bf16 v[40:43], v[146:149], v[192:195], v[40:43]
	v_mfma_f32_16x16x32_bf16 v[44:47], v[138:141], v[192:195], v[44:47]
	v_mfma_f32_16x16x32_bf16 v[28:31], v[138:141], v[200:203], v[28:31]
	v_mfma_f32_16x16x32_bf16 v[24:27], v[146:149], v[200:203], v[24:27]
	v_mfma_f32_16x16x32_bf16 v[8:11], v[146:149], v[208:211], v[8:11]
	v_mfma_f32_16x16x32_bf16 v[12:15], v[138:141], v[208:211], v[12:15]
	s_setprio 0
	s_setprio 1
	v_mfma_f32_16x16x32_bf16 v[52:55], v[150:153], v[166:169], 0
	v_mfma_f32_16x16x32_bf16 v[48:51], v[158:161], v[166:169], 0
	v_mfma_f32_16x16x32_bf16 v[32:35], v[158:161], v[188:191], 0
	v_mfma_f32_16x16x32_bf16 v[36:39], v[150:153], v[188:191], 0
	v_mfma_f32_16x16x32_bf16 v[20:23], v[150:153], v[196:199], 0
	v_mfma_f32_16x16x32_bf16 v[16:19], v[158:161], v[196:199], 0
	v_mfma_f32_16x16x32_bf16 v[0:3], v[158:161], v[204:207], 0
	v_mfma_f32_16x16x32_bf16 v[4:7], v[150:153], v[204:207], 0
	s_setprio 0
	s_setprio 1
	v_mfma_f32_16x16x32_bf16 v[52:55], v[154:157], v[184:187], v[52:55]
	v_mfma_f32_16x16x32_bf16 v[48:51], v[162:165], v[184:187], v[48:51]
	v_mfma_f32_16x16x32_bf16 v[32:35], v[162:165], v[192:195], v[32:35]
	v_mfma_f32_16x16x32_bf16 v[36:39], v[154:157], v[192:195], v[36:39]
	v_mfma_f32_16x16x32_bf16 v[20:23], v[154:157], v[200:203], v[20:23]
	v_mfma_f32_16x16x32_bf16 v[16:19], v[162:165], v[200:203], v[16:19]
	v_mfma_f32_16x16x32_bf16 v[0:3], v[162:165], v[208:211], v[0:3]
	v_mfma_f32_16x16x32_bf16 v[4:7], v[154:157], v[208:211], v[4:7]
	s_barrier
	s_setprio 0
	s_add_i32 s16, 0, 0x18000
	v_add_u32_e32 v128, s16, v174
	s_add_i32 s17, 0, 0x1c000
	ds_read_b128 v[134:137], v128
	ds_read_b128 v[138:141], v128 offset:1024
	ds_read_b128 v[142:145], v180
	ds_read_b128 v[146:149], v180 offset:1024
	v_add_u32_e32 v128, s17, v174
	ds_read_b128 v[150:153], v128
	ds_read_b128 v[154:157], v128 offset:1024
	ds_read_b128 v[158:161], v181
	ds_read_b128 v[162:165], v181 offset:1024
	s_add_u32 s50, s34, 0x100000
	v_mov_b32_e32 v128, v172
	s_mov_b32 m0, s89
	ds_read_b128 v[166:169], v179 offset:32768
	ds_read_b128 v[184:187], v179 offset:33792
	ds_read_b128 v[188:191], v179 offset:34816
	ds_read_b128 v[192:195], v179 offset:35840
	ds_read_b128 v[196:199], v179 offset:36864
	ds_read_b128 v[200:203], v179 offset:37888
	ds_read_b128 v[204:207], v179 offset:38912
	ds_read_b128 v[208:211], v179 offset:39936
	s_addc_u32 s51, s35, 0
	s_nop 0
	global_load_lds_dwordx4 v128, s[50:51]
	v_mov_b32_e32 v128, v173
	s_mov_b32 m0, s90
	s_nop 0
	global_load_lds_dwordx4 v128, s[50:51]
	s_waitcnt vmcnt(8)
	s_waitcnt lgkmcnt(0)
	s_setprio 1
	s_barrier
	v_mfma_f32_16x16x32_bf16 v[124:127], v[134:137], v[166:169], v[124:127]
	v_mfma_f32_16x16x32_bf16 v[120:123], v[142:145], v[166:169], v[120:123]
	v_mfma_f32_16x16x32_bf16 v[104:107], v[142:145], v[188:191], v[104:107]
	v_mfma_f32_16x16x32_bf16 v[108:111], v[134:137], v[188:191], v[108:111]
	v_mfma_f32_16x16x32_bf16 v[92:95], v[134:137], v[196:199], v[92:95]
	v_mfma_f32_16x16x32_bf16 v[88:91], v[142:145], v[196:199], v[88:91]
	v_mfma_f32_16x16x32_bf16 v[72:75], v[142:145], v[204:207], v[72:75]
	v_mfma_f32_16x16x32_bf16 v[76:79], v[134:137], v[204:207], v[76:79]
	s_setprio 0
	s_setprio 1
	v_mfma_f32_16x16x32_bf16 v[124:127], v[138:141], v[184:187], v[124:127]
	v_mfma_f32_16x16x32_bf16 v[120:123], v[146:149], v[184:187], v[120:123]
	v_mfma_f32_16x16x32_bf16 v[104:107], v[146:149], v[192:195], v[104:107]
	v_mfma_f32_16x16x32_bf16 v[108:111], v[138:141], v[192:195], v[108:111]
	v_mfma_f32_16x16x32_bf16 v[92:95], v[138:141], v[200:203], v[92:95]
	v_mfma_f32_16x16x32_bf16 v[88:91], v[146:149], v[200:203], v[88:91]
	v_mfma_f32_16x16x32_bf16 v[72:75], v[146:149], v[208:211], v[72:75]
	v_mfma_f32_16x16x32_bf16 v[76:79], v[138:141], v[208:211], v[76:79]
	s_setprio 0
	s_setprio 1
	v_mfma_f32_16x16x32_bf16 v[116:119], v[150:153], v[166:169], v[116:119]
	v_mfma_f32_16x16x32_bf16 v[112:115], v[158:161], v[166:169], v[112:115]
	v_mfma_f32_16x16x32_bf16 v[96:99], v[158:161], v[188:191], v[96:99]
	v_mfma_f32_16x16x32_bf16 v[100:103], v[150:153], v[188:191], v[100:103]
	v_mfma_f32_16x16x32_bf16 v[84:87], v[150:153], v[196:199], v[84:87]
	v_mfma_f32_16x16x32_bf16 v[80:83], v[158:161], v[196:199], v[80:83]
	v_mfma_f32_16x16x32_bf16 v[64:67], v[158:161], v[204:207], v[64:67]
	v_mfma_f32_16x16x32_bf16 v[68:71], v[150:153], v[204:207], v[68:71]
	s_setprio 0
	s_setprio 1
	v_mfma_f32_16x16x32_bf16 v[116:119], v[154:157], v[184:187], v[116:119]
	v_mfma_f32_16x16x32_bf16 v[112:115], v[162:165], v[184:187], v[112:115]
	v_mfma_f32_16x16x32_bf16 v[96:99], v[162:165], v[192:195], v[96:99]
	v_mfma_f32_16x16x32_bf16 v[100:103], v[154:157], v[192:195], v[100:103]
	v_mfma_f32_16x16x32_bf16 v[84:87], v[154:157], v[200:203], v[84:87]
	v_mfma_f32_16x16x32_bf16 v[80:83], v[162:165], v[200:203], v[80:83]
	v_mfma_f32_16x16x32_bf16 v[64:67], v[162:165], v[208:211], v[64:67]
	v_mfma_f32_16x16x32_bf16 v[68:71], v[154:157], v[208:211], v[68:71]
	s_barrier
; #define PG8_LDA(dst, b, h) do { if constexpr (FP8) { _Pragma("unroll") for (int m = 0; m < 4; ++m) dst##8[m] = PG8_LD8(PG8_SA(b, h), aoff, aoff1, m); } \
;         else { _Pragma("unroll") for (int m = 0; m < 4; ++m) _Pragma("unroll") for (int k = 0; k < 2; ++k) dst[m][k] = *(const LAS bf16x8*)(lds + PG8_SA(b, h) + (k ? aoff1 : aoff) + m * 2048); } } while (0)
; #define PG8_LDB(dst, b, h) do { if constexpr (FP8) { dst##8[0] = PG8_LD8(PG8_SB(b, h), boff, boff1, 0); dst##8[1] = PG8_LD8(PG8_SB(b, h), boff, boff1, 1); } \
;         else { _Pragma("unroll") for (int n = 0; n < 2; ++n) _Pragma("unroll") for (int k = 0; k < 2; ++k) dst[n][k] = *(const LAS bf16x8*)(lds + PG8_SB(b, h) + (k ? boff1 : boff) + n * 2048); } } while (0)
; #define PG8_WAIT_V(n) asm volatile("s_waitcnt vmcnt(" #n ")" ::: "memory")
; #define PG8_WAIT_L(n) asm volatile("s_waitcnt lgkmcnt(" #n ")" ::: "memory")
; #define PG8_BAR __builtin_amdgcn_s_barrier()
; #define PG8_SCHED __builtin_amdgcn_sched_barrier(0)
; #define PG8_S1 PG8_STAGE(PG8_SA(1, 1), a1 + hstepA, voffA)
; #define PG8_S4 do { PG8_STAGE(PG8_SB(1, 0), b3, voffB); PG8_STAGE(PG8_SB(1, 1), b3 + hstepB, voffB); PG8_STAGE(PG8_SA(1, 0), a3, voffA); } while (0)
; template <class Epi, class SchedT, bool ALIGN_EPI, bool SP2, bool FP8 = false>
; __device__ __forceinline__ void gemm_phase(LAS unsigned char* lds, const Gemm g, const SchedT& S, const Epi& E, const int wid) {
;     ...
;         for (int t = 0; t < nt; t += 2) {
;             const bool last = (t == nt - 2);
;             const char* a1 = cA + (size_t)(t + 1) * kstep;
;             const char* a2 = last ? nA : cA + (size_t)(t + 2) * kstep; const char* b2 = last ? nB : cB + (size_t)(t + 2) * kstep;
;             const char* a3 = a2 + kstep; const char* b3 = b2 + kstep;
;             if constexpr (SP2) {
;     ...
;             PG8_LDB(B0, 0, 0); PG8_LDB(B1, 0, 1); PG8_SCHED; PG8_LDA(At, 0, 0); PG8_S1;
;             PG8_WAIT_V(8); PG8_WAIT_L(0); PG8_BAR; PG8_MMAP(0, 0, 0); PG8_BAR; PG8_SCHED;
;     ...
;             PG8_LDA(At, 1, 1); PG8_S4;
;             PG8_WAIT_V(8); PG8_WAIT_L(0); PG8_BAR; PG8_MMAP(1, 1, 1); PG8_BAR; PG8_SCHED;
	s_setprio 0
	v_mov_b32_e32 v128, v172
	ds_read_b128 v[166:169], v179 offset:49152
	ds_read_b128 v[184:187], v179 offset:50176
	ds_read_b128 v[188:191], v179 offset:51200
	ds_read_b128 v[192:195], v179 offset:52224
	ds_read_b128 v[196:199], v179 offset:53248
	ds_read_b128 v[200:203], v179 offset:54272
	ds_read_b128 v[204:207], v179 offset:55296
	ds_read_b128 v[208:211], v179 offset:56320
	s_add_i32 s16, s16, s86
	v_lshl_add_u64 v[170:171], s[38:39], 0, v[128:129]
	v_lshl_add_u64 v[170:171], v[170:171], 0, s[8:9]
	s_mov_b32 m0, s16
	v_mov_b32_e32 v128, v173
	global_load_lds_dwordx4 v[170:171], off
	s_add_i32 m0, s16, 0x2000
	s_nop 0
	v_lshl_add_u64 v[170:171], s[38:39], 0, v[128:129]
	s_add_u32 s38, s38, 0x100080
	v_lshl_add_u64 v[170:171], v[170:171], 0, s[8:9]
	s_addc_u32 s39, s39, 0
	v_mov_b32_e32 v128, v172
	s_add_i32 s16, s17, s86
	global_load_lds_dwordx4 v[170:171], off
	s_mov_b32 m0, s16
	s_nop 0
	global_load_lds_dwordx4 v128, s[38:39]
	v_mov_b32_e32 v128, v173
	s_add_i32 m0, s16, 0x2000
	s_nop 0
	global_load_lds_dwordx4 v128, s[38:39]
	v_mov_b32_e32 v128, v172
	s_mov_b32 m0, s92
	v_lshl_add_u64 v[170:171], s[34:35], 0, v[128:129]
	v_lshl_add_u64 v[170:171], v[170:171], 0, s[8:9]
	v_mov_b32_e32 v128, v173
	global_load_lds_dwordx4 v[170:171], off
	s_mov_b32 m0, s93
	v_lshl_add_u64 v[170:171], s[34:35], 0, v[128:129]
	v_lshl_add_u64 v[170:171], v[170:171], 0, s[8:9]
	global_load_lds_dwordx4 v[170:171], off
	s_waitcnt vmcnt(8)
	s_waitcnt lgkmcnt(0)
	s_setprio 1
	s_barrier
	v_mfma_f32_16x16x32_bf16 v[60:63], v[134:137], v[166:169], v[60:63]
	v_mfma_f32_16x16x32_bf16 v[56:59], v[142:145], v[166:169], v[56:59]
	v_mfma_f32_16x16x32_bf16 v[40:43], v[142:145], v[188:191], v[40:43]
	v_mfma_f32_16x16x32_bf16 v[44:47], v[134:137], v[188:191], v[44:47]
	v_mfma_f32_16x16x32_bf16 v[28:31], v[134:137], v[196:199], v[28:31]
	v_mfma_f32_16x16x32_bf16 v[24:27], v[142:145], v[196:199], v[24:27]
	v_mfma_f32_16x16x32_bf16 v[8:11], v[142:145], v[204:207], v[8:11]
	v_mfma_f32_16x16x32_bf16 v[12:15], v[134:137], v[204:207], v[12:15]
	s_setprio 0
	s_setprio 1
	v_mfma_f32_16x16x32_bf16 v[60:63], v[138:141], v[184:187], v[60:63]
	v_mfma_f32_16x16x32_bf16 v[56:59], v[146:149], v[184:187], v[56:59]
	v_mfma_f32_16x16x32_bf16 v[40:43], v[146:149], v[192:195], v[40:43]
	v_mfma_f32_16x16x32_bf16 v[44:47], v[138:141], v[192:195], v[44:47]
	v_mfma_f32_16x16x32_bf16 v[28:31], v[138:141], v[200:203], v[28:31]
	v_mfma_f32_16x16x32_bf16 v[24:27], v[146:149], v[200:203], v[24:27]
	v_mfma_f32_16x16x32_bf16 v[8:11], v[146:149], v[208:211], v[8:11]
	v_mfma_f32_16x16x32_bf16 v[12:15], v[138:141], v[208:211], v[12:15]
	s_setprio 0
	s_setprio 1
	v_mfma_f32_16x16x32_bf16 v[52:55], v[150:153], v[166:169], v[52:55]
	v_mfma_f32_16x16x32_bf16 v[48:51], v[158:161], v[166:169], v[48:51]
	v_mfma_f32_16x16x32_bf16 v[32:35], v[158:161], v[188:191], v[32:35]
	v_mfma_f32_16x16x32_bf16 v[36:39], v[150:153], v[188:191], v[36:39]
	v_mfma_f32_16x16x32_bf16 v[20:23], v[150:153], v[196:199], v[20:23]
	v_mfma_f32_16x16x32_bf16 v[16:19], v[158:161], v[196:199], v[16:19]
	v_mfma_f32_16x16x32_bf16 v[0:3], v[158:161], v[204:207], v[0:3]
	v_mfma_f32_16x16x32_bf16 v[4:7], v[150:153], v[204:207], v[4:7]
	s_setprio 0
	s_setprio 1
	v_mfma_f32_16x16x32_bf16 v[52:55], v[154:157], v[184:187], v[52:55]
	v_mfma_f32_16x16x32_bf16 v[48:51], v[162:165], v[184:187], v[48:51]
	v_mfma_f32_16x16x32_bf16 v[32:35], v[162:165], v[192:195], v[32:35]
	v_mfma_f32_16x16x32_bf16 v[36:39], v[154:157], v[192:195], v[36:39]
	v_mfma_f32_16x16x32_bf16 v[20:23], v[154:157], v[200:203], v[20:23]
	v_mfma_f32_16x16x32_bf16 v[16:19], v[162:165], v[200:203], v[16:19]
	v_mfma_f32_16x16x32_bf16 v[0:3], v[162:165], v[208:211], v[0:3]
	v_mfma_f32_16x16x32_bf16 v[4:7], v[154:157], v[208:211], v[4:7]
	s_barrier
	s_setprio 0
	s_add_u32 s24, s24, 0x100
	s_addc_u32 s25, s25, 0
	s_add_u32 s46, s46, 0x100
	s_addc_u32 s47, s47, 0
	s_cmp_ge_i32 s48, s30
	s_mov_b32 s34, s48
	s_cbranch_scc1 .Lpeel_exit_lbb0_970
.LBB0_970:
	ds_read_b128 v[134:137], v175
	ds_read_b128 v[138:141], v175 offset:1024
	ds_read_b128 v[142:145], v176
	ds_read_b128 v[146:149], v176 offset:1024
	ds_read_b128 v[150:153], v177
	ds_read_b128 v[154:157], v177 offset:1024
	ds_read_b128 v[158:161], v178
	ds_read_b128 v[162:165], v178 offset:1024
	s_add_i32 s48, s34, 2
	s_add_u32 s16, s24, 0xfff00080
	s_addc_u32 s17, s25, -1
	s_cmp_eq_u32 s45, s34
	s_cselect_b32 s34, s15, s16
	s_cselect_b32 s35, s13, s17
	s_cselect_b32 s39, s27, s47
	s_cselect_b32 s38, s31, s46
	v_mov_b32_e32 v128, v172
	ds_read_b128 v[166:169], v179
	ds_read_b128 v[184:187], v179 offset:1024
	ds_read_b128 v[188:191], v179 offset:2048
	ds_read_b128 v[192:195], v179 offset:3072
	ds_read_b128 v[196:199], v179 offset:4096
	ds_read_b128 v[200:203], v179 offset:5120
	ds_read_b128 v[204:207], v179 offset:6144
	ds_read_b128 v[208:211], v179 offset:7168
	s_add_i32 m0, s87, 0xc000
	s_nop 0
	global_load_lds_dwordx4 v128, s[24:25]
	v_mov_b32_e32 v128, v173
	s_add_i32 m0, s87, 0xe000
	s_nop 0
	global_load_lds_dwordx4 v128, s[24:25]
	s_waitcnt vmcnt(8)
	s_waitcnt lgkmcnt(0)
	s_setprio 1
	s_barrier
; #define PG8_LDA(dst, b, h) do { if constexpr (FP8) { _Pragma("unroll") for (int m = 0; m < 4; ++m) dst##8[m] = PG8_LD8(PG8_SA(b, h), aoff, aoff1, m); } \
;         else { _Pragma("unroll") for (int m = 0; m < 4; ++m) _Pragma("unroll") for (int k = 0; k < 2; ++k) dst[m][k] = *(const LAS bf16x8*)(lds + PG8_SA(b, h) + (k ? aoff1 : aoff) + m * 2048); } } while (0)
; #define PG8_LDB(dst, b, h) do { if constexpr (FP8) { dst##8[0] = PG8_LD8(PG8_SB(b, h), boff, boff1, 0); dst##8[1] = PG8_LD8(PG8_SB(b, h), boff, boff1, 1); } \
;         else { _Pragma("unroll") for (int n = 0; n < 2; ++n) _Pragma("unroll") for (int k = 0; k < 2; ++k) dst[n][k] = *(const LAS bf16x8*)(lds + PG8_SB(b, h) + (k ? boff1 : boff) + n * 2048); } } while (0)
; #define PG8_WAIT_V(n) asm volatile("s_waitcnt vmcnt(" #n ")" ::: "memory")
; #define PG8_WAIT_L(n) asm volatile("s_waitcnt lgkmcnt(" #n ")" ::: "memory")
; #define PG8_BAR __builtin_amdgcn_s_barrier()
; #define PG8_SCHED __builtin_amdgcn_sched_barrier(0)
; #define PG8_S1 PG8_STAGE(PG8_SA(1, 1), a1 + hstepA, voffA)
; #define PG8_S2 do { PG8_STAGE(PG8_SB(0, 0), b2, voffB); PG8_STAGE(PG8_SB(0, 1), b2 + hstepB, voffB); PG8_STAGE(PG8_SA(0, 0), a2, voffA); } while (0)
; template <class Epi, class SchedT, bool ALIGN_EPI, bool SP2, bool FP8 = false>
; __device__ __forceinline__ void gemm_phase(LAS unsigned char* lds, const Gemm g, const SchedT& S, const Epi& E, const int wid) {
;     ...
;             PG8_LDB(B0, 0, 0); PG8_LDB(B1, 0, 1); PG8_SCHED; PG8_LDA(At, 0, 0); PG8_S1;
;             PG8_WAIT_V(8); PG8_WAIT_L(0); PG8_BAR; PG8_MMAP(0, 0, 0); PG8_BAR; PG8_SCHED;
;             PG8_LDA(At, 0, 1); PG8_S2;
;             PG8_WAIT_V(8); PG8_WAIT_L(0); PG8_BAR; PG8_MMAP(1, 0, 1); PG8_BAR; PG8_SCHED;
	v_mfma_f32_16x16x32_bf16 v[124:127], v[134:137], v[166:169], v[124:127]
	v_mfma_f32_16x16x32_bf16 v[120:123], v[142:145], v[166:169], v[120:123]
	v_mfma_f32_16x16x32_bf16 v[104:107], v[142:145], v[188:191], v[104:107]
	v_mfma_f32_16x16x32_bf16 v[108:111], v[134:137], v[188:191], v[108:111]
	v_mfma_f32_16x16x32_bf16 v[92:95], v[134:137], v[196:199], v[92:95]
	v_mfma_f32_16x16x32_bf16 v[88:91], v[142:145], v[196:199], v[88:91]
	v_mfma_f32_16x16x32_bf16 v[72:75], v[142:145], v[204:207], v[72:75]
	v_mfma_f32_16x16x32_bf16 v[76:79], v[134:137], v[204:207], v[76:79]
	s_setprio 0
	s_setprio 1
	v_mfma_f32_16x16x32_bf16 v[124:127], v[138:141], v[184:187], v[124:127]
	v_mfma_f32_16x16x32_bf16 v[120:123], v[146:149], v[184:187], v[120:123]
	v_mfma_f32_16x16x32_bf16 v[104:107], v[146:149], v[192:195], v[104:107]
	v_mfma_f32_16x16x32_bf16 v[108:111], v[138:141], v[192:195], v[108:111]
	v_mfma_f32_16x16x32_bf16 v[92:95], v[138:141], v[200:203], v[92:95]
	v_mfma_f32_16x16x32_bf16 v[88:91], v[146:149], v[200:203], v[88:91]
	v_mfma_f32_16x16x32_bf16 v[72:75], v[146:149], v[208:211], v[72:75]
	v_mfma_f32_16x16x32_bf16 v[76:79], v[138:141], v[208:211], v[76:79]
	s_setprio 0
	s_setprio 1
	v_mfma_f32_16x16x32_bf16 v[116:119], v[150:153], v[166:169], v[116:119]
	v_mfma_f32_16x16x32_bf16 v[112:115], v[158:161], v[166:169], v[112:115]
	v_mfma_f32_16x16x32_bf16 v[96:99], v[158:161], v[188:191], v[96:99]
	v_mfma_f32_16x16x32_bf16 v[100:103], v[150:153], v[188:191], v[100:103]
	v_mfma_f32_16x16x32_bf16 v[84:87], v[150:153], v[196:199], v[84:87]
	v_mfma_f32_16x16x32_bf16 v[80:83], v[158:161], v[196:199], v[80:83]
	v_mfma_f32_16x16x32_bf16 v[64:67], v[158:161], v[204:207], v[64:67]
	v_mfma_f32_16x16x32_bf16 v[68:71], v[150:153], v[204:207], v[68:71]
	s_setprio 0
	s_setprio 1
	v_mfma_f32_16x16x32_bf16 v[116:119], v[154:157], v[184:187], v[116:119]
	v_mfma_f32_16x16x32_bf16 v[112:115], v[162:165], v[184:187], v[112:115]
	v_mfma_f32_16x16x32_bf16 v[96:99], v[162:165], v[192:195], v[96:99]
	v_mfma_f32_16x16x32_bf16 v[100:103], v[154:157], v[192:195], v[100:103]
	v_mfma_f32_16x16x32_bf16 v[84:87], v[154:157], v[200:203], v[84:87]
	v_mfma_f32_16x16x32_bf16 v[80:83], v[162:165], v[200:203], v[80:83]
	v_mfma_f32_16x16x32_bf16 v[64:67], v[162:165], v[208:211], v[64:67]
	v_mfma_f32_16x16x32_bf16 v[68:71], v[154:157], v[208:211], v[68:71]
	s_barrier
	s_setprio 0
	v_mov_b32_e32 v128, v172
	s_add_i32 s16, s94, s86
	ds_read_b128 v[166:169], v179 offset:16384
	ds_read_b128 v[184:187], v179 offset:17408
	ds_read_b128 v[188:191], v179 offset:18432
	ds_read_b128 v[192:195], v179 offset:19456
	ds_read_b128 v[196:199], v179 offset:20480
	ds_read_b128 v[200:203], v179 offset:21504
	ds_read_b128 v[204:207], v179 offset:22528
	ds_read_b128 v[208:211], v179 offset:23552
	s_mov_b32 m0, s16
	s_nop 0
	global_load_lds_dwordx4 v128, s[38:39]
	v_mov_b32_e32 v128, v173
	s_add_i32 m0, s16, 0x2000
	s_add_u32 s50, s38, 0x100000
	global_load_lds_dwordx4 v128, s[38:39]
	s_addc_u32 s51, s39, 0
	v_mov_b32_e32 v128, v172
	s_add_i32 s16, s95, s86
	s_mov_b32 m0, s16
	s_nop 0
	global_load_lds_dwordx4 v128, s[50:51]
	v_mov_b32_e32 v128, v173
	s_add_i32 m0, s16, 0x2000
	s_nop 0
	global_load_lds_dwordx4 v128, s[50:51]
	v_mov_b32_e32 v128, v172
	s_mov_b32 m0, s87
	s_nop 0
	global_load_lds_dwordx4 v128, s[34:35]
	v_mov_b32_e32 v128, v173
	s_mov_b32 m0, s88
	s_nop 0
	global_load_lds_dwordx4 v128, s[34:35]
	s_waitcnt vmcnt(8)
	s_waitcnt lgkmcnt(0)
	s_setprio 1
	s_barrier
	v_mfma_f32_16x16x32_bf16 v[60:63], v[134:137], v[166:169], v[60:63]
	v_mfma_f32_16x16x32_bf16 v[56:59], v[142:145], v[166:169], v[56:59]
	v_mfma_f32_16x16x32_bf16 v[40:43], v[142:145], v[188:191], v[40:43]
	v_mfma_f32_16x16x32_bf16 v[44:47], v[134:137], v[188:191], v[44:47]
	v_mfma_f32_16x16x32_bf16 v[28:31], v[134:137], v[196:199], v[28:31]
	v_mfma_f32_16x16x32_bf16 v[24:27], v[142:145], v[196:199], v[24:27]
	v_mfma_f32_16x16x32_bf16 v[8:11], v[142:145], v[204:207], v[8:11]
	v_mfma_f32_16x16x32_bf16 v[12:15], v[134:137], v[204:207], v[12:15]
	s_setprio 0
	s_setprio 1
	v_mfma_f32_16x16x32_bf16 v[60:63], v[138:141], v[184:187], v[60:63]
	v_mfma_f32_16x16x32_bf16 v[56:59], v[146:149], v[184:187], v[56:59]
	v_mfma_f32_16x16x32_bf16 v[40:43], v[146:149], v[192:195], v[40:43]
	v_mfma_f32_16x16x32_bf16 v[44:47], v[138:141], v[192:195], v[44:47]
	v_mfma_f32_16x16x32_bf16 v[28:31], v[138:141], v[200:203], v[28:31]
	v_mfma_f32_16x16x32_bf16 v[24:27], v[146:149], v[200:203], v[24:27]
	v_mfma_f32_16x16x32_bf16 v[8:11], v[146:149], v[208:211], v[8:11]
	v_mfma_f32_16x16x32_bf16 v[12:15], v[138:141], v[208:211], v[12:15]
	s_setprio 0
	s_setprio 1
	v_mfma_f32_16x16x32_bf16 v[52:55], v[150:153], v[166:169], v[52:55]
	v_mfma_f32_16x16x32_bf16 v[48:51], v[158:161], v[166:169], v[48:51]
	v_mfma_f32_16x16x32_bf16 v[32:35], v[158:161], v[188:191], v[32:35]
	v_mfma_f32_16x16x32_bf16 v[36:39], v[150:153], v[188:191], v[36:39]
	v_mfma_f32_16x16x32_bf16 v[20:23], v[150:153], v[196:199], v[20:23]
	v_mfma_f32_16x16x32_bf16 v[16:19], v[158:161], v[196:199], v[16:19]
	v_mfma_f32_16x16x32_bf16 v[0:3], v[158:161], v[204:207], v[0:3]
	v_mfma_f32_16x16x32_bf16 v[4:7], v[150:153], v[204:207], v[4:7]
	s_setprio 0
	s_setprio 1
	v_mfma_f32_16x16x32_bf16 v[52:55], v[154:157], v[184:187], v[52:55]
	v_mfma_f32_16x16x32_bf16 v[48:51], v[162:165], v[184:187], v[48:51]
	v_mfma_f32_16x16x32_bf16 v[32:35], v[162:165], v[192:195], v[32:35]
	v_mfma_f32_16x16x32_bf16 v[36:39], v[154:157], v[192:195], v[36:39]
	v_mfma_f32_16x16x32_bf16 v[20:23], v[154:157], v[200:203], v[20:23]
	v_mfma_f32_16x16x32_bf16 v[16:19], v[162:165], v[200:203], v[16:19]
	v_mfma_f32_16x16x32_bf16 v[0:3], v[162:165], v[208:211], v[0:3]
	v_mfma_f32_16x16x32_bf16 v[4:7], v[154:157], v[208:211], v[4:7]
	s_barrier
; #define PG8_LDA(dst, b, h) do { if constexpr (FP8) { _Pragma("unroll") for (int m = 0; m < 4; ++m) dst##8[m] = PG8_LD8(PG8_SA(b, h), aoff, aoff1, m); } \
;         else { _Pragma("unroll") for (int m = 0; m < 4; ++m) _Pragma("unroll") for (int k = 0; k < 2; ++k) dst[m][k] = *(const LAS bf16x8*)(lds + PG8_SA(b, h) + (k ? aoff1 : aoff) + m * 2048); } } while (0)
; #define PG8_LDB(dst, b, h) do { if constexpr (FP8) { dst##8[0] = PG8_LD8(PG8_SB(b, h), boff, boff1, 0); dst##8[1] = PG8_LD8(PG8_SB(b, h), boff, boff1, 1); } \
;         else { _Pragma("unroll") for (int n = 0; n < 2; ++n) _Pragma("unroll") for (int k = 0; k < 2; ++k) dst[n][k] = *(const LAS bf16x8*)(lds + PG8_SB(b, h) + (k ? boff1 : boff) + n * 2048); } } while (0)
; #define PG8_WAIT_V(n) asm volatile("s_waitcnt vmcnt(" #n ")" ::: "memory")
; #define PG8_WAIT_L(n) asm volatile("s_waitcnt lgkmcnt(" #n ")" ::: "memory")
; #define PG8_BAR __builtin_amdgcn_s_barrier()
; #define PG8_SCHED __builtin_amdgcn_sched_barrier(0)
; #define PG8_S3 PG8_STAGE(PG8_SA(0, 1), a2 + hstepA, voffA)
; template <class Epi, class SchedT, bool ALIGN_EPI, bool SP2, bool FP8 = false>
; __device__ __forceinline__ void gemm_phase(LAS unsigned char* lds, const Gemm g, const SchedT& S, const Epi& E, const int wid) {
;     ...
;             PG8_LDB(B0, 1, 0); PG8_LDB(B1, 1, 1); PG8_SCHED; PG8_LDA(At, 1, 0); PG8_S3;
;             PG8_WAIT_V(8); PG8_WAIT_L(0); PG8_BAR; PG8_MMAP(0, 1, 0); PG8_BAR; PG8_SCHED;
	s_setprio 0
	s_add_i32 s16, 0, 0x18000
	v_add_u32_e32 v128, s16, v174
	s_add_i32 s17, 0, 0x1c000
	ds_read_b128 v[134:137], v128
	ds_read_b128 v[138:141], v128 offset:1024
	ds_read_b128 v[142:145], v180
	ds_read_b128 v[146:149], v180 offset:1024
	v_add_u32_e32 v128, s17, v174
	ds_read_b128 v[150:153], v128
	ds_read_b128 v[154:157], v128 offset:1024
	ds_read_b128 v[158:161], v181
	ds_read_b128 v[162:165], v181 offset:1024
	s_add_u32 s50, s34, 0x100000
	v_mov_b32_e32 v128, v172
	s_mov_b32 m0, s89
	ds_read_b128 v[166:169], v179 offset:32768
	ds_read_b128 v[184:187], v179 offset:33792
	ds_read_b128 v[188:191], v179 offset:34816
	ds_read_b128 v[192:195], v179 offset:35840
	ds_read_b128 v[196:199], v179 offset:36864
	ds_read_b128 v[200:203], v179 offset:37888
	ds_read_b128 v[204:207], v179 offset:38912
	ds_read_b128 v[208:211], v179 offset:39936
	s_addc_u32 s51, s35, 0
	s_nop 0
	global_load_lds_dwordx4 v128, s[50:51]
	v_mov_b32_e32 v128, v173
	s_mov_b32 m0, s90
	s_nop 0
	global_load_lds_dwordx4 v128, s[50:51]
	s_waitcnt vmcnt(8)
	s_waitcnt lgkmcnt(0)
	s_setprio 1
	s_barrier
	v_mfma_f32_16x16x32_bf16 v[124:127], v[134:137], v[166:169], v[124:127]
	v_mfma_f32_16x16x32_bf16 v[120:123], v[142:145], v[166:169], v[120:123]
	v_mfma_f32_16x16x32_bf16 v[104:107], v[142:145], v[188:191], v[104:107]
	v_mfma_f32_16x16x32_bf16 v[108:111], v[134:137], v[188:191], v[108:111]
	v_mfma_f32_16x16x32_bf16 v[92:95], v[134:137], v[196:199], v[92:95]
	v_mfma_f32_16x16x32_bf16 v[88:91], v[142:145], v[196:199], v[88:91]
	v_mfma_f32_16x16x32_bf16 v[72:75], v[142:145], v[204:207], v[72:75]
	v_mfma_f32_16x16x32_bf16 v[76:79], v[134:137], v[204:207], v[76:79]
	s_setprio 0
	s_setprio 1
	v_mfma_f32_16x16x32_bf16 v[124:127], v[138:141], v[184:187], v[124:127]
	v_mfma_f32_16x16x32_bf16 v[120:123], v[146:149], v[184:187], v[120:123]
	v_mfma_f32_16x16x32_bf16 v[104:107], v[146:149], v[192:195], v[104:107]
	v_mfma_f32_16x16x32_bf16 v[108:111], v[138:141], v[192:195], v[108:111]
	v_mfma_f32_16x16x32_bf16 v[92:95], v[138:141], v[200:203], v[92:95]
	v_mfma_f32_16x16x32_bf16 v[88:91], v[146:149], v[200:203], v[88:91]
	v_mfma_f32_16x16x32_bf16 v[72:75], v[146:149], v[208:211], v[72:75]
	v_mfma_f32_16x16x32_bf16 v[76:79], v[138:141], v[208:211], v[76:79]
	s_setprio 0
	s_setprio 1
	v_mfma_f32_16x16x32_bf16 v[116:119], v[150:153], v[166:169], v[116:119]
	v_mfma_f32_16x16x32_bf16 v[112:115], v[158:161], v[166:169], v[112:115]
	v_mfma_f32_16x16x32_bf16 v[96:99], v[158:161], v[188:191], v[96:99]
	v_mfma_f32_16x16x32_bf16 v[100:103], v[150:153], v[188:191], v[100:103]
	v_mfma_f32_16x16x32_bf16 v[84:87], v[150:153], v[196:199], v[84:87]
	v_mfma_f32_16x16x32_bf16 v[80:83], v[158:161], v[196:199], v[80:83]
	v_mfma_f32_16x16x32_bf16 v[64:67], v[158:161], v[204:207], v[64:67]
	v_mfma_f32_16x16x32_bf16 v[68:71], v[150:153], v[204:207], v[68:71]
	s_setprio 0
	s_setprio 1
	v_mfma_f32_16x16x32_bf16 v[116:119], v[154:157], v[184:187], v[116:119]
	v_mfma_f32_16x16x32_bf16 v[112:115], v[162:165], v[184:187], v[112:115]
	v_mfma_f32_16x16x32_bf16 v[96:99], v[162:165], v[192:195], v[96:99]
	v_mfma_f32_16x16x32_bf16 v[100:103], v[154:157], v[192:195], v[100:103]
	v_mfma_f32_16x16x32_bf16 v[84:87], v[154:157], v[200:203], v[84:87]
	v_mfma_f32_16x16x32_bf16 v[80:83], v[162:165], v[200:203], v[80:83]
	v_mfma_f32_16x16x32_bf16 v[64:67], v[162:165], v[208:211], v[64:67]
	v_mfma_f32_16x16x32_bf16 v[68:71], v[154:157], v[208:211], v[68:71]
	s_barrier
; #define PG8_LDA(dst, b, h) do { if constexpr (FP8) { _Pragma("unroll") for (int m = 0; m < 4; ++m) dst##8[m] = PG8_LD8(PG8_SA(b, h), aoff, aoff1, m); } \
;         else { _Pragma("unroll") for (int m = 0; m < 4; ++m) _Pragma("unroll") for (int k = 0; k < 2; ++k) dst[m][k] = *(const LAS bf16x8*)(lds + PG8_SA(b, h) + (k ? aoff1 : aoff) + m * 2048); } } while (0)
; #define PG8_WAIT_V(n) asm volatile("s_waitcnt vmcnt(" #n ")" ::: "memory")
; #define PG8_WAIT_L(n) asm volatile("s_waitcnt lgkmcnt(" #n ")" ::: "memory")
; #define PG8_BAR __builtin_amdgcn_s_barrier()
; #define PG8_SCHED __builtin_amdgcn_sched_barrier(0)
; #define PG8_S4 do { PG8_STAGE(PG8_SB(1, 0), b3, voffB); PG8_STAGE(PG8_SB(1, 1), b3 + hstepB, voffB); PG8_STAGE(PG8_SA(1, 0), a3, voffA); } while (0)
; template <class Epi, class SchedT, bool ALIGN_EPI, bool SP2, bool FP8 = false>
; __device__ __forceinline__ void gemm_phase(LAS unsigned char* lds, const Gemm g, const SchedT& S, const Epi& E, const int wid) {
;     ...
;         for (int t = 0; t < nt; t += 2) {
;     ...
;             PG8_LDA(At, 1, 1); PG8_S4;
;             PG8_WAIT_V(8); PG8_WAIT_L(0); PG8_BAR; PG8_MMAP(1, 1, 1); PG8_BAR; PG8_SCHED;
	s_setprio 0
	v_mov_b32_e32 v128, v172
	ds_read_b128 v[166:169], v179 offset:49152
	ds_read_b128 v[184:187], v179 offset:50176
	ds_read_b128 v[188:191], v179 offset:51200
	ds_read_b128 v[192:195], v179 offset:52224
	ds_read_b128 v[196:199], v179 offset:53248
	ds_read_b128 v[200:203], v179 offset:54272
	ds_read_b128 v[204:207], v179 offset:55296
	ds_read_b128 v[208:211], v179 offset:56320
	s_add_i32 s16, s16, s86
	v_lshl_add_u64 v[170:171], s[38:39], 0, v[128:129]
	v_lshl_add_u64 v[170:171], v[170:171], 0, s[8:9]
	s_mov_b32 m0, s16
	v_mov_b32_e32 v128, v173
	global_load_lds_dwordx4 v[170:171], off
	s_add_i32 m0, s16, 0x2000
	s_nop 0
	v_lshl_add_u64 v[170:171], s[38:39], 0, v[128:129]
	s_add_u32 s38, s38, 0x100080
	v_lshl_add_u64 v[170:171], v[170:171], 0, s[8:9]
	s_addc_u32 s39, s39, 0
	v_mov_b32_e32 v128, v172
	s_add_i32 s16, s17, s86
	global_load_lds_dwordx4 v[170:171], off
	s_mov_b32 m0, s16
	s_nop 0
	global_load_lds_dwordx4 v128, s[38:39]
	v_mov_b32_e32 v128, v173
	s_add_i32 m0, s16, 0x2000
	s_nop 0
	global_load_lds_dwordx4 v128, s[38:39]
	v_mov_b32_e32 v128, v172
	s_mov_b32 m0, s92
	v_lshl_add_u64 v[170:171], s[34:35], 0, v[128:129]
	v_lshl_add_u64 v[170:171], v[170:171], 0, s[8:9]
	v_mov_b32_e32 v128, v173
	global_load_lds_dwordx4 v[170:171], off
	s_mov_b32 m0, s93
	v_lshl_add_u64 v[170:171], s[34:35], 0, v[128:129]
	v_lshl_add_u64 v[170:171], v[170:171], 0, s[8:9]
	global_load_lds_dwordx4 v[170:171], off
	s_waitcnt vmcnt(8)
	s_waitcnt lgkmcnt(0)
	s_setprio 1
	s_barrier
	v_mfma_f32_16x16x32_bf16 v[60:63], v[134:137], v[166:169], v[60:63]
	v_mfma_f32_16x16x32_bf16 v[56:59], v[142:145], v[166:169], v[56:59]
	v_mfma_f32_16x16x32_bf16 v[40:43], v[142:145], v[188:191], v[40:43]
	v_mfma_f32_16x16x32_bf16 v[44:47], v[134:137], v[188:191], v[44:47]
	v_mfma_f32_16x16x32_bf16 v[28:31], v[134:137], v[196:199], v[28:31]
	v_mfma_f32_16x16x32_bf16 v[24:27], v[142:145], v[196:199], v[24:27]
	v_mfma_f32_16x16x32_bf16 v[8:11], v[142:145], v[204:207], v[8:11]
	v_mfma_f32_16x16x32_bf16 v[12:15], v[134:137], v[204:207], v[12:15]
	s_setprio 0
	s_setprio 1
	v_mfma_f32_16x16x32_bf16 v[60:63], v[138:141], v[184:187], v[60:63]
	v_mfma_f32_16x16x32_bf16 v[56:59], v[146:149], v[184:187], v[56:59]
	v_mfma_f32_16x16x32_bf16 v[40:43], v[146:149], v[192:195], v[40:43]
	v_mfma_f32_16x16x32_bf16 v[44:47], v[138:141], v[192:195], v[44:47]
	v_mfma_f32_16x16x32_bf16 v[28:31], v[138:141], v[200:203], v[28:31]
	v_mfma_f32_16x16x32_bf16 v[24:27], v[146:149], v[200:203], v[24:27]
	v_mfma_f32_16x16x32_bf16 v[8:11], v[146:149], v[208:211], v[8:11]
	v_mfma_f32_16x16x32_bf16 v[12:15], v[138:141], v[208:211], v[12:15]
	s_setprio 0
	s_setprio 1
	v_mfma_f32_16x16x32_bf16 v[52:55], v[150:153], v[166:169], v[52:55]
	v_mfma_f32_16x16x32_bf16 v[48:51], v[158:161], v[166:169], v[48:51]
	v_mfma_f32_16x16x32_bf16 v[32:35], v[158:161], v[188:191], v[32:35]
	v_mfma_f32_16x16x32_bf16 v[36:39], v[150:153], v[188:191], v[36:39]
	v_mfma_f32_16x16x32_bf16 v[20:23], v[150:153], v[196:199], v[20:23]
	v_mfma_f32_16x16x32_bf16 v[16:19], v[158:161], v[196:199], v[16:19]
	v_mfma_f32_16x16x32_bf16 v[0:3], v[158:161], v[204:207], v[0:3]
	v_mfma_f32_16x16x32_bf16 v[4:7], v[150:153], v[204:207], v[4:7]
	s_setprio 0
	s_setprio 1
	v_mfma_f32_16x16x32_bf16 v[52:55], v[154:157], v[184:187], v[52:55]
	v_mfma_f32_16x16x32_bf16 v[48:51], v[162:165], v[184:187], v[48:51]
	v_mfma_f32_16x16x32_bf16 v[32:35], v[162:165], v[192:195], v[32:35]
	v_mfma_f32_16x16x32_bf16 v[36:39], v[154:157], v[192:195], v[36:39]
	v_mfma_f32_16x16x32_bf16 v[20:23], v[154:157], v[200:203], v[20:23]
	v_mfma_f32_16x16x32_bf16 v[16:19], v[162:165], v[200:203], v[16:19]
	v_mfma_f32_16x16x32_bf16 v[0:3], v[162:165], v[208:211], v[0:3]
	v_mfma_f32_16x16x32_bf16 v[4:7], v[154:157], v[208:211], v[4:7]
	s_barrier
	s_setprio 0
	s_add_u32 s24, s24, 0x100
	s_addc_u32 s25, s25, 0
	s_add_u32 s46, s46, 0x100
	s_addc_u32 s47, s47, 0
	s_cmp_ge_i32 s48, s30
	s_mov_b32 s34, s48
	s_cbranch_scc0 .LBB0_970
